# k15
# speedup vs baseline: 1.0335x; 1.0335x over previous
; DI void attn_unit(unsigned char* smem, const Params& P, int bh, int qb) {
;   const int tid = TID(), lane = tid & 63, w = tid >> 6, l31 = lane & 31, hh = lane >> 5;
;   bf16_t* sK = (bf16_t*)smem;
;   bf16_t* sV = sK + 64 * KLD;
;   const bf16_t* qbuf = (const bf16_t*)(P.ws + OFF_Q) + (size_t)bh * 8192 * 192;
;   bf16_t* obuf = (bf16_t*)(P.ws + OFF_MIX) + ((size_t)(bh >> 2) * 8192) * 1024 + (bh & 3) * 128;
;   const bf16_t* kbuf = (const bf16_t*)(P.ws + OFF_K) + (size_t)bh * 8192 * 192;
;   const bf16_t* vtb = (const bf16_t*)(P.ws + OFF_VT) + (size_t)bh * 128 * 8192;
;   const int q0 = qb * 128, qrow = q0 + 32 * w + l31;
;   bf16x8 qf[12];
; #pragma unroll
;   for (int ks = 0; ks < 12; ++ks) qf[ks] = *(const bf16x8*)(qbuf + (size_t)qrow * 192 + ks * 16 + hh * 8);
;   f32x16 O[4];
; #pragma unroll
;   for (int d = 0; d < 4; ++d)
; #pragma unroll
;     for (int i = 0; i < 16; ++i) O[d][i] = 0.f;
;   float mrun = -1e30f, lrun = 0.f;
;   const int ntiles = 2 * qb + 2;
;   bf16_t* sK1 = sV + 128 * LDK;
;   uint4 kr0, kr1, kr2, kr3, kr4, kr5, vr0, vr1, vr2, vr3;
;   const int kgo = (tid >> 2) * 192 + (tid & 3) * 8, klo = (tid >> 2) * KLD + (tid & 3) * 8;
;   __syncthreads();
;   kr0 = *(const uint4*)(kbuf + kgo + 0); kr1 = *(const uint4*)(kbuf + kgo + 32); kr2 = *(const uint4*)(kbuf + kgo + 64); kr3 = *(const uint4*)(kbuf + kgo + 96); kr4 = *(const uint4*)(kbuf + kgo + 128); kr5 = *(const uint4*)(kbuf + kgo + 160);
;   *(uint4*)(sK + klo + 0) = kr0; *(uint4*)(sK + klo + 32) = kr1; *(uint4*)(sK + klo + 64) = kr2; *(uint4*)(sK + klo + 96) = kr3; *(uint4*)(sK + klo + 128) = kr4; *(uint4*)(sK + klo + 160) = kr5;
;   __syncthreads();
;   for (int jt = 0; jt < ntiles; ++jt) {
;     const bf16_t* cK = (jt & 1) ? sK1 : sK;
;     bf16_t* nK = (jt & 1) ? sK : sK1;
;     const bool more = (jt + 1 < ntiles);
;     const bool active = (jt * 64 <= q0 + 32 * w + 31);
;     if (more) {
;       const bf16_t* kp = kbuf + (size_t)(jt + 1) * 64 * 192;
;       kr0 = *(const uint4*)(kp + kgo + 0); kr1 = *(const uint4*)(kp + kgo + 32); kr2 = *(const uint4*)(kp + kgo + 64); kr3 = *(const uint4*)(kp + kgo + 96); kr4 = *(const uint4*)(kp + kgo + 128); kr5 = *(const uint4*)(kp + kgo + 160);
;     }
;     __builtin_amdgcn_sched_barrier(0);
;     f32x16 S[2];
;     const float sref = (jt == 0) ? 0.f : mrun;
;     if (active) {
; #pragma unroll
;       for (int a = 0; a < 2; ++a)
.LBB0_472:
	s_cmpk_gt_i32 s84, 0xff
	s_mov_b64 s[0:1], -1
	s_cbranch_scc0 .LBB0_537
	s_cmpk_gt_u32 s84, 0x10f
	s_cbranch_scc0 .LBB0_533
	s_cmp_eq_u32 s9, 0
	s_cbranch_scc1 .Lstag_in_0
	s_barrier
.Lstag_in_0:
	s_add_i32 s93, s84, 0xfffffef0
	s_and_b32 s97, s84, 15
	s_lshr_b32 s92, s93, 4
	v_mov_b32_e32 v4, v1
	s_sub_i32 s8, 63, s92
	s_mul_i32 s0, s97, 0x300000
	v_ashrrev_i32_e32 v2, 1, v4
	s_add_u32 s56, s29, s0
	v_and_b32_e32 v2, 0xffffffe0, v2
	v_and_b32_e32 v176, 31, v4
	s_addc_u32 s57, s58, 0
	v_lshl_add_u32 v175, s8, 7, v2
	v_bfe_u32 v174, v4, 5, 1
	v_or_b32_e32 v188, v175, v176
	v_mov_b64_e32 v[6:7], s[56:57]
	s_add_u32 s50, s59, s0
	v_mad_i64_i32 v[6:7], s[0:1], v188, s75, v[6:7]
	v_lshlrev_b32_e32 v2, 4, v174
	v_lshl_add_u64 v[6:7], v[6:7], 0, v[2:3]
	v_ashrrev_i32_e32 v5, 2, v4
	v_lshlrev_b32_e32 v70, 3, v4
	global_load_dwordx4 v[100:103], v[6:7], off
	global_load_dwordx4 v[104:107], v[6:7], off offset:32
	global_load_dwordx4 v[108:111], v[6:7], off offset:64
	global_load_dwordx4 v[112:115], v[6:7], off offset:96
	global_load_dwordx4 v[116:119], v[6:7], off offset:128
	global_load_dwordx4 v[120:123], v[6:7], off offset:160
	global_load_dwordx4 v[124:127], v[6:7], off offset:192
	global_load_dwordx4 v[128:131], v[6:7], off offset:224
	global_load_dwordx4 v[132:135], v[6:7], off offset:256
	global_load_dwordx4 v[136:139], v[6:7], off offset:288
	global_load_dwordx4 v[140:143], v[6:7], off offset:320
	global_load_dwordx4 v[144:147], v[6:7], off offset:352
	v_mul_lo_u32 v6, v5, s76
	v_and_b32_e32 v2, 24, v70
	v_or_b32_e32 v172, v6, v2
	s_addc_u32 s51, s60, 0
	v_ashrrev_i32_e32 v173, 31, v172
	v_lshl_add_u64 v[30:31], v[172:173], 1, s[50:51]
	s_waitcnt vmcnt(0)
	s_barrier
	global_load_dwordx4 v[6:9], v[30:31], off
	global_load_dwordx4 v[10:13], v[30:31], off offset:64
	global_load_dwordx4 v[14:17], v[30:31], off offset:128
	global_load_dwordx4 v[18:21], v[30:31], off offset:192
	global_load_dwordx4 v[22:25], v[30:31], off offset:256
	global_load_dwordx4 v[26:29], v[30:31], off offset:320
	s_movk_i32 s2, 0x6000
	v_mad_u64_u32 v[196:197], s[0:1], v5, s77, v[2:3]
	v_add_co_u32_e32 v30, vcc, s2, v30
	v_lshl_add_u32 v71, v196, 1, s9
	s_nop 0
	v_addc_co_u32_e32 v31, vcc, 0, v31, vcc
	v_lshlrev_b32_e32 v72, 3, v174
	v_cmp_lt_i32_e64 s[2:3], -1, v175
	v_mul_u32_u24_e32 v2, 0xc8, v176
	s_waitcnt vmcnt(5)
	ds_write_b128 v71, v[6:9]
	s_waitcnt vmcnt(4)
	ds_write_b128 v71, v[10:13] offset:64
	s_waitcnt vmcnt(3)
	ds_write_b128 v71, v[14:17] offset:128
	s_waitcnt vmcnt(2)
	ds_write_b128 v71, v[18:21] offset:192
	s_waitcnt vmcnt(1)
	ds_write_b128 v71, v[22:25] offset:256
	s_waitcnt vmcnt(0)
	ds_write_b128 v71, v[26:29] offset:320
	s_waitcnt lgkmcnt(0)
	s_barrier
	global_load_dwordx4 v[148:151], v[30:31], off
	global_load_dwordx4 v[152:155], v[30:31], off offset:64
	global_load_dwordx4 v[156:159], v[30:31], off offset:128
	global_load_dwordx4 v[160:163], v[30:31], off offset:192
	global_load_dwordx4 v[164:167], v[30:31], off offset:256
	global_load_dwordx4 v[168:171], v[30:31], off offset:320
	v_mov_b32_e32 v215, 0
	v_lshlrev_b32_e32 v197, 1, v2
	v_lshlrev_b32_e32 v201, 1, v72
	v_mov_b32_e32 v36, 0
	v_mov_b32_e32 v37, 0
	v_mov_b32_e32 v38, 0
	v_mov_b32_e32 v39, 0
	v_mov_b32_e32 v40, 0
	v_mov_b32_e32 v41, 0
	v_mov_b32_e32 v42, 0
	v_mov_b32_e32 v43, 0
	v_mov_b32_e32 v44, 0
	v_mov_b32_e32 v45, 0
	v_mov_b32_e32 v46, 0
	v_mov_b32_e32 v47, 0
	v_mov_b32_e32 v48, 0
	v_mov_b32_e32 v49, 0
	v_mov_b32_e32 v50, 0
	v_mov_b32_e32 v51, 0
	v_mov_b32_e32 v20, 0
	v_mov_b32_e32 v21, 0
	v_mov_b32_e32 v22, 0
	v_mov_b32_e32 v23, 0
	v_mov_b32_e32 v24, 0
	v_mov_b32_e32 v25, 0
	v_mov_b32_e32 v26, 0
	v_mov_b32_e32 v27, 0
	v_mov_b32_e32 v28, 0
	v_mov_b32_e32 v29, 0
	v_mov_b32_e32 v30, 0
	v_mov_b32_e32 v31, 0
	v_mov_b32_e32 v32, 0
	v_mov_b32_e32 v33, 0
	v_mov_b32_e32 v34, 0
	v_mov_b32_e32 v35, 0
	s_and_saveexec_b64 s[0:1], s[2:3]
	s_cbranch_execz .LBB0_476
	s_setprio 1
	v_add3_u32 v2, s9, v197, v201
	ds_read_b128 v[6:9], v2
	s_mov_b32 s26, s12
	s_mov_b32 s27, s12
	s_mov_b32 s13, s12
	s_mov_b32 s14, s12
	s_mov_b32 s15, s12
	s_mov_b32 s16, s12
	s_mov_b32 s17, s12
	s_mov_b32 s18, s12
	s_mov_b32 s19, s12
	s_mov_b32 s20, s12
	s_mov_b32 s21, s12
	s_mov_b32 s22, s12
	s_mov_b32 s23, s12
	s_mov_b32 s24, s12
	s_mov_b32 s25, s12
	v_mov_b64_e32 v[34:35], s[26:27]
	v_mov_b64_e32 v[32:33], s[24:25]
	v_mov_b64_e32 v[30:31], s[22:23]
	v_mov_b64_e32 v[28:29], s[20:21]
	v_mov_b64_e32 v[26:27], s[18:19]
	v_mov_b64_e32 v[24:25], s[16:17]
	v_mov_b64_e32 v[22:23], s[14:15]
	v_mov_b64_e32 v[20:21], s[12:13]
	s_waitcnt lgkmcnt(0)
	s_nop 0
	v_mfma_f32_32x32x16_bf16 v[36:51], v[6:9], v[100:103], v[20:35]
	ds_read_b128 v[6:9], v2 offset:12800
	s_waitcnt lgkmcnt(0)
	v_mfma_f32_32x32x16_bf16 v[20:35], v[6:9], v[100:103], v[20:35]
	ds_read_b128 v[6:9], v2 offset:32
	s_waitcnt lgkmcnt(0)
	v_mfma_f32_32x32x16_bf16 v[36:51], v[6:9], v[104:107], v[36:51]
	ds_read_b128 v[6:9], v2 offset:12832
	s_waitcnt lgkmcnt(0)
	v_mfma_f32_32x32x16_bf16 v[20:35], v[6:9], v[104:107], v[20:35]
	ds_read_b128 v[6:9], v2 offset:64
	s_waitcnt lgkmcnt(0)
	v_mfma_f32_32x32x16_bf16 v[36:51], v[6:9], v[108:111], v[36:51]
	ds_read_b128 v[6:9], v2 offset:12864
	s_waitcnt lgkmcnt(0)
	v_mfma_f32_32x32x16_bf16 v[20:35], v[6:9], v[108:111], v[20:35]
	ds_read_b128 v[6:9], v2 offset:96
	s_waitcnt lgkmcnt(0)
	v_mfma_f32_32x32x16_bf16 v[36:51], v[6:9], v[112:115], v[36:51]
	ds_read_b128 v[6:9], v2 offset:12896
	s_waitcnt lgkmcnt(0)
	v_mfma_f32_32x32x16_bf16 v[20:35], v[6:9], v[112:115], v[20:35]
	ds_read_b128 v[6:9], v2 offset:128
	s_waitcnt lgkmcnt(0)
	v_mfma_f32_32x32x16_bf16 v[36:51], v[6:9], v[116:119], v[36:51]
	ds_read_b128 v[6:9], v2 offset:12928
	s_waitcnt lgkmcnt(0)
; DI float xmax32(float x) { auto r = __builtin_amdgcn_permlane32_swap(__float_as_uint(x), __float_as_uint(x), false, false); return fmaxf(__uint_as_float(r[0]), __uint_as_float(r[1])); }
; DI int crow(int i, int h) { return (i & 3) + 8 * (i >> 2) + 4 * h; }
; DI void attn_unit(unsigned char* smem, const Params& P, int bh, int qb) {
;     ...
;     if (active) {
; #pragma unroll
;       for (int a = 0; a < 2; ++a)
; #pragma unroll
;         for (int i = 0; i < 16; ++i) S[a][i] = -sref;
;       __builtin_amdgcn_s_setprio(1);
; #pragma unroll
;       for (int ks = 0; ks < 12; ++ks) {
;         const bf16x8 a0 = *(const bf16x8*)(cK + l31 * KLD + ks * 16 + hh * 8), a1 = *(const bf16x8*)(cK + (32 + l31) * KLD + ks * 16 + hh * 8);
;         S[0] = MFMA32(a0, qf[ks], S[0]); S[1] = MFMA32(a1, qf[ks], S[1]);
;       }
;       __builtin_amdgcn_s_setprio(0);
;     }
;     { const bf16_t* vp_ = vtb + (size_t)(tid >> 3) * 8192 + jt * 64 + (tid & 7) * 8; vr0 = *(const uint4*)(vp_ + (size_t)0 * 8192); vr1 = *(const uint4*)(vp_ + (size_t)32 * 8192); vr2 = *(const uint4*)(vp_ + (size_t)64 * 8192); vr3 = *(const uint4*)(vp_ + (size_t)96 * 8192); }
;     __builtin_amdgcn_sched_barrier(0);
;     if (active) {
;       if (jt >= ntiles - 2) {
; #pragma unroll
;         for (int kt = 0; kt < 2; ++kt)
; #pragma unroll
;           for (int i = 0; i < 16; ++i) { const int key = jt * 64 + kt * 32 + crow(i, hh); if (key > qrow) S[kt][i] = -1e30f; }
;       }
;       float mx = S[0][0];
; #pragma unroll
;       for (int i = 1; i < 16; ++i) mx = fmaxf(mx, S[0][i]);
; #pragma unroll
;       for (int i = 0; i < 16; ++i) mx = fmaxf(mx, S[1][i]);
;       mx = xmax32(mx);
;       if (!__all(mx - (mrun - sref) <= 8.0f)) {
;         const float mnew = fmaxf(mrun, mx + sref), alpha = __builtin_amdgcn_exp2f(mrun - mnew), shift = mnew - sref;
;         mrun = mnew; lrun *= alpha;
; #pragma unroll
;         for (int d = 0; d < 4; ++d)
; #pragma unroll
;           for (int i = 0; i < 16; ++i) O[d][i] *= alpha;
; #pragma unroll
;         for (int kt = 0; kt < 2; ++kt)
; #pragma unroll
;           for (int i = 0; i < 16; ++i) S[kt][i] -= shift;
;       }
;       float ls = 0.f;
; #pragma unroll
;       for (int kt = 0; kt < 2; ++kt)
; #pragma unroll
;         for (int i = 0; i < 16; ++i) { const float p = __builtin_amdgcn_exp2f(S[kt][i]); S[kt][i] = p; ls += p; }
;       lrun += ls;
	v_mfma_f32_32x32x16_bf16 v[20:35], v[6:9], v[116:119], v[20:35]
	ds_read_b128 v[6:9], v2 offset:160
	s_waitcnt lgkmcnt(0)
	v_mfma_f32_32x32x16_bf16 v[36:51], v[6:9], v[120:123], v[36:51]
	ds_read_b128 v[6:9], v2 offset:12960
	s_waitcnt lgkmcnt(0)
	v_mfma_f32_32x32x16_bf16 v[20:35], v[6:9], v[120:123], v[20:35]
	ds_read_b128 v[6:9], v2 offset:192
	s_waitcnt lgkmcnt(0)
	v_mfma_f32_32x32x16_bf16 v[36:51], v[6:9], v[124:127], v[36:51]
	ds_read_b128 v[6:9], v2 offset:12992
	s_waitcnt lgkmcnt(0)
	v_mfma_f32_32x32x16_bf16 v[20:35], v[6:9], v[124:127], v[20:35]
	ds_read_b128 v[6:9], v2 offset:224
	s_waitcnt lgkmcnt(0)
	v_mfma_f32_32x32x16_bf16 v[36:51], v[6:9], v[128:131], v[36:51]
	ds_read_b128 v[6:9], v2 offset:13024
	s_waitcnt lgkmcnt(0)
	v_mfma_f32_32x32x16_bf16 v[20:35], v[6:9], v[128:131], v[20:35]
	ds_read_b128 v[6:9], v2 offset:256
	s_waitcnt lgkmcnt(0)
	v_mfma_f32_32x32x16_bf16 v[36:51], v[6:9], v[132:135], v[36:51]
	ds_read_b128 v[6:9], v2 offset:13056
	s_waitcnt lgkmcnt(0)
	v_mfma_f32_32x32x16_bf16 v[20:35], v[6:9], v[132:135], v[20:35]
	ds_read_b128 v[6:9], v2 offset:288
	s_waitcnt lgkmcnt(0)
	v_mfma_f32_32x32x16_bf16 v[36:51], v[6:9], v[136:139], v[36:51]
	ds_read_b128 v[6:9], v2 offset:13088
	s_waitcnt lgkmcnt(0)
	v_mfma_f32_32x32x16_bf16 v[20:35], v[6:9], v[136:139], v[20:35]
	ds_read_b128 v[6:9], v2 offset:320
	s_waitcnt lgkmcnt(0)
	v_mfma_f32_32x32x16_bf16 v[36:51], v[6:9], v[140:143], v[36:51]
	ds_read_b128 v[6:9], v2 offset:13120
	s_waitcnt lgkmcnt(0)
	v_mfma_f32_32x32x16_bf16 v[20:35], v[6:9], v[140:143], v[20:35]
	ds_read_b128 v[6:9], v2 offset:352
	s_waitcnt lgkmcnt(0)
	v_mfma_f32_32x32x16_bf16 v[36:51], v[6:9], v[144:147], v[36:51]
	ds_read_b128 v[6:9], v2 offset:13152
	s_waitcnt lgkmcnt(0)
	v_mfma_f32_32x32x16_bf16 v[20:35], v[6:9], v[144:147], v[20:35]
	s_setprio 0
.LBB0_476:
	s_or_b64 exec, exec, s[0:1]
	s_barrier
	s_lshl_b32 s0, s97, 21
	v_ashrrev_i32_e32 v68, 3, v4
	s_add_u32 s52, s61, s0
	v_ashrrev_i32_e32 v69, 31, v68
	s_addc_u32 s53, s62, 0
	v_lshlrev_b64 v[4:5], 14, v[68:69]
	v_and_b32_e32 v2, 56, v70
	v_lshl_add_u64 v[4:5], s[52:53], 0, v[4:5]
	v_lshlrev_b32_e32 v2, 1, v2
	v_lshl_add_u64 v[198:199], v[4:5], 0, v[2:3]
	v_add_co_u32_e32 v4, vcc, s78, v198
	s_nop 1
	v_addc_co_u32_e32 v5, vcc, 0, v199, vcc
	global_load_dwordx4 v[52:55], v[198:199], off
	global_load_dwordx4 v[56:59], v[4:5], off
	v_add_co_u32_e32 v4, vcc, s79, v198
	s_nop 1
	v_addc_co_u32_e32 v5, vcc, 0, v199, vcc
	v_add_co_u32_e32 v6, vcc, s80, v198
	s_nop 1
	v_addc_co_u32_e32 v7, vcc, 0, v199, vcc
	global_load_dwordx4 v[60:63], v[4:5], off
	global_load_dwordx4 v[64:67], v[6:7], off
	v_mov_b32_e32 v4, v3
	v_mov_b32_e32 v5, v3
	v_mov_b32_e32 v6, v3
	v_mov_b32_e32 v7, v3
	v_mov_b32_e32 v8, v3
	v_mov_b32_e32 v9, v3
	v_mov_b32_e32 v10, v3
	v_mov_b32_e32 v11, v3
	v_mov_b32_e32 v12, v3
	v_mov_b32_e32 v13, v3
	v_mov_b32_e32 v14, v3
	v_mov_b32_e32 v15, v3
	v_mov_b32_e32 v16, v3
	v_mov_b32_e32 v17, v3
	v_mov_b32_e32 v2, v3
	v_mov_b64_e32 v[18:19], v[16:17]
	v_mov_b32_e32 v200, 0xf149f2ca
	v_mov_b64_e32 v[16:17], v[14:15]
	v_mov_b64_e32 v[14:15], v[12:13]
	v_mov_b64_e32 v[12:13], v[10:11]
	v_mov_b64_e32 v[10:11], v[8:9]
	v_mov_b64_e32 v[8:9], v[6:7]
	v_mov_b64_e32 v[6:7], v[4:5]
	v_mov_b64_e32 v[4:5], v[2:3]
	s_and_saveexec_b64 s[0:1], s[2:3]
	s_cbranch_execz .LBB0_481
	v_max_f32_e32 v2, v37, v37
	v_max_f32_e32 v4, v36, v36
	v_max_f32_e32 v2, v4, v2
	v_max3_f32 v2, v2, v38, v39
	v_max3_f32 v2, v2, v40, v41
	v_max3_f32 v2, v2, v42, v43
	v_max3_f32 v2, v2, v44, v45
	v_max3_f32 v2, v2, v46, v47
	v_max3_f32 v2, v2, v48, v49
	v_max3_f32 v2, v2, v50, v51
	v_max3_f32 v2, v2, v20, v21
	v_max3_f32 v2, v2, v22, v23
	v_max3_f32 v2, v2, v24, v25
	v_max3_f32 v2, v2, v26, v27
	v_max3_f32 v2, v2, v28, v29
	v_max3_f32 v2, v2, v30, v31
	v_max3_f32 v2, v2, v32, v33
	v_max3_f32 v2, v2, v34, v35
	v_mov_b32_e32 v4, v2
	s_nop 1
	v_permlane32_swap_b32_e32 v2, v4
	v_max_f32_e32 v4, v4, v4
	v_max_f32_e32 v2, v2, v2
	v_max_f32_e32 v2, v2, v4
	v_add_f32_e32 v4, 0x7149f2ca, v2
	v_cmp_ge_f32_e32 vcc, s81, v4
	s_cmp_eq_u64 vcc, exec
	s_cbranch_scc1 .LBB0_479
	v_add_f32_e32 v2, 0, v2
	v_max_f32_e32 v200, 0xf149f2ca, v2
	v_sub_f32_e32 v2, 0xf149f2ca, v200
	v_exp_f32_e32 v2, v2
	v_pk_add_f32 v[36:37], v[36:37], v[200:201] op_sel_hi:[1,0] neg_lo:[0,1] neg_hi:[0,1]
	v_pk_add_f32 v[38:39], v[38:39], v[200:201] op_sel_hi:[1,0] neg_lo:[0,1] neg_hi:[0,1]
	v_pk_add_f32 v[40:41], v[40:41], v[200:201] op_sel_hi:[1,0] neg_lo:[0,1] neg_hi:[0,1]
	v_mul_f32_e32 v4, 0, v2
	v_mov_b32_e32 v5, v4
	v_mov_b32_e32 v6, v4
	v_mov_b32_e32 v7, v4
	v_mov_b32_e32 v8, v4
	v_mov_b32_e32 v9, v4
	v_mov_b32_e32 v10, v4
	v_mov_b32_e32 v11, v4
	v_mov_b32_e32 v12, v4
	v_mov_b32_e32 v13, v4
	v_mov_b32_e32 v14, v4
	v_mov_b32_e32 v15, v4
	v_mov_b32_e32 v16, v4
	v_mov_b32_e32 v17, v4
	v_mov_b32_e32 v18, v4
	v_mov_b32_e32 v19, v4
	v_pk_add_f32 v[42:43], v[42:43], v[200:201] op_sel_hi:[1,0] neg_lo:[0,1] neg_hi:[0,1]
	v_pk_add_f32 v[44:45], v[44:45], v[200:201] op_sel_hi:[1,0] neg_lo:[0,1] neg_hi:[0,1]
	v_pk_add_f32 v[46:47], v[46:47], v[200:201] op_sel_hi:[1,0] neg_lo:[0,1] neg_hi:[0,1]
	v_pk_add_f32 v[48:49], v[48:49], v[200:201] op_sel_hi:[1,0] neg_lo:[0,1] neg_hi:[0,1]
	v_pk_add_f32 v[50:51], v[50:51], v[200:201] op_sel_hi:[1,0] neg_lo:[0,1] neg_hi:[0,1]
	v_pk_add_f32 v[20:21], v[20:21], v[200:201] op_sel_hi:[1,0] neg_lo:[0,1] neg_hi:[0,1]
	v_pk_add_f32 v[22:23], v[22:23], v[200:201] op_sel_hi:[1,0] neg_lo:[0,1] neg_hi:[0,1]
	v_pk_add_f32 v[24:25], v[24:25], v[200:201] op_sel_hi:[1,0] neg_lo:[0,1] neg_hi:[0,1]
	v_pk_add_f32 v[26:27], v[26:27], v[200:201] op_sel_hi:[1,0] neg_lo:[0,1] neg_hi:[0,1]
	v_pk_add_f32 v[28:29], v[28:29], v[200:201] op_sel_hi:[1,0] neg_lo:[0,1] neg_hi:[0,1]
	v_pk_add_f32 v[30:31], v[30:31], v[200:201] op_sel_hi:[1,0] neg_lo:[0,1] neg_hi:[0,1]
	v_pk_add_f32 v[32:33], v[32:33], v[200:201] op_sel_hi:[1,0] neg_lo:[0,1] neg_hi:[0,1]
	v_pk_add_f32 v[34:35], v[34:35], v[200:201] op_sel_hi:[1,0] neg_lo:[0,1] neg_hi:[0,1]
	v_mov_b32_e32 v69, v4
	s_branch .LBB0_480

; DI void attn_unit(unsigned char* smem, const Params& P, int bh, int qb) {
;     ...
;     { bf16_t* vq_ = sV + (tid >> 3) * LDK + ((tid & 7) >> 1) * 16 + (tid & 1) * 4;
;       *(uint2*)(vq_) = make_uint2(vr0.x, vr0.y); *(uint2*)(vq_ + 8) = make_uint2(vr0.z, vr0.w);
;       *(uint2*)(vq_ + 32 * LDK) = make_uint2(vr1.x, vr1.y); *(uint2*)(vq_ + 32 * LDK + 8) = make_uint2(vr1.z, vr1.w);
;       *(uint2*)(vq_ + 64 * LDK) = make_uint2(vr2.x, vr2.y); *(uint2*)(vq_ + 64 * LDK + 8) = make_uint2(vr2.z, vr2.w);
;       *(uint2*)(vq_ + 96 * LDK) = make_uint2(vr3.x, vr3.y); *(uint2*)(vq_ + 96 * LDK + 8) = make_uint2(vr3.z, vr3.w); }
;     if (more) {
;       *(uint4*)(nK + klo + 0) = kr0; *(uint4*)(nK + klo + 32) = kr1; *(uint4*)(nK + klo + 64) = kr2; *(uint4*)(nK + klo + 96) = kr3; *(uint4*)(nK + klo + 128) = kr4; *(uint4*)(nK + klo + 160) = kr5;
;     }
;     __syncthreads();
; DI void run_phase(unsigned char* smem_in, const Params& P, int ph) {
;     ...
;         const int i = it - 272, x = (i >> 1) & 7, bh = x * 2 + (i & 1), j = i >> 4;
;         for (int rep = 0; rep < ATTN_REPS; ++rep) {
;           attn_unit(smem, P, bh, 63 - j);
.LBB0_481:
	s_or_b64 exec, exec, s[0:1]
	v_mul_lo_u32 v2, v68, s82
	v_and_b32_e32 v68, 48, v70
	v_add_u32_e32 v2, s9, v2
	v_lshlrev_b32_e32 v68, 1, v68
	v_and_b32_e32 v69, 8, v70
	v_ashrrev_i32_e32 v189, 31, v188
	v_add3_u32 v68, v2, v68, v69
	v_lshl_add_u32 v177, v72, 1, s9
	v_add_u32_e32 v2, 0x6000, v68
	v_add_u32_e32 v216, 0x7000, v68
	v_add_u32_e32 v217, 0x8800, v68
	v_add_u32_e32 v218, 0x9800, v68
	v_mul_u32_u24_e32 v178, 0x48, v176
	v_mad_u32_u24 v179, v176, s83, v210
	v_mad_u32_u24 v180, v176, s83, v211
	v_mad_u32_u24 v181, v176, s83, v212
	s_waitcnt vmcnt(3)
	ds_write2_b64 v2, v[52:53], v[54:55] offset0:128 offset1:130
	s_waitcnt vmcnt(2)
	ds_write2_b64 v216, v[56:57], v[58:59] offset0:192 offset1:194
	s_waitcnt vmcnt(1)
	ds_write2_b64 v217, v[60:61], v[62:63] offset1:2
	s_waitcnt vmcnt(0)
	ds_write2_b64 v218, v[64:65], v[66:67] offset0:64 offset1:66
	ds_write_b128 v71, v[148:151] offset:44032
	ds_write_b128 v71, v[152:155] offset:44096
	ds_write_b128 v71, v[156:159] offset:44160
	ds_write_b128 v71, v[160:163] offset:44224
	ds_write_b128 v71, v[164:167] offset:44288
	ds_write_b128 v71, v[168:171] offset:44352
	s_waitcnt lgkmcnt(0)
	s_barrier
	s_nop 8
	v_mov_b64_e32 v[66:67], v[18:19]
	v_mov_b64_e32 v[82:83], v[18:19]
	v_mov_b64_e32 v[98:99], v[18:19]
	v_mov_b64_e32 v[64:65], v[16:17]
	v_mov_b64_e32 v[62:63], v[14:15]
	v_mov_b64_e32 v[60:61], v[12:13]
	v_mov_b64_e32 v[58:59], v[10:11]
	v_mov_b64_e32 v[56:57], v[8:9]
	v_mov_b64_e32 v[54:55], v[6:7]
	v_mov_b64_e32 v[52:53], v[4:5]
	v_mov_b64_e32 v[80:81], v[16:17]
	v_mov_b64_e32 v[78:79], v[14:15]
	v_mov_b64_e32 v[76:77], v[12:13]
	v_mov_b64_e32 v[74:75], v[10:11]
	v_mov_b64_e32 v[72:73], v[8:9]
	v_mov_b64_e32 v[70:71], v[6:7]
	v_mov_b64_e32 v[68:69], v[4:5]
	v_mov_b64_e32 v[96:97], v[16:17]
	v_mov_b64_e32 v[94:95], v[14:15]
	v_mov_b64_e32 v[92:93], v[12:13]
	v_mov_b64_e32 v[90:91], v[10:11]
	v_mov_b64_e32 v[88:89], v[8:9]
	v_mov_b64_e32 v[86:87], v[6:7]
	v_mov_b64_e32 v[84:85], v[4:5]
	s_and_b32 s0, s7, 15
	s_mul_i32 s96, s0, 0x300000
	s_lshr_b32 s0, s67, 4
	s_lshl_b32 s8, s8, 1
	s_lshl_b32 s85, s0, 1
	s_add_i32 s13, s8, 2
	s_sub_i32 s18, 0, s85
	s_add_u32 s0, s65, s96
	s_addc_u32 s1, s66, 0
	v_or_b32_e32 v220, 31, v175
	v_lshlrev_b32_e32 v219, 2, v174
	s_mov_b32 s20, 0
	v_lshl_add_u32 v221, v178, 1, v177
	v_lshl_add_u32 v222, v179, 1, v177
	v_lshl_add_u32 v223, v180, 1, v177
	v_lshl_add_u32 v224, v181, 1, v177
	v_lshl_add_u64 v[202:203], v[172:173], 1, s[0:1]
	s_movk_i32 s19, 0xff81

; #define MFMA32(a, b, c) __builtin_amdgcn_mfma_f32_32x32x16_bf16((a), (b), (c), 0, 0, 0)
; DI void attn_unit(unsigned char* smem, const Params& P, int bh, int qb) {
;     ...
;   for (int jt = 0; jt < ntiles; ++jt) {
;     const bf16_t* cK = (jt & 1) ? sK1 : sK;
;     bf16_t* nK = (jt & 1) ? sK : sK1;
;     const bool more = (jt + 1 < ntiles);
;     const bool active = (jt * 64 <= q0 + 32 * w + 31);
;     if (more) {
;       const bf16_t* kp = kbuf + (size_t)(jt + 1) * 64 * 192;
;       kr0 = *(const uint4*)(kp + kgo + 0); kr1 = *(const uint4*)(kp + kgo + 32); kr2 = *(const uint4*)(kp + kgo + 64); kr3 = *(const uint4*)(kp + kgo + 96); kr4 = *(const uint4*)(kp + kgo + 128); kr5 = *(const uint4*)(kp + kgo + 160);
;     }
;     __builtin_amdgcn_sched_barrier(0);
;     f32x16 S[2];
;     const float sref = (jt == 0) ? 0.f : mrun;
;     if (active) {
; #pragma unroll
;       for (int a = 0; a < 2; ++a)
; #pragma unroll
;         for (int i = 0; i < 16; ++i) S[a][i] = -sref;
;       __builtin_amdgcn_s_setprio(1);
; #pragma unroll
;       for (int ks = 0; ks < 12; ++ks) {
;         const bf16x8 a0 = *(const bf16x8*)(cK + l31 * KLD + ks * 16 + hh * 8), a1 = *(const bf16x8*)(cK + (32 + l31) * KLD + ks * 16 + hh * 8);
;         S[0] = MFMA32(a0, qf[ks], S[0]); S[1] = MFMA32(a1, qf[ks], S[1]);
;       }
;       __builtin_amdgcn_s_setprio(0);
;     }
;     { const bf16_t* vp_ = vtb + (size_t)(tid >> 3) * 8192 + jt * 64 + (tid & 7) * 8; vr0 = *(const uint4*)(vp_ + (size_t)0 * 8192); vr1 = *(const uint4*)(vp_ + (size_t)32 * 8192); vr2 = *(const uint4*)(vp_ + (size_t)64 * 8192); vr3 = *(const uint4*)(vp_ + (size_t)96 * 8192); }
;     ...
;     if (active) {
;       __builtin_amdgcn_s_setprio(1);
; #pragma unroll
;       for (int kt = 0; kt < 2; ++kt)
; #pragma unroll
;         for (int s2 = 0; s2 < 2; ++s2) {
;           uint4 pp; pp.x = pk2(S[kt][8 * s2], S[kt][8 * s2 + 1]); pp.y = pk2(S[kt][8 * s2 + 2], S[kt][8 * s2 + 3]);
;           pp.z = pk2(S[kt][8 * s2 + 4], S[kt][8 * s2 + 5]); pp.w = pk2(S[kt][8 * s2 + 6], S[kt][8 * s2 + 7]);
;           const bf16x8 pb = __builtin_bit_cast(bf16x8, pp);
; #pragma unroll
;           for (int d = 0; d < 4; ++d) {
;             const bf16x8 vf = *(const bf16x8*)(sV + (d * 32 + l31) * LDK + kt * 32 + s2 * 16 + hh * 8);
;             O[d] = MFMA32(vf, pb, O[d]);
;           }
;         }
;       __builtin_amdgcn_s_setprio(0);
;     }
.LBB0_488:
	s_add_i32 s21, s19, 0x80
	s_bitcmp0_b32 s21, 0
	s_cselect_b64 s[14:15], -1, 0
	s_add_i32 s10, s20, 64
	v_cmp_le_i32_e64 s[2:3], s10, v220
	v_cmp_le_i32_e64 s[98:99], s20, v220
	s_cmp_lg_u64 s[2:3], 0
	s_cbranch_scc0 .Lslow_0
	s_and_b64 s[22:23], s[14:15], exec
	s_cselect_b32 s22, s9, s28
	v_add3_u32 v243, s22, v197, v201
	s_setprio 1
	ds_read_b128 v[180:183], v221 offset:25600
	ds_read_b128 v[184:187], v222 offset:25600
	ds_read_b128 v[226:229], v223 offset:25600
	ds_read_b128 v[230:233], v224 offset:25600
	ds_read_b128 v[244:247], v221 offset:25632
	ds_read_b128 v[248:251], v222 offset:25632
	ds_read_b128 v[252:255], v223 offset:25632
	v_cvt_pk_bf16_f32 v176, v36, v37
	v_cvt_pk_bf16_f32 v177, v38, v39
	v_cvt_pk_bf16_f32 v178, v40, v41
	v_cvt_pk_bf16_f32 v179, v42, v43
	v_cvt_pk_bf16_f32 v172, v44, v45
	v_cvt_pk_bf16_f32 v173, v46, v47
	v_cvt_pk_bf16_f32 v174, v48, v49
	v_cvt_pk_bf16_f32 v175, v50, v51
	s_waitcnt lgkmcnt(6)
	v_mfma_f32_32x32x16_bf16 v[84:99], v[180:183], v[176:179], v[84:99]
	ds_read_b128 v[180:183], v224 offset:25632
	global_load_dwordx4 v[148:151], v[202:203], off
	s_waitcnt lgkmcnt(6)
	v_mfma_f32_32x32x16_bf16 v[68:83], v[184:187], v[176:179], v[68:83]
	ds_read_b128 v[184:187], v221 offset:25664
	global_load_dwordx4 v[152:155], v[202:203], off offset:64
	s_waitcnt lgkmcnt(6)
	v_mfma_f32_32x32x16_bf16 v[52:67], v[226:229], v[176:179], v[52:67]
	ds_read_b128 v[226:229], v222 offset:25664
	global_load_dwordx4 v[156:159], v[202:203], off offset:128
	s_waitcnt lgkmcnt(6)
	v_mfma_f32_32x32x16_bf16 v[4:19], v[230:233], v[176:179], v[4:19]
	ds_read_b128 v[230:233], v223 offset:25664
	global_load_dwordx4 v[160:163], v[202:203], off offset:192
	s_waitcnt lgkmcnt(6)
	v_mfma_f32_32x32x16_bf16 v[84:99], v[244:247], v[172:175], v[84:99]
	ds_read_b128 v[244:247], v224 offset:25664
	global_load_dwordx4 v[164:167], v[202:203], off offset:256
	v_cvt_pk_bf16_f32 v176, v20, v21
	v_cvt_pk_bf16_f32 v177, v22, v23
	v_cvt_pk_bf16_f32 v178, v24, v25
	v_cvt_pk_bf16_f32 v179, v26, v27
	s_waitcnt lgkmcnt(6)
	v_mfma_f32_32x32x16_bf16 v[68:83], v[248:251], v[172:175], v[68:83]
	ds_read_b128 v[248:251], v221 offset:25696
	global_load_dwordx4 v[168:171], v[202:203], off offset:320
	s_waitcnt lgkmcnt(6)
	v_mfma_f32_32x32x16_bf16 v[52:67], v[252:255], v[172:175], v[52:67]
	ds_read_b128 v[252:255], v222 offset:25696
	s_waitcnt lgkmcnt(6)
	v_mfma_f32_32x32x16_bf16 v[4:19], v[180:183], v[172:175], v[4:19]
	ds_read_b128 v[180:183], v223 offset:25696
	s_waitcnt lgkmcnt(6)
	v_mfma_f32_32x32x16_bf16 v[84:99], v[184:187], v[176:179], v[84:99]
	ds_read_b128 v[184:187], v224 offset:25696
	v_cvt_pk_bf16_f32 v172, v28, v29
	v_cvt_pk_bf16_f32 v173, v30, v31
	v_cvt_pk_bf16_f32 v174, v32, v33
	v_cvt_pk_bf16_f32 v175, v34, v35
	s_waitcnt lgkmcnt(6)
	v_mfma_f32_32x32x16_bf16 v[68:83], v[226:229], v[176:179], v[68:83]
	v_xor_b32_e32 v20, 0x80000000, v200
	v_mov_b32_e32 v21, v20
	v_mov_b32_e32 v22, v20
	v_mov_b32_e32 v23, v20
	ds_read_b128 v[226:229], v243 offset:12832
	s_waitcnt lgkmcnt(6)
	v_mfma_f32_32x32x16_bf16 v[52:67], v[230:233], v[176:179], v[52:67]
	v_mov_b32_e32 v24, v20
	v_mov_b32_e32 v25, v20
	v_mov_b32_e32 v26, v20
	v_mov_b32_e32 v27, v20
	ds_read_b128 v[230:233], v243 offset:64
	s_waitcnt lgkmcnt(6)
	v_mfma_f32_32x32x16_bf16 v[4:19], v[244:247], v[176:179], v[4:19]
	v_mov_b32_e32 v28, v20
	v_mov_b32_e32 v29, v20
	v_mov_b32_e32 v30, v20
	v_mov_b32_e32 v31, v20
	ds_read_b128 v[244:247], v243
	s_waitcnt lgkmcnt(6)
	v_mfma_f32_32x32x16_bf16 v[84:99], v[248:251], v[172:175], v[84:99]
	v_mov_b32_e32 v32, v20
	v_mov_b32_e32 v33, v20
	v_mov_b32_e32 v34, v20
	v_mov_b32_e32 v35, v20
	ds_read_b128 v[248:251], v243 offset:12800
	s_waitcnt lgkmcnt(6)
	v_mfma_f32_32x32x16_bf16 v[68:83], v[252:255], v[172:175], v[68:83]
	ds_read_b128 v[252:255], v243 offset:32
	s_waitcnt lgkmcnt(6)
	v_mfma_f32_32x32x16_bf16 v[52:67], v[180:183], v[172:175], v[52:67]
	s_waitcnt lgkmcnt(5)
	v_mfma_f32_32x32x16_bf16 v[4:19], v[184:187], v[172:175], v[4:19]
	s_waitcnt lgkmcnt(2)
	v_mfma_f32_32x32x16_bf16 v[36:51], v[244:247], v[100:103], v[20:35]
	ds_read_b128 v[244:247], v243 offset:12864
	v_lshl_add_u64 v[180:181], s[10:11], 1, v[198:199]
	v_add_co_u32_e32 v176, vcc, s78, v180
	s_nop 1
	v_addc_co_u32_e32 v177, vcc, 0, v181, vcc
	s_waitcnt lgkmcnt(2)
	v_mfma_f32_32x32x16_bf16 v[20:35], v[248:251], v[100:103], v[20:35]
	ds_read_b128 v[248:251], v243 offset:96
	v_add_co_u32_e32 v182, vcc, 0x100000, v180
	global_load_dwordx4 v[172:175], v[180:181], off
	s_nop 0
	global_load_dwordx4 v[176:179], v[176:177], off
	s_waitcnt lgkmcnt(2)
	v_mfma_f32_32x32x16_bf16 v[36:51], v[252:255], v[104:107], v[36:51]
	ds_read_b128 v[252:255], v243 offset:12896
	v_addc_co_u32_e32 v183, vcc, 0, v181, vcc
	v_add_co_u32_e32 v180, vcc, 0x180000, v180
	s_nop 1
	v_addc_co_u32_e32 v181, vcc, 0, v181, vcc
	s_waitcnt lgkmcnt(7)
	v_mfma_f32_32x32x16_bf16 v[20:35], v[226:229], v[104:107], v[20:35]
	ds_read_b128 v[226:229], v243 offset:128
	global_load_dwordx4 v[184:187], v[182:183], off
	s_nop 0
	global_load_dwordx4 v[180:183], v[180:181], off
	s_waitcnt lgkmcnt(7)
	v_mfma_f32_32x32x16_bf16 v[36:51], v[230:233], v[108:111], v[36:51]
	ds_read_b128 v[230:233], v243 offset:12928
	s_waitcnt lgkmcnt(4)
	v_mfma_f32_32x32x16_bf16 v[20:35], v[244:247], v[108:111], v[20:35]
	ds_read_b128 v[244:247], v243 offset:160
	s_waitcnt lgkmcnt(4)
	v_mfma_f32_32x32x16_bf16 v[36:51], v[248:251], v[112:115], v[36:51]
	ds_read_b128 v[248:251], v243 offset:12960
	s_waitcnt lgkmcnt(4)
	v_mfma_f32_32x32x16_bf16 v[20:35], v[252:255], v[112:115], v[20:35]
	ds_read_b128 v[252:255], v243 offset:192
	s_waitcnt lgkmcnt(4)
; #define MFMA32(a, b, c) __builtin_amdgcn_mfma_f32_32x32x16_bf16((a), (b), (c), 0, 0, 0)
; DI void attn_unit(unsigned char* smem, const Params& P, int bh, int qb) {
;     ...
;       kr0 = *(const uint4*)(kp + kgo + 0); kr1 = *(const uint4*)(kp + kgo + 32); kr2 = *(const uint4*)(kp + kgo + 64); kr3 = *(const uint4*)(kp + kgo + 96); kr4 = *(const uint4*)(kp + kgo + 128); kr5 = *(const uint4*)(kp + kgo + 160);
;     }
;     __builtin_amdgcn_sched_barrier(0);
;     f32x16 S[2];
;     const float sref = (jt == 0) ? 0.f : mrun;
;     if (active) {
; #pragma unroll
;       for (int a = 0; a < 2; ++a)
; #pragma unroll
;         for (int i = 0; i < 16; ++i) S[a][i] = -sref;
;       __builtin_amdgcn_s_setprio(1);
; #pragma unroll
;       for (int ks = 0; ks < 12; ++ks) {
;         const bf16x8 a0 = *(const bf16x8*)(cK + l31 * KLD + ks * 16 + hh * 8), a1 = *(const bf16x8*)(cK + (32 + l31) * KLD + ks * 16 + hh * 8);
;         S[0] = MFMA32(a0, qf[ks], S[0]); S[1] = MFMA32(a1, qf[ks], S[1]);
;       }
;       __builtin_amdgcn_s_setprio(0);
;     ...
;     if (active) {
;       __builtin_amdgcn_s_setprio(1);
; #pragma unroll
;       for (int kt = 0; kt < 2; ++kt)
; #pragma unroll
;         for (int s2 = 0; s2 < 2; ++s2) {
;           uint4 pp; pp.x = pk2(S[kt][8 * s2], S[kt][8 * s2 + 1]); pp.y = pk2(S[kt][8 * s2 + 2], S[kt][8 * s2 + 3]);
;           pp.z = pk2(S[kt][8 * s2 + 4], S[kt][8 * s2 + 5]); pp.w = pk2(S[kt][8 * s2 + 6], S[kt][8 * s2 + 7]);
;           const bf16x8 pb = __builtin_bit_cast(bf16x8, pp);
; #pragma unroll
;           for (int d = 0; d < 4; ++d) {
;             const bf16x8 vf = *(const bf16x8*)(sV + (d * 32 + l31) * LDK + kt * 32 + s2 * 16 + hh * 8);
;             O[d] = MFMA32(vf, pb, O[d]);
;           }
;         }
;       __builtin_amdgcn_s_setprio(0);
;     }
	v_mfma_f32_32x32x16_bf16 v[36:51], v[226:229], v[116:119], v[36:51]
	ds_read_b128 v[226:229], v243 offset:12992
	s_waitcnt lgkmcnt(4)
	v_mfma_f32_32x32x16_bf16 v[20:35], v[230:233], v[116:119], v[20:35]
	ds_read_b128 v[230:233], v243 offset:224
	s_waitcnt lgkmcnt(4)
	v_mfma_f32_32x32x16_bf16 v[36:51], v[244:247], v[120:123], v[36:51]
	ds_read_b128 v[244:247], v243 offset:13024
	s_waitcnt lgkmcnt(4)
	v_mfma_f32_32x32x16_bf16 v[20:35], v[248:251], v[120:123], v[20:35]
	ds_read_b128 v[248:251], v243 offset:256
	s_waitcnt lgkmcnt(4)
	v_mfma_f32_32x32x16_bf16 v[36:51], v[252:255], v[124:127], v[36:51]
	ds_read_b128 v[252:255], v243 offset:13056
	s_waitcnt lgkmcnt(4)
	v_mfma_f32_32x32x16_bf16 v[20:35], v[226:229], v[124:127], v[20:35]
	ds_read_b128 v[226:229], v243 offset:288
	s_waitcnt lgkmcnt(4)
	v_mfma_f32_32x32x16_bf16 v[36:51], v[230:233], v[128:131], v[36:51]
	ds_read_b128 v[230:233], v243 offset:13088
	s_waitcnt lgkmcnt(4)
	v_mfma_f32_32x32x16_bf16 v[20:35], v[244:247], v[128:131], v[20:35]
	ds_read_b128 v[244:247], v243 offset:320
	s_waitcnt lgkmcnt(4)
	v_mfma_f32_32x32x16_bf16 v[36:51], v[248:251], v[132:135], v[36:51]
	ds_read_b128 v[248:251], v243 offset:13120
	s_waitcnt lgkmcnt(4)
	v_mfma_f32_32x32x16_bf16 v[20:35], v[252:255], v[132:135], v[20:35]
	ds_read_b128 v[252:255], v243 offset:352
	s_waitcnt lgkmcnt(4)
	v_mfma_f32_32x32x16_bf16 v[36:51], v[226:229], v[136:139], v[36:51]
	ds_read_b128 v[226:229], v243 offset:13152
	s_waitcnt lgkmcnt(4)
	v_mfma_f32_32x32x16_bf16 v[20:35], v[230:233], v[136:139], v[20:35]
	s_waitcnt lgkmcnt(3)
	v_mfma_f32_32x32x16_bf16 v[36:51], v[244:247], v[140:143], v[36:51]
	s_waitcnt lgkmcnt(2)
	v_mfma_f32_32x32x16_bf16 v[20:35], v[248:251], v[140:143], v[20:35]
	s_waitcnt lgkmcnt(1)
	v_mfma_f32_32x32x16_bf16 v[36:51], v[252:255], v[144:147], v[36:51]
	s_waitcnt lgkmcnt(0)
	v_mfma_f32_32x32x16_bf16 v[20:35], v[226:229], v[144:147], v[20:35]
	s_nop 11
	s_setprio 0
	s_branch .LBB0_490
.Lslow_0:
	s_cmp_lg_u64 s[0:1], 0
	s_cbranch_scc0 .Lnok2_0
	global_load_dwordx4 v[148:151], v[202:203], off
	global_load_dwordx4 v[152:155], v[202:203], off offset:64
	global_load_dwordx4 v[156:159], v[202:203], off offset:128
	global_load_dwordx4 v[160:163], v[202:203], off offset:192
	global_load_dwordx4 v[164:167], v[202:203], off offset:256
	global_load_dwordx4 v[168:171], v[202:203], off offset:320
.Lnok2_0:
	s_and_saveexec_b64 s[100:101], s[98:99]
	s_cbranch_execz .Lpvtop_skip_0
	s_setprio 1
	ds_read_b128 v[180:183], v221 offset:25600
	ds_read_b128 v[184:187], v222 offset:25600
	ds_read_b128 v[226:229], v223 offset:25600
	ds_read_b128 v[230:233], v224 offset:25600
	ds_read_b128 v[244:247], v221 offset:25632
	ds_read_b128 v[248:251], v222 offset:25632
	ds_read_b128 v[252:255], v223 offset:25632
	v_cvt_pk_bf16_f32 v176, v36, v37
	v_cvt_pk_bf16_f32 v177, v38, v39
	v_cvt_pk_bf16_f32 v178, v40, v41
	v_cvt_pk_bf16_f32 v179, v42, v43
	v_cvt_pk_bf16_f32 v172, v44, v45
	v_cvt_pk_bf16_f32 v173, v46, v47
	v_cvt_pk_bf16_f32 v174, v48, v49
	v_cvt_pk_bf16_f32 v175, v50, v51
	s_waitcnt lgkmcnt(6)
	v_mfma_f32_32x32x16_bf16 v[84:99], v[180:183], v[176:179], v[84:99]
	ds_read_b128 v[180:183], v224 offset:25632
	s_waitcnt lgkmcnt(6)
	v_mfma_f32_32x32x16_bf16 v[68:83], v[184:187], v[176:179], v[68:83]
	ds_read_b128 v[184:187], v221 offset:25664
	s_waitcnt lgkmcnt(6)
	v_mfma_f32_32x32x16_bf16 v[52:67], v[226:229], v[176:179], v[52:67]
	ds_read_b128 v[226:229], v222 offset:25664
	s_waitcnt lgkmcnt(6)
	v_mfma_f32_32x32x16_bf16 v[4:19], v[230:233], v[176:179], v[4:19]
	ds_read_b128 v[230:233], v223 offset:25664
	s_waitcnt lgkmcnt(6)
	v_mfma_f32_32x32x16_bf16 v[84:99], v[244:247], v[172:175], v[84:99]
	ds_read_b128 v[244:247], v224 offset:25664
	v_cvt_pk_bf16_f32 v176, v20, v21
	v_cvt_pk_bf16_f32 v177, v22, v23
	v_cvt_pk_bf16_f32 v178, v24, v25
	v_cvt_pk_bf16_f32 v179, v26, v27
	s_waitcnt lgkmcnt(6)
	v_mfma_f32_32x32x16_bf16 v[68:83], v[248:251], v[172:175], v[68:83]
	ds_read_b128 v[248:251], v221 offset:25696
	s_waitcnt lgkmcnt(6)
	v_mfma_f32_32x32x16_bf16 v[52:67], v[252:255], v[172:175], v[52:67]
	ds_read_b128 v[252:255], v222 offset:25696
	s_waitcnt lgkmcnt(6)
	v_mfma_f32_32x32x16_bf16 v[4:19], v[180:183], v[172:175], v[4:19]
	ds_read_b128 v[180:183], v223 offset:25696
	s_waitcnt lgkmcnt(6)
	v_mfma_f32_32x32x16_bf16 v[84:99], v[184:187], v[176:179], v[84:99]
	ds_read_b128 v[184:187], v224 offset:25696
	v_cvt_pk_bf16_f32 v172, v28, v29
	v_cvt_pk_bf16_f32 v173, v30, v31
	v_cvt_pk_bf16_f32 v174, v32, v33
	v_cvt_pk_bf16_f32 v175, v34, v35
	s_waitcnt lgkmcnt(6)
	v_mfma_f32_32x32x16_bf16 v[68:83], v[226:229], v[176:179], v[68:83]
	s_waitcnt lgkmcnt(5)
	v_mfma_f32_32x32x16_bf16 v[52:67], v[230:233], v[176:179], v[52:67]
	s_waitcnt lgkmcnt(4)
	v_mfma_f32_32x32x16_bf16 v[4:19], v[244:247], v[176:179], v[4:19]
	s_waitcnt lgkmcnt(3)
	v_mfma_f32_32x32x16_bf16 v[84:99], v[248:251], v[172:175], v[84:99]
	s_waitcnt lgkmcnt(2)
	v_mfma_f32_32x32x16_bf16 v[68:83], v[252:255], v[172:175], v[68:83]
	s_waitcnt lgkmcnt(1)
	v_mfma_f32_32x32x16_bf16 v[52:67], v[180:183], v[172:175], v[52:67]
	s_waitcnt lgkmcnt(0)
	v_mfma_f32_32x32x16_bf16 v[4:19], v[184:187], v[172:175], v[4:19]
	s_setprio 0
; #define MFMA32(a, b, c) __builtin_amdgcn_mfma_f32_32x32x16_bf16((a), (b), (c), 0, 0, 0)
; DI void attn_unit(unsigned char* smem, const Params& P, int bh, int qb) {
;     ...
;     if (active) {
; #pragma unroll
;       for (int a = 0; a < 2; ++a)
; #pragma unroll
;         for (int i = 0; i < 16; ++i) S[a][i] = -sref;
;       __builtin_amdgcn_s_setprio(1);
; #pragma unroll
;       for (int ks = 0; ks < 12; ++ks) {
;         const bf16x8 a0 = *(const bf16x8*)(cK + l31 * KLD + ks * 16 + hh * 8), a1 = *(const bf16x8*)(cK + (32 + l31) * KLD + ks * 16 + hh * 8);
;         S[0] = MFMA32(a0, qf[ks], S[0]); S[1] = MFMA32(a1, qf[ks], S[1]);
;       }
;       __builtin_amdgcn_s_setprio(0);
;     }
;     { const bf16_t* vp_ = vtb + (size_t)(tid >> 3) * 8192 + jt * 64 + (tid & 7) * 8; vr0 = *(const uint4*)(vp_ + (size_t)0 * 8192); vr1 = *(const uint4*)(vp_ + (size_t)32 * 8192); vr2 = *(const uint4*)(vp_ + (size_t)64 * 8192); vr3 = *(const uint4*)(vp_ + (size_t)96 * 8192); }
.Lpvtop_skip_0:
	s_or_b64 exec, exec, s[100:101]
	v_lshl_add_u64 v[180:181], s[10:11], 1, v[198:199]
	v_add_co_u32_e32 v176, vcc, s78, v180
	s_nop 1
	v_addc_co_u32_e32 v177, vcc, 0, v181, vcc
	v_add_co_u32_e32 v182, vcc, 0x100000, v180
	global_load_dwordx4 v[172:175], v[180:181], off
	s_nop 0
	global_load_dwordx4 v[176:179], v[176:177], off
	v_addc_co_u32_e32 v183, vcc, 0, v181, vcc
	v_add_co_u32_e32 v180, vcc, 0x180000, v180
	s_nop 1
	v_addc_co_u32_e32 v181, vcc, 0, v181, vcc
	global_load_dwordx4 v[184:187], v[182:183], off
	s_nop 0
	global_load_dwordx4 v[180:183], v[180:181], off
	s_and_saveexec_b64 s[16:17], s[2:3]
	s_cbranch_execz .LBB0_490
	s_and_b64 s[22:23], s[14:15], exec
	v_xor_b32_e32 v20, 0x80000000, v200
	s_cselect_b32 s22, s9, s28
	s_setprio 1
	v_add3_u32 v243, s22, v197, v201
	ds_read_b128 v[244:247], v243
	ds_read_b128 v[248:251], v243 offset:12800
	ds_read_b128 v[252:255], v243 offset:32
	ds_read_b128 v[226:229], v243 offset:12832
	ds_read_b128 v[230:233], v243 offset:64
	v_mov_b32_e32 v21, v20
	v_mov_b32_e32 v22, v20
	v_mov_b32_e32 v23, v20
	v_mov_b32_e32 v24, v20
	v_mov_b32_e32 v25, v20
	v_mov_b32_e32 v26, v20
	v_mov_b32_e32 v27, v20
	v_mov_b32_e32 v28, v20
	v_mov_b32_e32 v29, v20
	v_mov_b32_e32 v30, v20
	v_mov_b32_e32 v31, v20
	v_mov_b32_e32 v32, v20
	v_mov_b32_e32 v33, v20
	v_mov_b32_e32 v34, v20
	v_mov_b32_e32 v35, v20
	s_waitcnt lgkmcnt(4)
	s_nop 0
	v_mfma_f32_32x32x16_bf16 v[36:51], v[244:247], v[100:103], v[20:35]
	ds_read_b128 v[244:247], v243 offset:12864
	s_waitcnt lgkmcnt(4)
	v_mfma_f32_32x32x16_bf16 v[20:35], v[248:251], v[100:103], v[20:35]
	ds_read_b128 v[248:251], v243 offset:96
	s_waitcnt lgkmcnt(4)
	v_mfma_f32_32x32x16_bf16 v[36:51], v[252:255], v[104:107], v[36:51]
	ds_read_b128 v[252:255], v243 offset:12896
	s_waitcnt lgkmcnt(4)
	v_mfma_f32_32x32x16_bf16 v[20:35], v[226:229], v[104:107], v[20:35]
	ds_read_b128 v[226:229], v243 offset:128
	s_waitcnt lgkmcnt(4)
	v_mfma_f32_32x32x16_bf16 v[36:51], v[230:233], v[108:111], v[36:51]
	ds_read_b128 v[230:233], v243 offset:12928
	s_waitcnt lgkmcnt(4)
	v_mfma_f32_32x32x16_bf16 v[20:35], v[244:247], v[108:111], v[20:35]
	ds_read_b128 v[244:247], v243 offset:160
	s_waitcnt lgkmcnt(4)
	v_mfma_f32_32x32x16_bf16 v[36:51], v[248:251], v[112:115], v[36:51]
	ds_read_b128 v[248:251], v243 offset:12960
	s_waitcnt lgkmcnt(4)
	v_mfma_f32_32x32x16_bf16 v[20:35], v[252:255], v[112:115], v[20:35]
	ds_read_b128 v[252:255], v243 offset:192
	s_waitcnt lgkmcnt(4)
	v_mfma_f32_32x32x16_bf16 v[36:51], v[226:229], v[116:119], v[36:51]
	ds_read_b128 v[226:229], v243 offset:12992
	s_waitcnt lgkmcnt(4)
	v_mfma_f32_32x32x16_bf16 v[20:35], v[230:233], v[116:119], v[20:35]
	ds_read_b128 v[230:233], v243 offset:224
	s_waitcnt lgkmcnt(4)
	v_mfma_f32_32x32x16_bf16 v[36:51], v[244:247], v[120:123], v[36:51]
	ds_read_b128 v[244:247], v243 offset:13024
	s_waitcnt lgkmcnt(4)
	v_mfma_f32_32x32x16_bf16 v[20:35], v[248:251], v[120:123], v[20:35]
	ds_read_b128 v[248:251], v243 offset:256
	s_waitcnt lgkmcnt(4)
	v_mfma_f32_32x32x16_bf16 v[36:51], v[252:255], v[124:127], v[36:51]
	ds_read_b128 v[252:255], v243 offset:13056
	s_waitcnt lgkmcnt(4)
	v_mfma_f32_32x32x16_bf16 v[20:35], v[226:229], v[124:127], v[20:35]
	ds_read_b128 v[226:229], v243 offset:288
	s_waitcnt lgkmcnt(4)
	v_mfma_f32_32x32x16_bf16 v[36:51], v[230:233], v[128:131], v[36:51]
	ds_read_b128 v[230:233], v243 offset:13088
	s_waitcnt lgkmcnt(4)
	v_mfma_f32_32x32x16_bf16 v[20:35], v[244:247], v[128:131], v[20:35]
	ds_read_b128 v[244:247], v243 offset:320
	s_waitcnt lgkmcnt(4)
	v_mfma_f32_32x32x16_bf16 v[36:51], v[248:251], v[132:135], v[36:51]
	ds_read_b128 v[248:251], v243 offset:13120
	s_waitcnt lgkmcnt(4)
	v_mfma_f32_32x32x16_bf16 v[20:35], v[252:255], v[132:135], v[20:35]
	ds_read_b128 v[252:255], v243 offset:352
	s_waitcnt lgkmcnt(4)
	v_mfma_f32_32x32x16_bf16 v[36:51], v[226:229], v[136:139], v[36:51]
	ds_read_b128 v[226:229], v243 offset:13152
	s_waitcnt lgkmcnt(4)
	v_mfma_f32_32x32x16_bf16 v[20:35], v[230:233], v[136:139], v[20:35]
	s_waitcnt lgkmcnt(3)
	v_mfma_f32_32x32x16_bf16 v[36:51], v[244:247], v[140:143], v[36:51]
	s_waitcnt lgkmcnt(2)
	v_mfma_f32_32x32x16_bf16 v[20:35], v[248:251], v[140:143], v[20:35]
	s_waitcnt lgkmcnt(1)
	v_mfma_f32_32x32x16_bf16 v[36:51], v[252:255], v[144:147], v[36:51]
	s_waitcnt lgkmcnt(0)
	v_mfma_f32_32x32x16_bf16 v[20:35], v[226:229], v[144:147], v[20:35]
	s_nop 11
	s_setprio 0
; DI int crow(int i, int h) { return (i & 3) + 8 * (i >> 2) + 4 * h; }
; DI void attn_unit(unsigned char* smem, const Params& P, int bh, int qb) {
;     ...
;     { const bf16_t* vp_ = vtb + (size_t)(tid >> 3) * 8192 + jt * 64 + (tid & 7) * 8; vr0 = *(const uint4*)(vp_ + (size_t)0 * 8192); vr1 = *(const uint4*)(vp_ + (size_t)32 * 8192); vr2 = *(const uint4*)(vp_ + (size_t)64 * 8192); vr3 = *(const uint4*)(vp_ + (size_t)96 * 8192); }
;     __builtin_amdgcn_sched_barrier(0);
;     if (active) {
;       if (jt >= ntiles - 2) {
; #pragma unroll
;         for (int kt = 0; kt < 2; ++kt)
; #pragma unroll
;           for (int i = 0; i < 16; ++i) { const int key = jt * 64 + kt * 32 + crow(i, hh); if (key > qrow) S[kt][i] = -1e30f; }
;       }
.LBB0_490:
	s_or_b64 exec, exec, s[16:17]
	s_barrier
	s_and_saveexec_b64 s[16:17], s[2:3]
	s_cbranch_execz .LBB0_496
	s_cmp_lt_u32 s21, s8
	s_cbranch_scc1 .LBB0_493
	v_add_u32_e32 v225, s20, v219
	v_add_u32_e32 v226, 64, v225
	v_cmp_le_i32_e32 vcc, v226, v188
	s_nop 1
	v_cndmask_b32_e32 v36, v213, v36, vcc
	v_cmp_lt_i32_e32 vcc, v226, v188
	v_add_u32_e32 v226, 0x42, v225
	s_nop 0
	v_cndmask_b32_e32 v37, v213, v37, vcc
	v_cmp_le_i32_e32 vcc, v226, v188
	v_add_u32_e32 v226, 0x43, v225
	s_nop 0
	v_cndmask_b32_e32 v38, v213, v38, vcc
	v_cmp_le_i32_e32 vcc, v226, v188
	v_add_u32_e32 v226, 0x48, v225
	s_nop 0
	v_cndmask_b32_e32 v39, v213, v39, vcc
	v_cmp_le_i32_e32 vcc, v226, v188
	v_add_u32_e32 v226, 0x49, v225
	s_nop 0
	v_cndmask_b32_e32 v40, v213, v40, vcc
	v_cmp_le_i32_e32 vcc, v226, v188
	v_add_u32_e32 v226, 0x4a, v225
	s_nop 0
	v_cndmask_b32_e32 v41, v213, v41, vcc
	v_cmp_le_i32_e32 vcc, v226, v188
	v_add_u32_e32 v226, 0x4b, v225
	s_nop 0
	v_cndmask_b32_e32 v42, v213, v42, vcc
	v_cmp_le_i32_e32 vcc, v226, v188
	v_add_u32_e32 v226, 0x50, v225
	s_nop 0
	v_cndmask_b32_e32 v43, v213, v43, vcc
	v_cmp_le_i32_e32 vcc, v226, v188
	v_add_u32_e32 v226, 0x51, v225
	s_nop 0
	v_cndmask_b32_e32 v44, v213, v44, vcc
	v_cmp_le_i32_e32 vcc, v226, v188
	v_add_u32_e32 v226, 0x52, v225
	s_nop 0
	v_cndmask_b32_e32 v45, v213, v45, vcc
	v_cmp_le_i32_e32 vcc, v226, v188
	v_add_u32_e32 v226, 0x53, v225
	s_nop 0
	v_cndmask_b32_e32 v46, v213, v46, vcc
	v_cmp_le_i32_e32 vcc, v226, v188
	v_add_u32_e32 v226, 0x58, v225
	s_nop 0
	v_cndmask_b32_e32 v47, v213, v47, vcc
	v_cmp_le_i32_e32 vcc, v226, v188
	v_add_u32_e32 v226, 0x59, v225
	s_nop 0
	v_cndmask_b32_e32 v48, v213, v48, vcc
	v_cmp_le_i32_e32 vcc, v226, v188
	v_add_u32_e32 v226, 0x5a, v225
	s_nop 0
	v_cndmask_b32_e32 v49, v213, v49, vcc
	v_cmp_le_i32_e32 vcc, v226, v188
	v_add_u32_e32 v226, 0x5b, v225
	s_nop 0
	v_cndmask_b32_e32 v50, v213, v50, vcc
	v_cmp_le_i32_e32 vcc, v226, v188
	v_add_u32_e32 v226, 0x60, v225
	s_nop 0
	v_cndmask_b32_e32 v51, v213, v51, vcc
	v_cmp_le_i32_e32 vcc, v226, v188
	v_add_u32_e32 v226, 0x61, v225
	s_nop 0
	v_cndmask_b32_e32 v20, v213, v20, vcc
	v_cmp_le_i32_e32 vcc, v226, v188
	v_add_u32_e32 v226, 0x62, v225
	s_nop 0
	v_cndmask_b32_e32 v21, v213, v21, vcc
	v_cmp_le_i32_e32 vcc, v226, v188
	v_add_u32_e32 v226, 0x63, v225
	s_nop 0
	v_cndmask_b32_e32 v22, v213, v22, vcc
	v_cmp_le_i32_e32 vcc, v226, v188
	v_add_u32_e32 v226, 0x68, v225
	s_nop 0
	v_cndmask_b32_e32 v23, v213, v23, vcc
	v_cmp_le_i32_e32 vcc, v226, v188
	v_add_u32_e32 v226, 0x69, v225
	s_nop 0
	v_cndmask_b32_e32 v24, v213, v24, vcc
	v_cmp_le_i32_e32 vcc, v226, v188
	v_add_u32_e32 v226, 0x6a, v225
	s_nop 0
	v_cndmask_b32_e32 v25, v213, v25, vcc
	v_cmp_le_i32_e32 vcc, v226, v188
	v_add_u32_e32 v226, 0x6b, v225
	s_nop 0
	v_cndmask_b32_e32 v26, v213, v26, vcc
	v_cmp_le_i32_e32 vcc, v226, v188
	v_add_u32_e32 v226, 0x70, v225
	s_nop 0
	v_cndmask_b32_e32 v27, v213, v27, vcc
	v_cmp_le_i32_e32 vcc, v226, v188
	v_add_u32_e32 v226, 0x71, v225
	s_nop 0
	v_cndmask_b32_e32 v28, v213, v28, vcc
	v_cmp_le_i32_e32 vcc, v226, v188
	v_add_u32_e32 v226, 0x72, v225
	s_nop 0
	v_cndmask_b32_e32 v29, v213, v29, vcc
	v_cmp_le_i32_e32 vcc, v226, v188
	v_add_u32_e32 v226, 0x73, v225
	s_nop 0
	v_cndmask_b32_e32 v30, v213, v30, vcc
	v_cmp_le_i32_e32 vcc, v226, v188
	v_add_u32_e32 v226, 0x78, v225
	s_nop 0
	v_cndmask_b32_e32 v31, v213, v31, vcc
	v_cmp_le_i32_e32 vcc, v226, v188
	v_add_u32_e32 v226, 0x79, v225
	s_nop 0
	v_cndmask_b32_e32 v32, v213, v32, vcc
	v_cmp_le_i32_e32 vcc, v226, v188
	v_add_u32_e32 v226, 0x7a, v225
	v_add_u32_e32 v225, 0x7b, v225
	v_cndmask_b32_e32 v33, v213, v33, vcc
	v_cmp_le_i32_e32 vcc, v226, v188
	s_nop 1
	v_cndmask_b32_e32 v34, v213, v34, vcc
	v_cmp_le_i32_e32 vcc, v225, v188
	s_nop 1
	v_cndmask_b32_e32 v35, v213, v35, vcc

; #define MFMA32(a, b, c) __builtin_amdgcn_mfma_f32_32x32x16_bf16((a), (b), (c), 0, 0, 0)
; DI void attn_unit(unsigned char* smem, const Params& P, int bh, int qb) {
;     ...
;     __syncthreads();
;     if (active) {
;       __builtin_amdgcn_s_setprio(1);
; #pragma unroll
;       for (int kt = 0; kt < 2; ++kt)
; #pragma unroll
;         for (int s2 = 0; s2 < 2; ++s2) {
;           uint4 pp; pp.x = pk2(S[kt][8 * s2], S[kt][8 * s2 + 1]); pp.y = pk2(S[kt][8 * s2 + 2], S[kt][8 * s2 + 3]);
;           pp.z = pk2(S[kt][8 * s2 + 4], S[kt][8 * s2 + 5]); pp.w = pk2(S[kt][8 * s2 + 6], S[kt][8 * s2 + 7]);
;           const bf16x8 pb = __builtin_bit_cast(bf16x8, pp);
; #pragma unroll
;           for (int d = 0; d < 4; ++d) {
;             const bf16x8 vf = *(const bf16x8*)(sV + (d * 32 + l31) * LDK + kt * 32 + s2 * 16 + hh * 8);
;             O[d] = MFMA32(vf, pb, O[d]);
;           }
;         }
;       __builtin_amdgcn_s_setprio(0);
;     }
;     __syncthreads();
;   }
;   const float ltot = lrun + __shfl_xor(lrun, 32), inv = 1.0f / ltot;
; #pragma unroll
;   for (int d = 0; d < 4; ++d)
; #pragma unroll
;     for (int g4 = 0; g4 < 4; ++g4) {
;       const int dv = d * 32 + 8 * g4 + 4 * hh;
;       uint2 pk; pk.x = pk2(O[d][4 * g4] * inv, O[d][4 * g4 + 1] * inv); pk.y = pk2(O[d][4 * g4 + 2] * inv, O[d][4 * g4 + 3] * inv);
;       *(uint2*)(obuf + (size_t)qrow * 1024 + dv) = pk;
;     }
.LBB0_498:
	s_waitcnt lgkmcnt(0)
	s_barrier
	s_add_i32 s19, s19, 1
	s_cmp_lg_u32 s18, s19
	v_lshl_add_u64 v[202:203], v[202:203], 0, s[40:41]
	s_cbranch_scc0 .LBB0_502
	s_mov_b32 s20, s10
	s_branch .LBB0_486
.LBB0_502:
	s_and_saveexec_b64 s[100:101], s[2:3]
	s_cbranch_execz .Lpvexit_skip_0
	s_setprio 1
	ds_read_b128 v[180:183], v221 offset:25600
	ds_read_b128 v[184:187], v222 offset:25600
	ds_read_b128 v[226:229], v223 offset:25600
	ds_read_b128 v[230:233], v224 offset:25600
	ds_read_b128 v[244:247], v221 offset:25632
	ds_read_b128 v[248:251], v222 offset:25632
	ds_read_b128 v[252:255], v223 offset:25632
	v_cvt_pk_bf16_f32 v176, v36, v37
	v_cvt_pk_bf16_f32 v177, v38, v39
	v_cvt_pk_bf16_f32 v178, v40, v41
	v_cvt_pk_bf16_f32 v179, v42, v43
	v_cvt_pk_bf16_f32 v172, v44, v45
	v_cvt_pk_bf16_f32 v173, v46, v47
	v_cvt_pk_bf16_f32 v174, v48, v49
	v_cvt_pk_bf16_f32 v175, v50, v51
	s_waitcnt lgkmcnt(6)
	v_mfma_f32_32x32x16_bf16 v[84:99], v[180:183], v[176:179], v[84:99]
	ds_read_b128 v[180:183], v224 offset:25632
	s_waitcnt lgkmcnt(6)
	v_mfma_f32_32x32x16_bf16 v[68:83], v[184:187], v[176:179], v[68:83]
	ds_read_b128 v[184:187], v221 offset:25664
	s_waitcnt lgkmcnt(6)
	v_mfma_f32_32x32x16_bf16 v[52:67], v[226:229], v[176:179], v[52:67]
	ds_read_b128 v[226:229], v222 offset:25664
	s_waitcnt lgkmcnt(6)
	v_mfma_f32_32x32x16_bf16 v[4:19], v[230:233], v[176:179], v[4:19]
	ds_read_b128 v[230:233], v223 offset:25664
	s_waitcnt lgkmcnt(6)
	v_mfma_f32_32x32x16_bf16 v[84:99], v[244:247], v[172:175], v[84:99]
	ds_read_b128 v[244:247], v224 offset:25664
	v_cvt_pk_bf16_f32 v176, v20, v21
	v_cvt_pk_bf16_f32 v177, v22, v23
	v_cvt_pk_bf16_f32 v178, v24, v25
	v_cvt_pk_bf16_f32 v179, v26, v27
	s_waitcnt lgkmcnt(6)
	v_mfma_f32_32x32x16_bf16 v[68:83], v[248:251], v[172:175], v[68:83]
	ds_read_b128 v[248:251], v221 offset:25696
	s_waitcnt lgkmcnt(6)
	v_mfma_f32_32x32x16_bf16 v[52:67], v[252:255], v[172:175], v[52:67]
	ds_read_b128 v[252:255], v222 offset:25696
	s_waitcnt lgkmcnt(6)
	v_mfma_f32_32x32x16_bf16 v[4:19], v[180:183], v[172:175], v[4:19]
	ds_read_b128 v[180:183], v223 offset:25696
	s_waitcnt lgkmcnt(6)
	v_mfma_f32_32x32x16_bf16 v[84:99], v[184:187], v[176:179], v[84:99]
	ds_read_b128 v[184:187], v224 offset:25696
	v_cvt_pk_bf16_f32 v172, v28, v29
	v_cvt_pk_bf16_f32 v173, v30, v31
	v_cvt_pk_bf16_f32 v174, v32, v33
	v_cvt_pk_bf16_f32 v175, v34, v35
	s_waitcnt lgkmcnt(6)
	v_mfma_f32_32x32x16_bf16 v[68:83], v[226:229], v[176:179], v[68:83]
	s_waitcnt lgkmcnt(5)
	v_mfma_f32_32x32x16_bf16 v[52:67], v[230:233], v[176:179], v[52:67]
	s_waitcnt lgkmcnt(4)
	v_mfma_f32_32x32x16_bf16 v[4:19], v[244:247], v[176:179], v[4:19]
	s_waitcnt lgkmcnt(3)
	v_mfma_f32_32x32x16_bf16 v[84:99], v[248:251], v[172:175], v[84:99]
	s_waitcnt lgkmcnt(2)
	v_mfma_f32_32x32x16_bf16 v[68:83], v[252:255], v[172:175], v[68:83]
	s_waitcnt lgkmcnt(1)
	v_mfma_f32_32x32x16_bf16 v[52:67], v[180:183], v[172:175], v[52:67]
	s_waitcnt lgkmcnt(0)
	v_mfma_f32_32x32x16_bf16 v[4:19], v[184:187], v[172:175], v[4:19]
	s_setprio 0
	s_nop 7
	s_nop 7
.Lpvexit_skip_0:
	s_or_b64 exec, exec, s[100:101]
	v_and_b32_e32 v20, 64, v214
	v_xor_b32_e32 v2, 32, v214
	v_add_u32_e32 v20, 64, v20
	v_cmp_lt_i32_e32 vcc, v2, v20
	s_lshl_b32 s0, s97, 22
	s_and_b32 s0, s0, 0x3000000
	v_cndmask_b32_e32 v2, v214, v2, vcc
	v_lshlrev_b32_e32 v203, 2, v2
	ds_bpermute_b32 v2, v203, v215
	s_add_u32 s2, s63, s0
	s_addc_u32 s3, s64, 0
	s_lshl_b32 s8, s97, 8
	s_waitcnt lgkmcnt(0)
	v_add_f32_e32 v2, v215, v2
	v_div_scale_f32 v20, s[0:1], v2, v2, 1.0
	v_rcp_f32_e32 v21, v20
	s_and_b32 s0, s8, 0x300
	s_add_u32 s0, s2, s0
	s_addc_u32 s1, s3, 0
	v_fma_f32 v22, -v20, v21, 1.0
	v_fmac_f32_e32 v21, v22, v21
	v_div_scale_f32 v22, vcc, 1.0, v2, 1.0
	v_mul_f32_e32 v23, v22, v21
	v_fma_f32 v24, -v20, v23, v22
	v_fmac_f32_e32 v23, v24, v21
	v_fma_f32 v20, -v20, v23, v22
	v_div_fmas_f32 v20, v20, v21, v23
	v_div_fixup_f32 v24, v20, v2, 1.0
	v_lshlrev_b64 v[20:21], 11, v[188:189]
	v_lshl_add_u64 v[20:21], s[0:1], 0, v[20:21]
	v_mul_f32_e32 v22, v84, v24
	v_mul_f32_e32 v25, v85, v24
	v_mul_f32_e32 v23, v86, v24
	v_mul_f32_e32 v26, v87, v24
	v_lshlrev_b32_e32 v2, 1, v219
	v_lshl_add_u64 v[20:21], v[20:21], 0, v[2:3]
	v_cvt_pk_bf16_f32 v23, v23, v26
	v_cvt_pk_bf16_f32 v22, v22, v25
	global_store_dwordx2 v[20:21], v[22:23], off
	v_mul_f32_e32 v2, v88, v24
	v_mul_f32_e32 v22, v89, v24
	v_mul_f32_e32 v23, v90, v24
	v_mul_f32_e32 v25, v91, v24
	v_cvt_pk_bf16_f32 v23, v23, v25
	v_cvt_pk_bf16_f32 v22, v2, v22
	global_store_dwordx2 v[20:21], v[22:23], off offset:16
	v_mul_f32_e32 v2, v92, v24
	v_mul_f32_e32 v22, v93, v24
	v_mul_f32_e32 v23, v94, v24
	v_mul_f32_e32 v25, v95, v24
	v_cvt_pk_bf16_f32 v23, v23, v25
	v_cvt_pk_bf16_f32 v22, v2, v22
	global_store_dwordx2 v[20:21], v[22:23], off offset:32
	v_mul_f32_e32 v2, v96, v24
	v_mul_f32_e32 v22, v97, v24
	v_mul_f32_e32 v23, v98, v24
	v_mul_f32_e32 v25, v99, v24
	v_cvt_pk_bf16_f32 v23, v23, v25
	v_cvt_pk_bf16_f32 v22, v2, v22
	global_store_dwordx2 v[20:21], v[22:23], off offset:48
	v_mul_f32_e32 v2, v68, v24
	v_mul_f32_e32 v22, v69, v24
	v_mul_f32_e32 v23, v70, v24
	v_mul_f32_e32 v25, v71, v24
	v_cvt_pk_bf16_f32 v23, v23, v25
	v_cvt_pk_bf16_f32 v22, v2, v22
	global_store_dwordx2 v[20:21], v[22:23], off offset:64
	v_mul_f32_e32 v2, v72, v24
	v_mul_f32_e32 v22, v73, v24
	v_mul_f32_e32 v23, v74, v24
	v_mul_f32_e32 v25, v75, v24
	v_cvt_pk_bf16_f32 v23, v23, v25
	v_cvt_pk_bf16_f32 v22, v2, v22
	global_store_dwordx2 v[20:21], v[22:23], off offset:80
	v_mul_f32_e32 v2, v76, v24
	v_mul_f32_e32 v22, v77, v24
	v_mul_f32_e32 v23, v78, v24
	v_mul_f32_e32 v25, v79, v24
	v_cvt_pk_bf16_f32 v23, v23, v25
	v_cvt_pk_bf16_f32 v22, v2, v22
; DI int TID() { int t = threadIdx.x & 255; asm volatile("" : "+v"(t)); return t; }
; DI void attn_unit(unsigned char* smem, const Params& P, int bh, int qb) {
;   const int tid = TID(), lane = tid & 63, w = tid >> 6, l31 = lane & 31, hh = lane >> 5;
;   bf16_t* sK = (bf16_t*)smem;
;   bf16_t* sV = sK + 64 * KLD;
;   const bf16_t* qbuf = (const bf16_t*)(P.ws + OFF_Q) + (size_t)bh * 8192 * 192;
;   bf16_t* obuf = (bf16_t*)(P.ws + OFF_MIX) + ((size_t)(bh >> 2) * 8192) * 1024 + (bh & 3) * 128;
;   const bf16_t* kbuf = (const bf16_t*)(P.ws + OFF_K) + (size_t)bh * 8192 * 192;
;   const bf16_t* vtb = (const bf16_t*)(P.ws + OFF_VT) + (size_t)bh * 128 * 8192;
;   const int q0 = qb * 128, qrow = q0 + 32 * w + l31;
;   bf16x8 qf[12];
; #pragma unroll
;   for (int ks = 0; ks < 12; ++ks) qf[ks] = *(const bf16x8*)(qbuf + (size_t)qrow * 192 + ks * 16 + hh * 8);
;   f32x16 O[4];
; #pragma unroll
;   for (int d = 0; d < 4; ++d)
; #pragma unroll
;     for (int i = 0; i < 16; ++i) O[d][i] = 0.f;
;   float mrun = -1e30f, lrun = 0.f;
;   const int ntiles = 2 * qb + 2;
;   bf16_t* sK1 = sV + 128 * LDK;
;   uint4 kr0, kr1, kr2, kr3, kr4, kr5, vr0, vr1, vr2, vr3;
;   const int kgo = (tid >> 2) * 192 + (tid & 3) * 8, klo = (tid >> 2) * KLD + (tid & 3) * 8;
;   __syncthreads();
;   kr0 = *(const uint4*)(kbuf + kgo + 0); kr1 = *(const uint4*)(kbuf + kgo + 32); kr2 = *(const uint4*)(kbuf + kgo + 64); kr3 = *(const uint4*)(kbuf + kgo + 96); kr4 = *(const uint4*)(kbuf + kgo + 128); kr5 = *(const uint4*)(kbuf + kgo + 160);
;   *(uint4*)(sK + klo + 0) = kr0; *(uint4*)(sK + klo + 32) = kr1; *(uint4*)(sK + klo + 64) = kr2; *(uint4*)(sK + klo + 96) = kr3; *(uint4*)(sK + klo + 128) = kr4; *(uint4*)(sK + klo + 160) = kr5;
;   __syncthreads();
;     ...
;   const float ltot = lrun + __shfl_xor(lrun, 32), inv = 1.0f / ltot;
; #pragma unroll
;   for (int d = 0; d < 4; ++d)
; #pragma unroll
;     for (int g4 = 0; g4 < 4; ++g4) {
;       const int dv = d * 32 + 8 * g4 + 4 * hh;
;       uint2 pk; pk.x = pk2(O[d][4 * g4] * inv, O[d][4 * g4 + 1] * inv); pk.y = pk2(O[d][4 * g4 + 2] * inv, O[d][4 * g4 + 3] * inv);
;       *(uint2*)(obuf + (size_t)qrow * 1024 + dv) = pk;
;     }
	global_store_dwordx2 v[20:21], v[22:23], off offset:96
	v_mul_f32_e32 v2, v80, v24
	v_mul_f32_e32 v22, v81, v24
	v_mul_f32_e32 v23, v82, v24
	v_mul_f32_e32 v25, v83, v24
	v_cvt_pk_bf16_f32 v23, v23, v25
	v_cvt_pk_bf16_f32 v22, v2, v22
	global_store_dwordx2 v[20:21], v[22:23], off offset:112
	v_mul_f32_e32 v2, v52, v24
	v_mul_f32_e32 v22, v53, v24
	v_mul_f32_e32 v23, v54, v24
	v_mul_f32_e32 v25, v55, v24
	v_cvt_pk_bf16_f32 v23, v23, v25
	v_cvt_pk_bf16_f32 v22, v2, v22
	global_store_dwordx2 v[20:21], v[22:23], off offset:128
	v_mul_f32_e32 v2, v56, v24
	v_mul_f32_e32 v22, v57, v24
	v_mul_f32_e32 v23, v58, v24
	v_mul_f32_e32 v25, v59, v24
	v_cvt_pk_bf16_f32 v23, v23, v25
	v_cvt_pk_bf16_f32 v22, v2, v22
	global_store_dwordx2 v[20:21], v[22:23], off offset:144
	v_mul_f32_e32 v2, v60, v24
	v_mul_f32_e32 v22, v61, v24
	v_mul_f32_e32 v23, v62, v24
	v_mul_f32_e32 v25, v63, v24
	v_cvt_pk_bf16_f32 v23, v23, v25
	v_cvt_pk_bf16_f32 v22, v2, v22
	global_store_dwordx2 v[20:21], v[22:23], off offset:160
	v_mul_f32_e32 v2, v64, v24
	v_mul_f32_e32 v22, v65, v24
	v_cvt_pk_bf16_f32 v22, v2, v22
	v_mul_f32_e32 v2, v4, v24
	v_mul_f32_e32 v4, v5, v24
	v_mul_f32_e32 v5, v6, v24
	v_mul_f32_e32 v6, v7, v24
	v_cvt_pk_bf16_f32 v5, v5, v6
	v_cvt_pk_bf16_f32 v4, v2, v4
	global_store_dwordx2 v[20:21], v[4:5], off offset:192
	v_mul_f32_e32 v2, v8, v24
	v_mul_f32_e32 v4, v9, v24
	v_mul_f32_e32 v5, v10, v24
	v_mul_f32_e32 v6, v11, v24
	v_cvt_pk_bf16_f32 v5, v5, v6
	v_cvt_pk_bf16_f32 v4, v2, v4
	global_store_dwordx2 v[20:21], v[4:5], off offset:208
	v_mul_f32_e32 v2, v12, v24
	v_mul_f32_e32 v4, v13, v24
	v_mul_f32_e32 v5, v14, v24
	v_mul_f32_e32 v6, v15, v24
	v_cvt_pk_bf16_f32 v5, v5, v6
	v_cvt_pk_bf16_f32 v4, v2, v4
	global_store_dwordx2 v[20:21], v[4:5], off offset:224
	v_mul_f32_e32 v2, v16, v24
	v_mul_f32_e32 v4, v17, v24
	v_mul_f32_e32 v5, v18, v24
	v_mul_f32_e32 v6, v19, v24
	v_mul_f32_e32 v23, v66, v24
	v_mul_f32_e32 v25, v67, v24
	v_cvt_pk_bf16_f32 v5, v5, v6
	v_cvt_pk_bf16_f32 v4, v2, v4
	v_cvt_pk_bf16_f32 v23, v23, v25
	global_store_dwordx2 v[20:21], v[4:5], off offset:240
	v_mov_b32_e32 v5, v1
	global_store_dwordx2 v[20:21], v[22:23], off offset:176
	v_mov_b64_e32 v[6:7], s[56:57]
	v_ashrrev_i32_e32 v2, 1, v5
	v_and_b32_e32 v2, 0xffffffe0, v2
	v_and_b32_e32 v189, 31, v5
	v_lshl_add_u32 v188, s92, 7, v2
	v_bfe_u32 v4, v5, 5, 1
	v_or_b32_e32 v196, v188, v189
	v_mad_i64_i32 v[6:7], s[2:3], v196, s75, v[6:7]
	v_lshlrev_b32_e32 v2, 4, v4
	v_lshl_add_u64 v[6:7], v[6:7], 0, v[2:3]
	v_ashrrev_i32_e32 v32, 2, v5
	v_lshlrev_b32_e32 v84, 3, v5
	global_load_dwordx4 v[114:117], v[6:7], off
	global_load_dwordx4 v[118:121], v[6:7], off offset:32
	global_load_dwordx4 v[122:125], v[6:7], off offset:64
	global_load_dwordx4 v[126:129], v[6:7], off offset:96
	global_load_dwordx4 v[130:133], v[6:7], off offset:128
	global_load_dwordx4 v[134:137], v[6:7], off offset:160
	global_load_dwordx4 v[138:141], v[6:7], off offset:192
	global_load_dwordx4 v[142:145], v[6:7], off offset:224
	global_load_dwordx4 v[146:149], v[6:7], off offset:256
	global_load_dwordx4 v[150:153], v[6:7], off offset:288
	global_load_dwordx4 v[154:157], v[6:7], off offset:320
	global_load_dwordx4 v[158:161], v[6:7], off offset:352
	v_mul_lo_u32 v6, v32, s76
	v_and_b32_e32 v2, 24, v84
	v_or_b32_e32 v186, v6, v2
	v_ashrrev_i32_e32 v187, 31, v186
	v_lshl_add_u64 v[30:31], v[186:187], 1, s[50:51]
	s_barrier
	global_load_dwordx4 v[6:9], v[30:31], off
	global_load_dwordx4 v[10:13], v[30:31], off offset:64
	global_load_dwordx4 v[14:17], v[30:31], off offset:128
	global_load_dwordx4 v[18:21], v[30:31], off offset:192
	global_load_dwordx4 v[22:25], v[30:31], off offset:256
	global_load_dwordx4 v[26:29], v[30:31], off offset:320
	v_mad_u64_u32 v[198:199], s[2:3], v32, s77, v[2:3]
	v_lshl_add_u32 v85, v198, 1, s9
	s_waitcnt vmcnt(5)
	ds_write_b128 v85, v[6:9]
	s_waitcnt vmcnt(4)
	ds_write_b128 v85, v[10:13] offset:64
	s_waitcnt vmcnt(3)
	ds_write_b128 v85, v[14:17] offset:128
	s_waitcnt vmcnt(2)
	ds_write_b128 v85, v[18:21] offset:192
	s_waitcnt vmcnt(1)
	ds_write_b128 v85, v[22:25] offset:256
	s_waitcnt vmcnt(0)
	ds_write_b128 v85, v[26:29] offset:320
	v_add_co_u32_e32 v6, vcc, 0x6000, v30
	s_waitcnt lgkmcnt(0)
	s_nop 0
	v_addc_co_u32_e32 v7, vcc, 0, v31, vcc
	s_barrier
	global_load_dwordx4 v[162:165], v[6:7], off
	global_load_dwordx4 v[166:169], v[6:7], off offset:64
	global_load_dwordx4 v[170:173], v[6:7], off offset:128
	global_load_dwordx4 v[174:177], v[6:7], off offset:192
	global_load_dwordx4 v[178:181], v[6:7], off offset:256
	global_load_dwordx4 v[182:185], v[6:7], off offset:320
	v_lshlrev_b32_e32 v86, 3, v4
	v_cmp_lt_i32_e64 s[2:3], -1, v188
	v_mul_u32_u24_e32 v2, 0xc8, v189
	v_mov_b32_e32 v217, 0
	v_lshlrev_b32_e32 v199, 1, v2
	v_lshlrev_b32_e32 v215, 1, v86
	v_mov_b32_e32 v34, 0
	v_mov_b32_e32 v35, 0
	v_mov_b32_e32 v36, 0
	v_mov_b32_e32 v37, 0
	v_mov_b32_e32 v38, 0
	v_mov_b32_e32 v39, 0
	v_mov_b32_e32 v40, 0
	v_mov_b32_e32 v41, 0
	v_mov_b32_e32 v42, 0
	v_mov_b32_e32 v43, 0
	v_mov_b32_e32 v44, 0
	v_mov_b32_e32 v45, 0
	v_mov_b32_e32 v46, 0
	v_mov_b32_e32 v47, 0
	v_mov_b32_e32 v48, 0
	v_mov_b32_e32 v49, 0
	v_mov_b32_e32 v18, 0
	v_mov_b32_e32 v19, 0
	v_mov_b32_e32 v20, 0
	v_mov_b32_e32 v21, 0
	v_mov_b32_e32 v22, 0
	v_mov_b32_e32 v23, 0
	v_mov_b32_e32 v24, 0
	v_mov_b32_e32 v25, 0
	v_mov_b32_e32 v26, 0
	v_mov_b32_e32 v27, 0
	v_mov_b32_e32 v28, 0
	v_mov_b32_e32 v29, 0
	v_mov_b32_e32 v30, 0
	v_mov_b32_e32 v31, 0
	v_mov_b32_e32 v32, 0
	v_mov_b32_e32 v33, 0
	s_and_saveexec_b64 s[50:51], s[2:3]
	s_cbranch_execz .LBB0_504
; #define MFMA32(a, b, c) __builtin_amdgcn_mfma_f32_32x32x16_bf16((a), (b), (c), 0, 0, 0)
; DI void attn_unit(unsigned char* smem, const Params& P, int bh, int qb) {
;     ...
;     if (active) {
; #pragma unroll
;       for (int a = 0; a < 2; ++a)
; #pragma unroll
;         for (int i = 0; i < 16; ++i) S[a][i] = -sref;
;       __builtin_amdgcn_s_setprio(1);
; #pragma unroll
;       for (int ks = 0; ks < 12; ++ks) {
;         const bf16x8 a0 = *(const bf16x8*)(cK + l31 * KLD + ks * 16 + hh * 8), a1 = *(const bf16x8*)(cK + (32 + l31) * KLD + ks * 16 + hh * 8);
;         S[0] = MFMA32(a0, qf[ks], S[0]); S[1] = MFMA32(a1, qf[ks], S[1]);
;       }
;       __builtin_amdgcn_s_setprio(0);
	s_setprio 1
	v_add3_u32 v2, s9, v199, v215
	ds_read_b128 v[6:9], v2
	s_mov_b32 s26, s12
	s_mov_b32 s27, s12
	s_mov_b32 s13, s12
	s_mov_b32 s14, s12
	s_mov_b32 s15, s12
	s_mov_b32 s16, s12
	s_mov_b32 s17, s12
	s_mov_b32 s18, s12
	s_mov_b32 s19, s12
	s_mov_b32 s20, s12
	s_mov_b32 s21, s12
	s_mov_b32 s22, s12
	s_mov_b32 s23, s12
	s_mov_b32 s24, s12
	s_mov_b32 s25, s12
	v_mov_b64_e32 v[32:33], s[26:27]
	v_mov_b64_e32 v[30:31], s[24:25]
	v_mov_b64_e32 v[28:29], s[22:23]
	v_mov_b64_e32 v[26:27], s[20:21]
	v_mov_b64_e32 v[24:25], s[18:19]
	v_mov_b64_e32 v[22:23], s[16:17]
	v_mov_b64_e32 v[20:21], s[14:15]
	v_mov_b64_e32 v[18:19], s[12:13]
	s_waitcnt lgkmcnt(0)
	s_nop 0
	v_mfma_f32_32x32x16_bf16 v[34:49], v[6:9], v[114:117], v[18:33]
	ds_read_b128 v[6:9], v2 offset:12800
	s_waitcnt lgkmcnt(0)
	v_mfma_f32_32x32x16_bf16 v[18:33], v[6:9], v[114:117], v[18:33]
	ds_read_b128 v[6:9], v2 offset:32
	s_waitcnt lgkmcnt(0)
	v_mfma_f32_32x32x16_bf16 v[34:49], v[6:9], v[118:121], v[34:49]
	ds_read_b128 v[6:9], v2 offset:12832
	s_waitcnt lgkmcnt(0)
	v_mfma_f32_32x32x16_bf16 v[18:33], v[6:9], v[118:121], v[18:33]
	ds_read_b128 v[6:9], v2 offset:64
	s_waitcnt lgkmcnt(0)
	v_mfma_f32_32x32x16_bf16 v[34:49], v[6:9], v[122:125], v[34:49]
	ds_read_b128 v[6:9], v2 offset:12864
	s_waitcnt lgkmcnt(0)
	v_mfma_f32_32x32x16_bf16 v[18:33], v[6:9], v[122:125], v[18:33]
	ds_read_b128 v[6:9], v2 offset:96
	s_waitcnt lgkmcnt(0)
	v_mfma_f32_32x32x16_bf16 v[34:49], v[6:9], v[126:129], v[34:49]
	ds_read_b128 v[6:9], v2 offset:12896
	s_waitcnt lgkmcnt(0)
	v_mfma_f32_32x32x16_bf16 v[18:33], v[6:9], v[126:129], v[18:33]
	ds_read_b128 v[6:9], v2 offset:128
	s_waitcnt lgkmcnt(0)
	v_mfma_f32_32x32x16_bf16 v[34:49], v[6:9], v[130:133], v[34:49]
	ds_read_b128 v[6:9], v2 offset:12928
	s_waitcnt lgkmcnt(0)
	v_mfma_f32_32x32x16_bf16 v[18:33], v[6:9], v[130:133], v[18:33]
	ds_read_b128 v[6:9], v2 offset:160
	s_waitcnt lgkmcnt(0)
	v_mfma_f32_32x32x16_bf16 v[34:49], v[6:9], v[134:137], v[34:49]
	ds_read_b128 v[6:9], v2 offset:12960
	s_waitcnt lgkmcnt(0)
	v_mfma_f32_32x32x16_bf16 v[18:33], v[6:9], v[134:137], v[18:33]
	ds_read_b128 v[6:9], v2 offset:192
	s_waitcnt lgkmcnt(0)
	v_mfma_f32_32x32x16_bf16 v[34:49], v[6:9], v[138:141], v[34:49]
	ds_read_b128 v[6:9], v2 offset:12992
	s_waitcnt lgkmcnt(0)
	v_mfma_f32_32x32x16_bf16 v[18:33], v[6:9], v[138:141], v[18:33]
	ds_read_b128 v[6:9], v2 offset:224
	s_waitcnt lgkmcnt(0)
	v_mfma_f32_32x32x16_bf16 v[34:49], v[6:9], v[142:145], v[34:49]
	ds_read_b128 v[6:9], v2 offset:13024
	s_waitcnt lgkmcnt(0)
	v_mfma_f32_32x32x16_bf16 v[18:33], v[6:9], v[142:145], v[18:33]
	ds_read_b128 v[6:9], v2 offset:256
	s_waitcnt lgkmcnt(0)
	v_mfma_f32_32x32x16_bf16 v[34:49], v[6:9], v[146:149], v[34:49]
	ds_read_b128 v[6:9], v2 offset:13056
	s_waitcnt lgkmcnt(0)
	v_mfma_f32_32x32x16_bf16 v[18:33], v[6:9], v[146:149], v[18:33]
	ds_read_b128 v[6:9], v2 offset:288
	s_waitcnt lgkmcnt(0)
	v_mfma_f32_32x32x16_bf16 v[34:49], v[6:9], v[150:153], v[34:49]
	ds_read_b128 v[6:9], v2 offset:13088
	s_waitcnt lgkmcnt(0)
	v_mfma_f32_32x32x16_bf16 v[18:33], v[6:9], v[150:153], v[18:33]
	ds_read_b128 v[6:9], v2 offset:320
	s_waitcnt lgkmcnt(0)
	v_mfma_f32_32x32x16_bf16 v[34:49], v[6:9], v[154:157], v[34:49]
	ds_read_b128 v[6:9], v2 offset:13120
	s_waitcnt lgkmcnt(0)
	v_mfma_f32_32x32x16_bf16 v[18:33], v[6:9], v[154:157], v[18:33]
	ds_read_b128 v[6:9], v2 offset:352
	s_waitcnt lgkmcnt(0)
	v_mfma_f32_32x32x16_bf16 v[34:49], v[6:9], v[158:161], v[34:49]
	ds_read_b128 v[6:9], v2 offset:13152
	s_waitcnt lgkmcnt(0)
	v_mfma_f32_32x32x16_bf16 v[18:33], v[6:9], v[158:161], v[18:33]
	s_setprio 0
; DI int crow(int i, int h) { return (i & 3) + 8 * (i >> 2) + 4 * h; }
; DI void attn_unit(unsigned char* smem, const Params& P, int bh, int qb) {
;     ...
;     { const bf16_t* vp_ = vtb + (size_t)(tid >> 3) * 8192 + jt * 64 + (tid & 7) * 8; vr0 = *(const uint4*)(vp_ + (size_t)0 * 8192); vr1 = *(const uint4*)(vp_ + (size_t)32 * 8192); vr2 = *(const uint4*)(vp_ + (size_t)64 * 8192); vr3 = *(const uint4*)(vp_ + (size_t)96 * 8192); }
;     __builtin_amdgcn_sched_barrier(0);
;     if (active) {
;       if (jt >= ntiles - 2) {
; #pragma unroll
;         for (int kt = 0; kt < 2; ++kt)
; #pragma unroll
;           for (int i = 0; i < 16; ++i) { const int key = jt * 64 + kt * 32 + crow(i, hh); if (key > qrow) S[kt][i] = -1e30f; }
;       }
.LBB0_504:
	s_or_b64 exec, exec, s[50:51]
	s_barrier
	v_ashrrev_i32_e32 v82, 3, v5
	v_ashrrev_i32_e32 v83, 31, v82
	v_lshlrev_b64 v[6:7], 14, v[82:83]
	v_and_b32_e32 v2, 56, v84
	v_lshl_add_u64 v[6:7], s[52:53], 0, v[6:7]
	v_lshlrev_b32_e32 v2, 1, v2
	v_lshl_add_u64 v[200:201], v[6:7], 0, v[2:3]
	v_add_co_u32_e32 v6, vcc, s78, v200
	v_ashrrev_i32_e32 v197, 31, v196
	s_nop 0
	v_addc_co_u32_e32 v7, vcc, 0, v201, vcc
	global_load_dwordx4 v[66:69], v[200:201], off
	global_load_dwordx4 v[70:73], v[6:7], off
	v_add_co_u32_e32 v6, vcc, s79, v200
	v_lshlrev_b32_e32 v216, 2, v4
	s_nop 0
	v_addc_co_u32_e32 v7, vcc, 0, v201, vcc
	v_add_co_u32_e32 v8, vcc, s80, v200
	s_nop 1
	v_addc_co_u32_e32 v9, vcc, 0, v201, vcc
	global_load_dwordx4 v[74:77], v[6:7], off
	global_load_dwordx4 v[78:81], v[8:9], off
	v_mov_b32_e32 v16, v3
	v_mov_b32_e32 v17, v3
	v_mov_b32_e32 v2, v3
	v_mov_b32_e32 v4, v3
	v_mov_b32_e32 v5, v3
	v_mov_b32_e32 v6, v3
	v_mov_b32_e32 v7, v3
	v_mov_b32_e32 v8, v3
	v_mov_b32_e32 v9, v3
	v_mov_b32_e32 v10, v3
	v_mov_b32_e32 v11, v3
	v_mov_b32_e32 v12, v3
	v_mov_b32_e32 v13, v3
	v_mov_b32_e32 v14, v3
	v_mov_b32_e32 v15, v3
	v_mov_b64_e32 v[64:65], v[16:17]
	v_mov_b32_e32 v202, 0xf149f2ca
	v_mov_b64_e32 v[62:63], v[14:15]
	v_mov_b64_e32 v[60:61], v[12:13]
	v_mov_b64_e32 v[58:59], v[10:11]
	v_mov_b64_e32 v[56:57], v[8:9]
	v_mov_b64_e32 v[54:55], v[6:7]
	v_mov_b64_e32 v[52:53], v[4:5]
	v_mov_b64_e32 v[50:51], v[2:3]
	s_and_saveexec_b64 s[14:15], s[2:3]
	s_cbranch_execz .LBB0_511
	s_cmp_gt_u32 s93, 15
	s_cbranch_scc1 .LBB0_507
	v_cmp_le_i32_e32 vcc, v216, v196
	v_or_b32_e32 v2, 2, v216
	s_nop 0
	v_cndmask_b32_e32 v34, v213, v34, vcc
	v_cmp_lt_i32_e32 vcc, v216, v196
	s_nop 1
	v_cndmask_b32_e32 v35, v213, v35, vcc
	v_cmp_le_i32_e32 vcc, v2, v196
	v_or_b32_e32 v2, 3, v216
	s_nop 0
	v_cndmask_b32_e32 v36, v213, v36, vcc
	v_cmp_le_i32_e32 vcc, v2, v196
	v_or_b32_e32 v2, 8, v216
	s_nop 0
	v_cndmask_b32_e32 v37, v213, v37, vcc
	v_cmp_le_i32_e32 vcc, v2, v196
	v_or_b32_e32 v2, 9, v216
	s_nop 0
	v_cndmask_b32_e32 v38, v213, v38, vcc
	v_cmp_le_i32_e32 vcc, v2, v196
	v_or_b32_e32 v2, 10, v216
	s_nop 0
	v_cndmask_b32_e32 v39, v213, v39, vcc
	v_cmp_le_i32_e32 vcc, v2, v196
	v_or_b32_e32 v2, 11, v216
	s_nop 0
	v_cndmask_b32_e32 v40, v213, v40, vcc
	v_cmp_le_i32_e32 vcc, v2, v196
	v_or_b32_e32 v2, 16, v216
	s_nop 0
	v_cndmask_b32_e32 v41, v213, v41, vcc
	v_cmp_le_i32_e32 vcc, v2, v196
	v_or_b32_e32 v2, 17, v216
	s_nop 0
	v_cndmask_b32_e32 v42, v213, v42, vcc
	v_cmp_le_i32_e32 vcc, v2, v196
	v_or_b32_e32 v2, 18, v216
	s_nop 0
	v_cndmask_b32_e32 v43, v213, v43, vcc
	v_cmp_le_i32_e32 vcc, v2, v196
	v_or_b32_e32 v2, 19, v216
	s_nop 0
	v_cndmask_b32_e32 v44, v213, v44, vcc
	v_cmp_le_i32_e32 vcc, v2, v196
	v_or_b32_e32 v2, 24, v216
	s_nop 0
	v_cndmask_b32_e32 v45, v213, v45, vcc
	v_cmp_le_i32_e32 vcc, v2, v196
	v_or_b32_e32 v2, 25, v216
	s_nop 0
	v_cndmask_b32_e32 v46, v213, v46, vcc
	v_cmp_le_i32_e32 vcc, v2, v196
	v_or_b32_e32 v2, 26, v216
	s_nop 0
	v_cndmask_b32_e32 v47, v213, v47, vcc
	v_cmp_le_i32_e32 vcc, v2, v196
	v_or_b32_e32 v2, 27, v216
	s_nop 0
	v_cndmask_b32_e32 v48, v213, v48, vcc
	v_cmp_le_i32_e32 vcc, v2, v196
	v_or_b32_e32 v2, 32, v216
	s_nop 0
	v_cndmask_b32_e32 v49, v213, v49, vcc
	v_cmp_le_i32_e32 vcc, v2, v196
	v_or_b32_e32 v2, 33, v216
	s_nop 0
	v_cndmask_b32_e32 v18, v213, v18, vcc
	v_cmp_le_i32_e32 vcc, v2, v196
	v_or_b32_e32 v2, 34, v216
	s_nop 0
	v_cndmask_b32_e32 v19, v213, v19, vcc
	v_cmp_le_i32_e32 vcc, v2, v196
	v_or_b32_e32 v2, 35, v216
	s_nop 0
	v_cndmask_b32_e32 v20, v213, v20, vcc
	v_cmp_le_i32_e32 vcc, v2, v196
	v_or_b32_e32 v2, 40, v216
	s_nop 0
	v_cndmask_b32_e32 v21, v213, v21, vcc
	v_cmp_le_i32_e32 vcc, v2, v196
	v_or_b32_e32 v2, 41, v216
	s_nop 0
	v_cndmask_b32_e32 v22, v213, v22, vcc
	v_cmp_le_i32_e32 vcc, v2, v196
	v_or_b32_e32 v2, 42, v216
	s_nop 0
	v_cndmask_b32_e32 v23, v213, v23, vcc
	v_cmp_le_i32_e32 vcc, v2, v196
	v_or_b32_e32 v2, 43, v216
	s_nop 0
	v_cndmask_b32_e32 v24, v213, v24, vcc
	v_cmp_le_i32_e32 vcc, v2, v196
	v_or_b32_e32 v2, 48, v216
	s_nop 0
	v_cndmask_b32_e32 v25, v213, v25, vcc
	v_cmp_le_i32_e32 vcc, v2, v196
	v_or_b32_e32 v2, 49, v216
	s_nop 0
	v_cndmask_b32_e32 v26, v213, v26, vcc
	v_cmp_le_i32_e32 vcc, v2, v196
	v_or_b32_e32 v2, 50, v216
	s_nop 0
	v_cndmask_b32_e32 v27, v213, v27, vcc
	v_cmp_le_i32_e32 vcc, v2, v196
	v_or_b32_e32 v2, 51, v216
	s_nop 0
	v_cndmask_b32_e32 v28, v213, v28, vcc
	v_cmp_le_i32_e32 vcc, v2, v196
	v_or_b32_e32 v2, 56, v216
	s_nop 0
	v_cndmask_b32_e32 v29, v213, v29, vcc
	v_cmp_le_i32_e32 vcc, v2, v196
	v_or_b32_e32 v2, 57, v216
	s_nop 0
	v_cndmask_b32_e32 v30, v213, v30, vcc
	v_cmp_le_i32_e32 vcc, v2, v196
	v_or_b32_e32 v2, 58, v216
	s_nop 0
	v_cndmask_b32_e32 v31, v213, v31, vcc
	v_cmp_le_i32_e32 vcc, v2, v196
	v_or_b32_e32 v2, 59, v216
	s_nop 0
	v_cndmask_b32_e32 v32, v213, v32, vcc
	v_cmp_le_i32_e32 vcc, v2, v196
	s_nop 1
	v_cndmask_b32_e32 v33, v213, v33, vcc

; DI void attn_unit(unsigned char* smem, const Params& P, int bh, int qb) {
;     ...
;     { bf16_t* vq_ = sV + (tid >> 3) * LDK + ((tid & 7) >> 1) * 16 + (tid & 1) * 4;
;       *(uint2*)(vq_) = make_uint2(vr0.x, vr0.y); *(uint2*)(vq_ + 8) = make_uint2(vr0.z, vr0.w);
;       *(uint2*)(vq_ + 32 * LDK) = make_uint2(vr1.x, vr1.y); *(uint2*)(vq_ + 32 * LDK + 8) = make_uint2(vr1.z, vr1.w);
;       *(uint2*)(vq_ + 64 * LDK) = make_uint2(vr2.x, vr2.y); *(uint2*)(vq_ + 64 * LDK + 8) = make_uint2(vr2.z, vr2.w);
;       *(uint2*)(vq_ + 96 * LDK) = make_uint2(vr3.x, vr3.y); *(uint2*)(vq_ + 96 * LDK + 8) = make_uint2(vr3.z, vr3.w); }
;     if (more) {
;       *(uint4*)(nK + klo + 0) = kr0; *(uint4*)(nK + klo + 32) = kr1; *(uint4*)(nK + klo + 64) = kr2; *(uint4*)(nK + klo + 96) = kr3; *(uint4*)(nK + klo + 128) = kr4; *(uint4*)(nK + klo + 160) = kr5;
;     }
;     __syncthreads();
.LBB0_511:
	s_or_b64 exec, exec, s[14:15]
	v_mul_lo_u32 v2, v82, s82
	v_and_b32_e32 v4, 48, v84
	v_add_u32_e32 v2, s9, v2
	v_lshlrev_b32_e32 v4, 1, v4
	v_and_b32_e32 v5, 8, v84
	v_add3_u32 v5, v2, v4, v5
	v_lshl_add_u32 v4, v86, 1, s9
	v_add_u32_e32 v2, 0x6000, v5
	v_add_u32_e32 v218, 0x7000, v5
	v_add_u32_e32 v219, 0x8800, v5
	v_add_u32_e32 v220, 0x9800, v5
	v_mul_u32_u24_e32 v5, 0x48, v189
	v_mad_u32_u24 v6, v189, s83, v210
	v_mad_u32_u24 v7, v189, s83, v211
	v_mad_u32_u24 v8, v189, s83, v212
	s_waitcnt vmcnt(3)
	ds_write2_b64 v2, v[66:67], v[68:69] offset0:128 offset1:130
	s_waitcnt vmcnt(2)
	ds_write2_b64 v218, v[70:71], v[72:73] offset0:192 offset1:194
	s_waitcnt vmcnt(1)
	ds_write2_b64 v219, v[74:75], v[76:77] offset1:2
	s_waitcnt vmcnt(0)
	ds_write2_b64 v220, v[78:79], v[80:81] offset0:64 offset1:66
	ds_write_b128 v85, v[162:165] offset:44032
	ds_write_b128 v85, v[166:169] offset:44096
	ds_write_b128 v85, v[170:173] offset:44160
	ds_write_b128 v85, v[174:177] offset:44224
	ds_write_b128 v85, v[178:181] offset:44288
	ds_write_b128 v85, v[182:185] offset:44352
	s_waitcnt lgkmcnt(0)
	s_barrier
	s_nop 8
	v_mov_b64_e32 v[80:81], v[64:65]
	v_mov_b64_e32 v[96:97], v[64:65]
	v_mov_b64_e32 v[112:113], v[64:65]
	v_mov_b64_e32 v[78:79], v[62:63]
	v_mov_b64_e32 v[76:77], v[60:61]
	v_mov_b64_e32 v[74:75], v[58:59]
	v_mov_b64_e32 v[72:73], v[56:57]
	v_mov_b64_e32 v[70:71], v[54:55]
	v_mov_b64_e32 v[68:69], v[52:53]
	v_mov_b64_e32 v[66:67], v[50:51]
	v_mov_b64_e32 v[94:95], v[62:63]
	v_mov_b64_e32 v[92:93], v[60:61]
	v_mov_b64_e32 v[90:91], v[58:59]
	v_mov_b64_e32 v[88:89], v[56:57]
	v_mov_b64_e32 v[86:87], v[54:55]
	v_mov_b64_e32 v[84:85], v[52:53]
	v_mov_b64_e32 v[82:83], v[50:51]
	v_mov_b64_e32 v[110:111], v[62:63]
	v_mov_b64_e32 v[108:109], v[60:61]
	v_mov_b64_e32 v[106:107], v[58:59]
	v_mov_b64_e32 v[104:105], v[56:57]
	v_mov_b64_e32 v[102:103], v[54:55]
	v_mov_b64_e32 v[100:101], v[52:53]
	v_mov_b64_e32 v[98:99], v[50:51]
	s_lshl_b32 s8, s92, 1
	s_add_i32 s13, s8, 2
	s_add_u32 s2, s65, s96
	s_addc_u32 s3, s66, 0
	v_or_b32_e32 v221, 31, v188
	v_lshl_add_u32 v222, v5, 1, v4
	v_lshl_add_u32 v223, v6, 1, v4
	v_lshl_add_u32 v224, v7, 1, v4
	v_lshl_add_u32 v225, v8, 1, v4
	v_lshl_add_u64 v[16:17], v[186:187], 1, s[2:3]
	s_mov_b32 s20, -1
	s_mov_b32 s21, 0

; #define MFMA32(a, b, c) __builtin_amdgcn_mfma_f32_32x32x16_bf16((a), (b), (c), 0, 0, 0)
; DI void attn_unit(unsigned char* smem, const Params& P, int bh, int qb) {
;     ...
;   for (int jt = 0; jt < ntiles; ++jt) {
;     const bf16_t* cK = (jt & 1) ? sK1 : sK;
;     bf16_t* nK = (jt & 1) ? sK : sK1;
;     const bool more = (jt + 1 < ntiles);
;     const bool active = (jt * 64 <= q0 + 32 * w + 31);
;     if (more) {
;       const bf16_t* kp = kbuf + (size_t)(jt + 1) * 64 * 192;
;       kr0 = *(const uint4*)(kp + kgo + 0); kr1 = *(const uint4*)(kp + kgo + 32); kr2 = *(const uint4*)(kp + kgo + 64); kr3 = *(const uint4*)(kp + kgo + 96); kr4 = *(const uint4*)(kp + kgo + 128); kr5 = *(const uint4*)(kp + kgo + 160);
;     }
;     __builtin_amdgcn_sched_barrier(0);
;     f32x16 S[2];
;     const float sref = (jt == 0) ? 0.f : mrun;
;     if (active) {
; #pragma unroll
;       for (int a = 0; a < 2; ++a)
; #pragma unroll
;         for (int i = 0; i < 16; ++i) S[a][i] = -sref;
;       __builtin_amdgcn_s_setprio(1);
; #pragma unroll
;       for (int ks = 0; ks < 12; ++ks) {
;         const bf16x8 a0 = *(const bf16x8*)(cK + l31 * KLD + ks * 16 + hh * 8), a1 = *(const bf16x8*)(cK + (32 + l31) * KLD + ks * 16 + hh * 8);
;         S[0] = MFMA32(a0, qf[ks], S[0]); S[1] = MFMA32(a1, qf[ks], S[1]);
;       }
;       __builtin_amdgcn_s_setprio(0);
;     }
;     { const bf16_t* vp_ = vtb + (size_t)(tid >> 3) * 8192 + jt * 64 + (tid & 7) * 8; vr0 = *(const uint4*)(vp_ + (size_t)0 * 8192); vr1 = *(const uint4*)(vp_ + (size_t)32 * 8192); vr2 = *(const uint4*)(vp_ + (size_t)64 * 8192); vr3 = *(const uint4*)(vp_ + (size_t)96 * 8192); }
;     ...
;     if (active) {
;       __builtin_amdgcn_s_setprio(1);
; #pragma unroll
;       for (int kt = 0; kt < 2; ++kt)
; #pragma unroll
;         for (int s2 = 0; s2 < 2; ++s2) {
;           uint4 pp; pp.x = pk2(S[kt][8 * s2], S[kt][8 * s2 + 1]); pp.y = pk2(S[kt][8 * s2 + 2], S[kt][8 * s2 + 3]);
;           pp.z = pk2(S[kt][8 * s2 + 4], S[kt][8 * s2 + 5]); pp.w = pk2(S[kt][8 * s2 + 6], S[kt][8 * s2 + 7]);
;           const bf16x8 pb = __builtin_bit_cast(bf16x8, pp);
; #pragma unroll
;           for (int d = 0; d < 4; ++d) {
;             const bf16x8 vf = *(const bf16x8*)(sV + (d * 32 + l31) * LDK + kt * 32 + s2 * 16 + hh * 8);
;             O[d] = MFMA32(vf, pb, O[d]);
;           }
;         }
;       __builtin_amdgcn_s_setprio(0);
;     }
.LBB0_518:
	s_add_i32 s22, s20, 2
	s_bitcmp0_b32 s22, 0
	s_cselect_b64 s[16:17], -1, 0
	s_add_i32 s10, s21, 64
	v_cmp_le_i32_e64 s[2:3], s10, v221
	v_cmp_le_i32_e64 s[98:99], s21, v221
	s_cmp_lg_u64 s[2:3], 0
	s_cbranch_scc0 .Lslow_1
	s_and_b64 s[24:25], s[16:17], exec
	s_cselect_b32 s23, s9, s28
	v_add3_u32 v243, s23, v199, v215
	s_setprio 1
	ds_read_b128 v[12:15], v222 offset:25600
	ds_read_b128 v[186:189], v223 offset:25600
	ds_read_b128 v[226:229], v224 offset:25600
	ds_read_b128 v[230:233], v225 offset:25600
	ds_read_b128 v[244:247], v222 offset:25632
	ds_read_b128 v[248:251], v223 offset:25632
	ds_read_b128 v[252:255], v224 offset:25632
	v_cvt_pk_bf16_f32 v8, v34, v35
	v_cvt_pk_bf16_f32 v9, v36, v37
	v_cvt_pk_bf16_f32 v10, v38, v39
	v_cvt_pk_bf16_f32 v11, v40, v41
	v_cvt_pk_bf16_f32 v4, v42, v43
	v_cvt_pk_bf16_f32 v5, v44, v45
	v_cvt_pk_bf16_f32 v6, v46, v47
	v_cvt_pk_bf16_f32 v7, v48, v49
	s_waitcnt lgkmcnt(6)
	v_mfma_f32_32x32x16_bf16 v[98:113], v[12:15], v[8:11], v[98:113]
	ds_read_b128 v[12:15], v225 offset:25632
	global_load_dwordx4 v[162:165], v[16:17], off
	s_waitcnt lgkmcnt(6)
	v_mfma_f32_32x32x16_bf16 v[82:97], v[186:189], v[8:11], v[82:97]
	ds_read_b128 v[186:189], v222 offset:25664
	global_load_dwordx4 v[166:169], v[16:17], off offset:64
	s_waitcnt lgkmcnt(6)
	v_mfma_f32_32x32x16_bf16 v[66:81], v[226:229], v[8:11], v[66:81]
	ds_read_b128 v[226:229], v223 offset:25664
	global_load_dwordx4 v[170:173], v[16:17], off offset:128
	s_waitcnt lgkmcnt(6)
	v_mfma_f32_32x32x16_bf16 v[50:65], v[230:233], v[8:11], v[50:65]
	ds_read_b128 v[230:233], v224 offset:25664
	global_load_dwordx4 v[174:177], v[16:17], off offset:192
	s_waitcnt lgkmcnt(6)
	v_mfma_f32_32x32x16_bf16 v[98:113], v[244:247], v[4:7], v[98:113]
	ds_read_b128 v[244:247], v225 offset:25664
	global_load_dwordx4 v[178:181], v[16:17], off offset:256
	v_cvt_pk_bf16_f32 v8, v18, v19
	v_cvt_pk_bf16_f32 v9, v20, v21
	v_cvt_pk_bf16_f32 v10, v22, v23
	v_cvt_pk_bf16_f32 v11, v24, v25
	s_waitcnt lgkmcnt(6)
	v_mfma_f32_32x32x16_bf16 v[82:97], v[248:251], v[4:7], v[82:97]
	ds_read_b128 v[248:251], v222 offset:25696
	global_load_dwordx4 v[182:185], v[16:17], off offset:320
	s_waitcnt lgkmcnt(6)
	v_mfma_f32_32x32x16_bf16 v[66:81], v[252:255], v[4:7], v[66:81]
	ds_read_b128 v[252:255], v223 offset:25696
	s_waitcnt lgkmcnt(6)
	v_mfma_f32_32x32x16_bf16 v[50:65], v[12:15], v[4:7], v[50:65]
	ds_read_b128 v[12:15], v224 offset:25696
	s_waitcnt lgkmcnt(6)
	v_mfma_f32_32x32x16_bf16 v[98:113], v[186:189], v[8:11], v[98:113]
	ds_read_b128 v[186:189], v225 offset:25696
	v_cvt_pk_bf16_f32 v4, v26, v27
	v_cvt_pk_bf16_f32 v5, v28, v29
	v_cvt_pk_bf16_f32 v6, v30, v31
	v_cvt_pk_bf16_f32 v7, v32, v33
	s_waitcnt lgkmcnt(6)
	v_mfma_f32_32x32x16_bf16 v[82:97], v[226:229], v[8:11], v[82:97]
	v_xor_b32_e32 v18, 0x80000000, v202
	v_mov_b32_e32 v19, v18
	v_mov_b32_e32 v20, v18
	v_mov_b32_e32 v21, v18
	ds_read_b128 v[226:229], v243 offset:12832
	s_waitcnt lgkmcnt(6)
	v_mfma_f32_32x32x16_bf16 v[66:81], v[230:233], v[8:11], v[66:81]
	v_mov_b32_e32 v22, v18
	v_mov_b32_e32 v23, v18
	v_mov_b32_e32 v24, v18
	v_mov_b32_e32 v25, v18
	ds_read_b128 v[230:233], v243 offset:64
	s_waitcnt lgkmcnt(6)
	v_mfma_f32_32x32x16_bf16 v[50:65], v[244:247], v[8:11], v[50:65]
	v_mov_b32_e32 v26, v18
	v_mov_b32_e32 v27, v18
	v_mov_b32_e32 v28, v18
	v_mov_b32_e32 v29, v18
	ds_read_b128 v[244:247], v243
	s_waitcnt lgkmcnt(6)
	v_mfma_f32_32x32x16_bf16 v[98:113], v[248:251], v[4:7], v[98:113]
	v_mov_b32_e32 v30, v18
	v_mov_b32_e32 v31, v18
	v_mov_b32_e32 v32, v18
	v_mov_b32_e32 v33, v18
	ds_read_b128 v[248:251], v243 offset:12800
	s_waitcnt lgkmcnt(6)
	v_mfma_f32_32x32x16_bf16 v[82:97], v[252:255], v[4:7], v[82:97]
	ds_read_b128 v[252:255], v243 offset:32
	s_waitcnt lgkmcnt(6)
	v_mfma_f32_32x32x16_bf16 v[66:81], v[12:15], v[4:7], v[66:81]
	s_waitcnt lgkmcnt(5)
	v_mfma_f32_32x32x16_bf16 v[50:65], v[186:189], v[4:7], v[50:65]
	s_waitcnt lgkmcnt(2)
	v_mfma_f32_32x32x16_bf16 v[34:49], v[244:247], v[114:117], v[18:33]
	ds_read_b128 v[244:247], v243 offset:12864
	v_lshl_add_u64 v[12:13], s[10:11], 1, v[200:201]
	v_add_co_u32_e32 v8, vcc, s78, v12
	s_nop 1
	v_addc_co_u32_e32 v9, vcc, 0, v13, vcc
	s_waitcnt lgkmcnt(2)
	v_mfma_f32_32x32x16_bf16 v[18:33], v[248:251], v[114:117], v[18:33]
	ds_read_b128 v[248:251], v243 offset:96
	v_add_co_u32_e32 v14, vcc, 0x100000, v12
	global_load_dwordx4 v[4:7], v[12:13], off
	s_nop 0
	global_load_dwordx4 v[8:11], v[8:9], off
	s_waitcnt lgkmcnt(2)
	v_mfma_f32_32x32x16_bf16 v[34:49], v[252:255], v[118:121], v[34:49]
	ds_read_b128 v[252:255], v243 offset:12896
	v_addc_co_u32_e32 v15, vcc, 0, v13, vcc
	v_add_co_u32_e32 v12, vcc, 0x180000, v12
	s_nop 1
	v_addc_co_u32_e32 v13, vcc, 0, v13, vcc
	s_waitcnt lgkmcnt(7)
	v_mfma_f32_32x32x16_bf16 v[18:33], v[226:229], v[118:121], v[18:33]
	ds_read_b128 v[226:229], v243 offset:128
	global_load_dwordx4 v[186:189], v[14:15], off
	s_nop 0
	global_load_dwordx4 v[12:15], v[12:13], off
	s_waitcnt lgkmcnt(7)
	v_mfma_f32_32x32x16_bf16 v[34:49], v[230:233], v[122:125], v[34:49]
	ds_read_b128 v[230:233], v243 offset:12928
	s_waitcnt lgkmcnt(4)
	v_mfma_f32_32x32x16_bf16 v[18:33], v[244:247], v[122:125], v[18:33]
	ds_read_b128 v[244:247], v243 offset:160
	s_waitcnt lgkmcnt(4)
	v_mfma_f32_32x32x16_bf16 v[34:49], v[248:251], v[126:129], v[34:49]
	ds_read_b128 v[248:251], v243 offset:12960
	s_waitcnt lgkmcnt(4)
	v_mfma_f32_32x32x16_bf16 v[18:33], v[252:255], v[126:129], v[18:33]
	ds_read_b128 v[252:255], v243 offset:192
	s_waitcnt lgkmcnt(4)
	v_mfma_f32_32x32x16_bf16 v[34:49], v[226:229], v[130:133], v[34:49]
	ds_read_b128 v[226:229], v243 offset:12992
	s_waitcnt lgkmcnt(4)
; #define MFMA32(a, b, c) __builtin_amdgcn_mfma_f32_32x32x16_bf16((a), (b), (c), 0, 0, 0)
; DI void attn_unit(unsigned char* smem, const Params& P, int bh, int qb) {
;     ...
;       kr0 = *(const uint4*)(kp + kgo + 0); kr1 = *(const uint4*)(kp + kgo + 32); kr2 = *(const uint4*)(kp + kgo + 64); kr3 = *(const uint4*)(kp + kgo + 96); kr4 = *(const uint4*)(kp + kgo + 128); kr5 = *(const uint4*)(kp + kgo + 160);
;     }
;     __builtin_amdgcn_sched_barrier(0);
;     f32x16 S[2];
;     const float sref = (jt == 0) ? 0.f : mrun;
;     if (active) {
; #pragma unroll
;       for (int a = 0; a < 2; ++a)
; #pragma unroll
;         for (int i = 0; i < 16; ++i) S[a][i] = -sref;
;       __builtin_amdgcn_s_setprio(1);
; #pragma unroll
;       for (int ks = 0; ks < 12; ++ks) {
;         const bf16x8 a0 = *(const bf16x8*)(cK + l31 * KLD + ks * 16 + hh * 8), a1 = *(const bf16x8*)(cK + (32 + l31) * KLD + ks * 16 + hh * 8);
;         S[0] = MFMA32(a0, qf[ks], S[0]); S[1] = MFMA32(a1, qf[ks], S[1]);
;       }
;       __builtin_amdgcn_s_setprio(0);
;     ...
;     if (active) {
;       __builtin_amdgcn_s_setprio(1);
; #pragma unroll
;       for (int kt = 0; kt < 2; ++kt)
; #pragma unroll
;         for (int s2 = 0; s2 < 2; ++s2) {
;           uint4 pp; pp.x = pk2(S[kt][8 * s2], S[kt][8 * s2 + 1]); pp.y = pk2(S[kt][8 * s2 + 2], S[kt][8 * s2 + 3]);
;           pp.z = pk2(S[kt][8 * s2 + 4], S[kt][8 * s2 + 5]); pp.w = pk2(S[kt][8 * s2 + 6], S[kt][8 * s2 + 7]);
;           const bf16x8 pb = __builtin_bit_cast(bf16x8, pp);
; #pragma unroll
;           for (int d = 0; d < 4; ++d) {
;             const bf16x8 vf = *(const bf16x8*)(sV + (d * 32 + l31) * LDK + kt * 32 + s2 * 16 + hh * 8);
;             O[d] = MFMA32(vf, pb, O[d]);
;           }
;         }
;       __builtin_amdgcn_s_setprio(0);
;     }
	v_mfma_f32_32x32x16_bf16 v[18:33], v[230:233], v[130:133], v[18:33]
	ds_read_b128 v[230:233], v243 offset:224
	s_waitcnt lgkmcnt(4)
	v_mfma_f32_32x32x16_bf16 v[34:49], v[244:247], v[134:137], v[34:49]
	ds_read_b128 v[244:247], v243 offset:13024
	s_waitcnt lgkmcnt(4)
	v_mfma_f32_32x32x16_bf16 v[18:33], v[248:251], v[134:137], v[18:33]
	ds_read_b128 v[248:251], v243 offset:256
	s_waitcnt lgkmcnt(4)
	v_mfma_f32_32x32x16_bf16 v[34:49], v[252:255], v[138:141], v[34:49]
	ds_read_b128 v[252:255], v243 offset:13056
	s_waitcnt lgkmcnt(4)
	v_mfma_f32_32x32x16_bf16 v[18:33], v[226:229], v[138:141], v[18:33]
	ds_read_b128 v[226:229], v243 offset:288
	s_waitcnt lgkmcnt(4)
	v_mfma_f32_32x32x16_bf16 v[34:49], v[230:233], v[142:145], v[34:49]
	ds_read_b128 v[230:233], v243 offset:13088
	s_waitcnt lgkmcnt(4)
	v_mfma_f32_32x32x16_bf16 v[18:33], v[244:247], v[142:145], v[18:33]
	ds_read_b128 v[244:247], v243 offset:320
	s_waitcnt lgkmcnt(4)
	v_mfma_f32_32x32x16_bf16 v[34:49], v[248:251], v[146:149], v[34:49]
	ds_read_b128 v[248:251], v243 offset:13120
	s_waitcnt lgkmcnt(4)
	v_mfma_f32_32x32x16_bf16 v[18:33], v[252:255], v[146:149], v[18:33]
	ds_read_b128 v[252:255], v243 offset:352
	s_waitcnt lgkmcnt(4)
	v_mfma_f32_32x32x16_bf16 v[34:49], v[226:229], v[150:153], v[34:49]
	ds_read_b128 v[226:229], v243 offset:13152
	s_waitcnt lgkmcnt(4)
	v_mfma_f32_32x32x16_bf16 v[18:33], v[230:233], v[150:153], v[18:33]
	s_waitcnt lgkmcnt(3)
	v_mfma_f32_32x32x16_bf16 v[34:49], v[244:247], v[154:157], v[34:49]
	s_waitcnt lgkmcnt(2)
	v_mfma_f32_32x32x16_bf16 v[18:33], v[248:251], v[154:157], v[18:33]
	s_waitcnt lgkmcnt(1)
	v_mfma_f32_32x32x16_bf16 v[34:49], v[252:255], v[158:161], v[34:49]
	s_waitcnt lgkmcnt(0)
	v_mfma_f32_32x32x16_bf16 v[18:33], v[226:229], v[158:161], v[18:33]
	s_nop 11
	s_setprio 0
	s_branch .LBB0_520
.Lslow_1:
	s_cmp_lg_u64 s[14:15], 0
	s_cbranch_scc0 .Lnok2_1
	global_load_dwordx4 v[162:165], v[16:17], off
	global_load_dwordx4 v[166:169], v[16:17], off offset:64
	global_load_dwordx4 v[170:173], v[16:17], off offset:128
	global_load_dwordx4 v[174:177], v[16:17], off offset:192
	global_load_dwordx4 v[178:181], v[16:17], off offset:256
	global_load_dwordx4 v[182:185], v[16:17], off offset:320
.Lnok2_1:
	s_and_saveexec_b64 s[100:101], s[98:99]
	s_cbranch_execz .Lpvtop_skip_1
	s_setprio 1
	ds_read_b128 v[12:15], v222 offset:25600
	ds_read_b128 v[186:189], v223 offset:25600
	ds_read_b128 v[226:229], v224 offset:25600
	ds_read_b128 v[230:233], v225 offset:25600
	ds_read_b128 v[244:247], v222 offset:25632
	ds_read_b128 v[248:251], v223 offset:25632
	ds_read_b128 v[252:255], v224 offset:25632
	v_cvt_pk_bf16_f32 v8, v34, v35
	v_cvt_pk_bf16_f32 v9, v36, v37
	v_cvt_pk_bf16_f32 v10, v38, v39
	v_cvt_pk_bf16_f32 v11, v40, v41
	v_cvt_pk_bf16_f32 v4, v42, v43
	v_cvt_pk_bf16_f32 v5, v44, v45
	v_cvt_pk_bf16_f32 v6, v46, v47
	v_cvt_pk_bf16_f32 v7, v48, v49
	s_waitcnt lgkmcnt(6)
	v_mfma_f32_32x32x16_bf16 v[98:113], v[12:15], v[8:11], v[98:113]
	ds_read_b128 v[12:15], v225 offset:25632
	s_waitcnt lgkmcnt(6)
	v_mfma_f32_32x32x16_bf16 v[82:97], v[186:189], v[8:11], v[82:97]
	ds_read_b128 v[186:189], v222 offset:25664
	s_waitcnt lgkmcnt(6)
	v_mfma_f32_32x32x16_bf16 v[66:81], v[226:229], v[8:11], v[66:81]
	ds_read_b128 v[226:229], v223 offset:25664
	s_waitcnt lgkmcnt(6)
	v_mfma_f32_32x32x16_bf16 v[50:65], v[230:233], v[8:11], v[50:65]
	ds_read_b128 v[230:233], v224 offset:25664
	s_waitcnt lgkmcnt(6)
	v_mfma_f32_32x32x16_bf16 v[98:113], v[244:247], v[4:7], v[98:113]
	ds_read_b128 v[244:247], v225 offset:25664
	v_cvt_pk_bf16_f32 v8, v18, v19
	v_cvt_pk_bf16_f32 v9, v20, v21
	v_cvt_pk_bf16_f32 v10, v22, v23
	v_cvt_pk_bf16_f32 v11, v24, v25
	s_waitcnt lgkmcnt(6)
	v_mfma_f32_32x32x16_bf16 v[82:97], v[248:251], v[4:7], v[82:97]
	ds_read_b128 v[248:251], v222 offset:25696
	s_waitcnt lgkmcnt(6)
	v_mfma_f32_32x32x16_bf16 v[66:81], v[252:255], v[4:7], v[66:81]
	ds_read_b128 v[252:255], v223 offset:25696
	s_waitcnt lgkmcnt(6)
	v_mfma_f32_32x32x16_bf16 v[50:65], v[12:15], v[4:7], v[50:65]
	ds_read_b128 v[12:15], v224 offset:25696
	s_waitcnt lgkmcnt(6)
	v_mfma_f32_32x32x16_bf16 v[98:113], v[186:189], v[8:11], v[98:113]
	ds_read_b128 v[186:189], v225 offset:25696
	v_cvt_pk_bf16_f32 v4, v26, v27
	v_cvt_pk_bf16_f32 v5, v28, v29
	v_cvt_pk_bf16_f32 v6, v30, v31
	v_cvt_pk_bf16_f32 v7, v32, v33
	s_waitcnt lgkmcnt(6)
	v_mfma_f32_32x32x16_bf16 v[82:97], v[226:229], v[8:11], v[82:97]
	s_waitcnt lgkmcnt(5)
	v_mfma_f32_32x32x16_bf16 v[66:81], v[230:233], v[8:11], v[66:81]
	s_waitcnt lgkmcnt(4)
	v_mfma_f32_32x32x16_bf16 v[50:65], v[244:247], v[8:11], v[50:65]
	s_waitcnt lgkmcnt(3)
	v_mfma_f32_32x32x16_bf16 v[98:113], v[248:251], v[4:7], v[98:113]
	s_waitcnt lgkmcnt(2)
	v_mfma_f32_32x32x16_bf16 v[82:97], v[252:255], v[4:7], v[82:97]
	s_waitcnt lgkmcnt(1)
	v_mfma_f32_32x32x16_bf16 v[66:81], v[12:15], v[4:7], v[66:81]
	s_waitcnt lgkmcnt(0)
	v_mfma_f32_32x32x16_bf16 v[50:65], v[186:189], v[4:7], v[50:65]
	s_setprio 0
; #define MFMA32(a, b, c) __builtin_amdgcn_mfma_f32_32x32x16_bf16((a), (b), (c), 0, 0, 0)
; DI void attn_unit(unsigned char* smem, const Params& P, int bh, int qb) {
;     ...
;     if (active) {
; #pragma unroll
;       for (int a = 0; a < 2; ++a)
; #pragma unroll
;         for (int i = 0; i < 16; ++i) S[a][i] = -sref;
;       __builtin_amdgcn_s_setprio(1);
; #pragma unroll
;       for (int ks = 0; ks < 12; ++ks) {
;         const bf16x8 a0 = *(const bf16x8*)(cK + l31 * KLD + ks * 16 + hh * 8), a1 = *(const bf16x8*)(cK + (32 + l31) * KLD + ks * 16 + hh * 8);
;         S[0] = MFMA32(a0, qf[ks], S[0]); S[1] = MFMA32(a1, qf[ks], S[1]);
;       }
;       __builtin_amdgcn_s_setprio(0);
;     }
;     { const bf16_t* vp_ = vtb + (size_t)(tid >> 3) * 8192 + jt * 64 + (tid & 7) * 8; vr0 = *(const uint4*)(vp_ + (size_t)0 * 8192); vr1 = *(const uint4*)(vp_ + (size_t)32 * 8192); vr2 = *(const uint4*)(vp_ + (size_t)64 * 8192); vr3 = *(const uint4*)(vp_ + (size_t)96 * 8192); }
.Lpvtop_skip_1:
	s_or_b64 exec, exec, s[100:101]
	v_lshl_add_u64 v[12:13], s[10:11], 1, v[200:201]
	v_add_co_u32_e32 v8, vcc, s78, v12
	s_nop 1
	v_addc_co_u32_e32 v9, vcc, 0, v13, vcc
	v_add_co_u32_e32 v14, vcc, 0x100000, v12
	global_load_dwordx4 v[4:7], v[12:13], off
	s_nop 0
	global_load_dwordx4 v[8:11], v[8:9], off
	v_addc_co_u32_e32 v15, vcc, 0, v13, vcc
	v_add_co_u32_e32 v12, vcc, 0x180000, v12
	s_nop 1
	v_addc_co_u32_e32 v13, vcc, 0, v13, vcc
	global_load_dwordx4 v[186:189], v[14:15], off
	s_nop 0
	global_load_dwordx4 v[12:15], v[12:13], off
	s_and_saveexec_b64 s[18:19], s[2:3]
	s_cbranch_execz .LBB0_520
	s_and_b64 s[24:25], s[16:17], exec
	v_xor_b32_e32 v18, 0x80000000, v202
	s_cselect_b32 s23, s9, s28
	s_setprio 1
	v_add3_u32 v243, s23, v199, v215
	ds_read_b128 v[244:247], v243
	ds_read_b128 v[248:251], v243 offset:12800
	ds_read_b128 v[252:255], v243 offset:32
	ds_read_b128 v[226:229], v243 offset:12832
	ds_read_b128 v[230:233], v243 offset:64
	v_mov_b32_e32 v19, v18
	v_mov_b32_e32 v20, v18
	v_mov_b32_e32 v21, v18
	v_mov_b32_e32 v22, v18
	v_mov_b32_e32 v23, v18
	v_mov_b32_e32 v24, v18
	v_mov_b32_e32 v25, v18
	v_mov_b32_e32 v26, v18
	v_mov_b32_e32 v27, v18
	v_mov_b32_e32 v28, v18
	v_mov_b32_e32 v29, v18
	v_mov_b32_e32 v30, v18
	v_mov_b32_e32 v31, v18
	v_mov_b32_e32 v32, v18
	v_mov_b32_e32 v33, v18
	s_waitcnt lgkmcnt(4)
	s_nop 0
	v_mfma_f32_32x32x16_bf16 v[34:49], v[244:247], v[114:117], v[18:33]
	ds_read_b128 v[244:247], v243 offset:12864
	s_waitcnt lgkmcnt(4)
	v_mfma_f32_32x32x16_bf16 v[18:33], v[248:251], v[114:117], v[18:33]
	ds_read_b128 v[248:251], v243 offset:96
	s_waitcnt lgkmcnt(4)
	v_mfma_f32_32x32x16_bf16 v[34:49], v[252:255], v[118:121], v[34:49]
	ds_read_b128 v[252:255], v243 offset:12896
	s_waitcnt lgkmcnt(4)
	v_mfma_f32_32x32x16_bf16 v[18:33], v[226:229], v[118:121], v[18:33]
	ds_read_b128 v[226:229], v243 offset:128
	s_waitcnt lgkmcnt(4)
	v_mfma_f32_32x32x16_bf16 v[34:49], v[230:233], v[122:125], v[34:49]
	ds_read_b128 v[230:233], v243 offset:12928
	s_waitcnt lgkmcnt(4)
	v_mfma_f32_32x32x16_bf16 v[18:33], v[244:247], v[122:125], v[18:33]
	ds_read_b128 v[244:247], v243 offset:160
	s_waitcnt lgkmcnt(4)
	v_mfma_f32_32x32x16_bf16 v[34:49], v[248:251], v[126:129], v[34:49]
	ds_read_b128 v[248:251], v243 offset:12960
	s_waitcnt lgkmcnt(4)
	v_mfma_f32_32x32x16_bf16 v[18:33], v[252:255], v[126:129], v[18:33]
	ds_read_b128 v[252:255], v243 offset:192
	s_waitcnt lgkmcnt(4)
	v_mfma_f32_32x32x16_bf16 v[34:49], v[226:229], v[130:133], v[34:49]
	ds_read_b128 v[226:229], v243 offset:12992
	s_waitcnt lgkmcnt(4)
	v_mfma_f32_32x32x16_bf16 v[18:33], v[230:233], v[130:133], v[18:33]
	ds_read_b128 v[230:233], v243 offset:224
	s_waitcnt lgkmcnt(4)
	v_mfma_f32_32x32x16_bf16 v[34:49], v[244:247], v[134:137], v[34:49]
	ds_read_b128 v[244:247], v243 offset:13024
	s_waitcnt lgkmcnt(4)
	v_mfma_f32_32x32x16_bf16 v[18:33], v[248:251], v[134:137], v[18:33]
	ds_read_b128 v[248:251], v243 offset:256
	s_waitcnt lgkmcnt(4)
	v_mfma_f32_32x32x16_bf16 v[34:49], v[252:255], v[138:141], v[34:49]
	ds_read_b128 v[252:255], v243 offset:13056
	s_waitcnt lgkmcnt(4)
	v_mfma_f32_32x32x16_bf16 v[18:33], v[226:229], v[138:141], v[18:33]
	ds_read_b128 v[226:229], v243 offset:288
	s_waitcnt lgkmcnt(4)
	v_mfma_f32_32x32x16_bf16 v[34:49], v[230:233], v[142:145], v[34:49]
	ds_read_b128 v[230:233], v243 offset:13088
	s_waitcnt lgkmcnt(4)
	v_mfma_f32_32x32x16_bf16 v[18:33], v[244:247], v[142:145], v[18:33]
	ds_read_b128 v[244:247], v243 offset:320
	s_waitcnt lgkmcnt(4)
	v_mfma_f32_32x32x16_bf16 v[34:49], v[248:251], v[146:149], v[34:49]
	ds_read_b128 v[248:251], v243 offset:13120
	s_waitcnt lgkmcnt(4)
	v_mfma_f32_32x32x16_bf16 v[18:33], v[252:255], v[146:149], v[18:33]
	ds_read_b128 v[252:255], v243 offset:352
	s_waitcnt lgkmcnt(4)
	v_mfma_f32_32x32x16_bf16 v[34:49], v[226:229], v[150:153], v[34:49]
	ds_read_b128 v[226:229], v243 offset:13152
	s_waitcnt lgkmcnt(4)
	v_mfma_f32_32x32x16_bf16 v[18:33], v[230:233], v[150:153], v[18:33]
	s_waitcnt lgkmcnt(3)
	v_mfma_f32_32x32x16_bf16 v[34:49], v[244:247], v[154:157], v[34:49]
	s_waitcnt lgkmcnt(2)
	v_mfma_f32_32x32x16_bf16 v[18:33], v[248:251], v[154:157], v[18:33]
	s_waitcnt lgkmcnt(1)
	v_mfma_f32_32x32x16_bf16 v[34:49], v[252:255], v[158:161], v[34:49]
	s_waitcnt lgkmcnt(0)
	v_mfma_f32_32x32x16_bf16 v[18:33], v[226:229], v[158:161], v[18:33]
	s_nop 11
	s_setprio 0
; DI int crow(int i, int h) { return (i & 3) + 8 * (i >> 2) + 4 * h; }
; DI void attn_unit(unsigned char* smem, const Params& P, int bh, int qb) {
;     ...
;     { const bf16_t* vp_ = vtb + (size_t)(tid >> 3) * 8192 + jt * 64 + (tid & 7) * 8; vr0 = *(const uint4*)(vp_ + (size_t)0 * 8192); vr1 = *(const uint4*)(vp_ + (size_t)32 * 8192); vr2 = *(const uint4*)(vp_ + (size_t)64 * 8192); vr3 = *(const uint4*)(vp_ + (size_t)96 * 8192); }
;     __builtin_amdgcn_sched_barrier(0);
;     if (active) {
;       if (jt >= ntiles - 2) {
; #pragma unroll
;         for (int kt = 0; kt < 2; ++kt)
; #pragma unroll
;           for (int i = 0; i < 16; ++i) { const int key = jt * 64 + kt * 32 + crow(i, hh); if (key > qrow) S[kt][i] = -1e30f; }
;       }
.LBB0_520:
	s_or_b64 exec, exec, s[18:19]
	s_barrier
	s_and_saveexec_b64 s[18:19], s[2:3]
	s_cbranch_execz .LBB0_526
	s_cmp_lt_u32 s22, s8
	s_cbranch_scc1 .LBB0_523
	v_add_u32_e32 v226, s21, v216
	v_add_u32_e32 v227, 64, v226
	v_cmp_le_i32_e32 vcc, v227, v196
	s_nop 1
	v_cndmask_b32_e32 v34, v213, v34, vcc
	v_cmp_lt_i32_e32 vcc, v227, v196
	v_add_u32_e32 v227, 0x42, v226
	s_nop 0
	v_cndmask_b32_e32 v35, v213, v35, vcc
	v_cmp_le_i32_e32 vcc, v227, v196
	v_add_u32_e32 v227, 0x43, v226
	s_nop 0
	v_cndmask_b32_e32 v36, v213, v36, vcc
	v_cmp_le_i32_e32 vcc, v227, v196
	v_add_u32_e32 v227, 0x48, v226
	s_nop 0
	v_cndmask_b32_e32 v37, v213, v37, vcc
	v_cmp_le_i32_e32 vcc, v227, v196
	v_add_u32_e32 v227, 0x49, v226
	s_nop 0
	v_cndmask_b32_e32 v38, v213, v38, vcc
	v_cmp_le_i32_e32 vcc, v227, v196
	v_add_u32_e32 v227, 0x4a, v226
	s_nop 0
	v_cndmask_b32_e32 v39, v213, v39, vcc
	v_cmp_le_i32_e32 vcc, v227, v196
	v_add_u32_e32 v227, 0x4b, v226
	s_nop 0
	v_cndmask_b32_e32 v40, v213, v40, vcc
	v_cmp_le_i32_e32 vcc, v227, v196
	v_add_u32_e32 v227, 0x50, v226
	s_nop 0
	v_cndmask_b32_e32 v41, v213, v41, vcc
	v_cmp_le_i32_e32 vcc, v227, v196
	v_add_u32_e32 v227, 0x51, v226
	s_nop 0
	v_cndmask_b32_e32 v42, v213, v42, vcc
	v_cmp_le_i32_e32 vcc, v227, v196
	v_add_u32_e32 v227, 0x52, v226
	s_nop 0
	v_cndmask_b32_e32 v43, v213, v43, vcc
	v_cmp_le_i32_e32 vcc, v227, v196
	v_add_u32_e32 v227, 0x53, v226
	s_nop 0
	v_cndmask_b32_e32 v44, v213, v44, vcc
	v_cmp_le_i32_e32 vcc, v227, v196
	v_add_u32_e32 v227, 0x58, v226
	s_nop 0
	v_cndmask_b32_e32 v45, v213, v45, vcc
	v_cmp_le_i32_e32 vcc, v227, v196
	v_add_u32_e32 v227, 0x59, v226
	s_nop 0
	v_cndmask_b32_e32 v46, v213, v46, vcc
	v_cmp_le_i32_e32 vcc, v227, v196
	v_add_u32_e32 v227, 0x5a, v226
	s_nop 0
	v_cndmask_b32_e32 v47, v213, v47, vcc
	v_cmp_le_i32_e32 vcc, v227, v196
	v_add_u32_e32 v227, 0x5b, v226
	s_nop 0
	v_cndmask_b32_e32 v48, v213, v48, vcc
	v_cmp_le_i32_e32 vcc, v227, v196
	v_add_u32_e32 v227, 0x60, v226
	s_nop 0
	v_cndmask_b32_e32 v49, v213, v49, vcc
	v_cmp_le_i32_e32 vcc, v227, v196
	v_add_u32_e32 v227, 0x61, v226
	s_nop 0
	v_cndmask_b32_e32 v18, v213, v18, vcc
	v_cmp_le_i32_e32 vcc, v227, v196
	v_add_u32_e32 v227, 0x62, v226
	s_nop 0
	v_cndmask_b32_e32 v19, v213, v19, vcc
	v_cmp_le_i32_e32 vcc, v227, v196
	v_add_u32_e32 v227, 0x63, v226
	s_nop 0
	v_cndmask_b32_e32 v20, v213, v20, vcc
	v_cmp_le_i32_e32 vcc, v227, v196
	v_add_u32_e32 v227, 0x68, v226
	s_nop 0
	v_cndmask_b32_e32 v21, v213, v21, vcc
	v_cmp_le_i32_e32 vcc, v227, v196
	v_add_u32_e32 v227, 0x69, v226
	s_nop 0
	v_cndmask_b32_e32 v22, v213, v22, vcc
	v_cmp_le_i32_e32 vcc, v227, v196
	v_add_u32_e32 v227, 0x6a, v226
	s_nop 0
	v_cndmask_b32_e32 v23, v213, v23, vcc
	v_cmp_le_i32_e32 vcc, v227, v196
	v_add_u32_e32 v227, 0x6b, v226
	s_nop 0
	v_cndmask_b32_e32 v24, v213, v24, vcc
	v_cmp_le_i32_e32 vcc, v227, v196
	v_add_u32_e32 v227, 0x70, v226
	s_nop 0
	v_cndmask_b32_e32 v25, v213, v25, vcc
	v_cmp_le_i32_e32 vcc, v227, v196
	v_add_u32_e32 v227, 0x71, v226
	s_nop 0
	v_cndmask_b32_e32 v26, v213, v26, vcc
	v_cmp_le_i32_e32 vcc, v227, v196
	v_add_u32_e32 v227, 0x72, v226
	s_nop 0
	v_cndmask_b32_e32 v27, v213, v27, vcc
	v_cmp_le_i32_e32 vcc, v227, v196
	v_add_u32_e32 v227, 0x73, v226
	s_nop 0
	v_cndmask_b32_e32 v28, v213, v28, vcc
	v_cmp_le_i32_e32 vcc, v227, v196
	v_add_u32_e32 v227, 0x78, v226
	s_nop 0
	v_cndmask_b32_e32 v29, v213, v29, vcc
	v_cmp_le_i32_e32 vcc, v227, v196
	v_add_u32_e32 v227, 0x79, v226
	s_nop 0
	v_cndmask_b32_e32 v30, v213, v30, vcc
	v_cmp_le_i32_e32 vcc, v227, v196
	v_add_u32_e32 v227, 0x7a, v226
	v_add_u32_e32 v226, 0x7b, v226
	v_cndmask_b32_e32 v31, v213, v31, vcc
	v_cmp_le_i32_e32 vcc, v227, v196
	s_nop 1
	v_cndmask_b32_e32 v32, v213, v32, vcc
	v_cmp_le_i32_e32 vcc, v226, v196
	s_nop 1
	v_cndmask_b32_e32 v33, v213, v33, vcc

; #define MFMA32(a, b, c) __builtin_amdgcn_mfma_f32_32x32x16_bf16((a), (b), (c), 0, 0, 0)
; DI void attn_unit(unsigned char* smem, const Params& P, int bh, int qb) {
;     ...
;     __syncthreads();
;     if (active) {
;       __builtin_amdgcn_s_setprio(1);
; #pragma unroll
;       for (int kt = 0; kt < 2; ++kt)
; #pragma unroll
;         for (int s2 = 0; s2 < 2; ++s2) {
;           uint4 pp; pp.x = pk2(S[kt][8 * s2], S[kt][8 * s2 + 1]); pp.y = pk2(S[kt][8 * s2 + 2], S[kt][8 * s2 + 3]);
;           pp.z = pk2(S[kt][8 * s2 + 4], S[kt][8 * s2 + 5]); pp.w = pk2(S[kt][8 * s2 + 6], S[kt][8 * s2 + 7]);
;           const bf16x8 pb = __builtin_bit_cast(bf16x8, pp);
; #pragma unroll
;           for (int d = 0; d < 4; ++d) {
;             const bf16x8 vf = *(const bf16x8*)(sV + (d * 32 + l31) * LDK + kt * 32 + s2 * 16 + hh * 8);
;             O[d] = MFMA32(vf, pb, O[d]);
;           }
;         }
;       __builtin_amdgcn_s_setprio(0);
;     }
;     __syncthreads();
; DI void run_phase(unsigned char* smem_in, const Params& P, int ph) {
;     ...
;           attn_unit(smem, P, bh, 63 - j);
;           attn_unit(smem, P, bh, j);
;         }
.LBB0_528:
	s_waitcnt lgkmcnt(0)
	s_barrier
	s_add_i32 s20, s20, 1
	s_cmp_lg_u32 s85, s20
	v_lshl_add_u64 v[16:17], v[16:17], 0, s[40:41]
	s_cbranch_scc0 .LBB0_532
	s_mov_b32 s21, s10
	s_branch .LBB0_516
.LBB0_532:
	s_and_saveexec_b64 s[100:101], s[2:3]
	s_cbranch_execz .Lpvexit_skip_1
	s_setprio 1
	ds_read_b128 v[12:15], v222 offset:25600
	ds_read_b128 v[186:189], v223 offset:25600
	ds_read_b128 v[226:229], v224 offset:25600
	ds_read_b128 v[230:233], v225 offset:25600
	ds_read_b128 v[244:247], v222 offset:25632
	ds_read_b128 v[248:251], v223 offset:25632
	ds_read_b128 v[252:255], v224 offset:25632
	v_cvt_pk_bf16_f32 v8, v34, v35
	v_cvt_pk_bf16_f32 v9, v36, v37
	v_cvt_pk_bf16_f32 v10, v38, v39
	v_cvt_pk_bf16_f32 v11, v40, v41
	v_cvt_pk_bf16_f32 v4, v42, v43
	v_cvt_pk_bf16_f32 v5, v44, v45
	v_cvt_pk_bf16_f32 v6, v46, v47
	v_cvt_pk_bf16_f32 v7, v48, v49
	s_waitcnt lgkmcnt(6)
	v_mfma_f32_32x32x16_bf16 v[98:113], v[12:15], v[8:11], v[98:113]
	ds_read_b128 v[12:15], v225 offset:25632
	s_waitcnt lgkmcnt(6)
	v_mfma_f32_32x32x16_bf16 v[82:97], v[186:189], v[8:11], v[82:97]
	ds_read_b128 v[186:189], v222 offset:25664
	s_waitcnt lgkmcnt(6)
	v_mfma_f32_32x32x16_bf16 v[66:81], v[226:229], v[8:11], v[66:81]
	ds_read_b128 v[226:229], v223 offset:25664
	s_waitcnt lgkmcnt(6)
	v_mfma_f32_32x32x16_bf16 v[50:65], v[230:233], v[8:11], v[50:65]
	ds_read_b128 v[230:233], v224 offset:25664
	s_waitcnt lgkmcnt(6)
	v_mfma_f32_32x32x16_bf16 v[98:113], v[244:247], v[4:7], v[98:113]
	ds_read_b128 v[244:247], v225 offset:25664
	v_cvt_pk_bf16_f32 v8, v18, v19
	v_cvt_pk_bf16_f32 v9, v20, v21
	v_cvt_pk_bf16_f32 v10, v22, v23
	v_cvt_pk_bf16_f32 v11, v24, v25
	s_waitcnt lgkmcnt(6)
	v_mfma_f32_32x32x16_bf16 v[82:97], v[248:251], v[4:7], v[82:97]
	ds_read_b128 v[248:251], v222 offset:25696
	s_waitcnt lgkmcnt(6)
	v_mfma_f32_32x32x16_bf16 v[66:81], v[252:255], v[4:7], v[66:81]
	ds_read_b128 v[252:255], v223 offset:25696
	s_waitcnt lgkmcnt(6)
	v_mfma_f32_32x32x16_bf16 v[50:65], v[12:15], v[4:7], v[50:65]
	ds_read_b128 v[12:15], v224 offset:25696
	s_waitcnt lgkmcnt(6)
	v_mfma_f32_32x32x16_bf16 v[98:113], v[186:189], v[8:11], v[98:113]
	ds_read_b128 v[186:189], v225 offset:25696
	v_cvt_pk_bf16_f32 v4, v26, v27
	v_cvt_pk_bf16_f32 v5, v28, v29
	v_cvt_pk_bf16_f32 v6, v30, v31
	v_cvt_pk_bf16_f32 v7, v32, v33
	s_waitcnt lgkmcnt(6)
	v_mfma_f32_32x32x16_bf16 v[82:97], v[226:229], v[8:11], v[82:97]
	s_waitcnt lgkmcnt(5)
	v_mfma_f32_32x32x16_bf16 v[66:81], v[230:233], v[8:11], v[66:81]
	s_waitcnt lgkmcnt(4)
	v_mfma_f32_32x32x16_bf16 v[50:65], v[244:247], v[8:11], v[50:65]
	s_waitcnt lgkmcnt(3)
	v_mfma_f32_32x32x16_bf16 v[98:113], v[248:251], v[4:7], v[98:113]
	s_waitcnt lgkmcnt(2)
	v_mfma_f32_32x32x16_bf16 v[82:97], v[252:255], v[4:7], v[82:97]
	s_waitcnt lgkmcnt(1)
	v_mfma_f32_32x32x16_bf16 v[66:81], v[12:15], v[4:7], v[66:81]
	s_waitcnt lgkmcnt(0)
	v_mfma_f32_32x32x16_bf16 v[50:65], v[186:189], v[4:7], v[50:65]
	s_setprio 0
	s_nop 7
	s_nop 7
.Lpvexit_skip_1:
	s_or_b64 exec, exec, s[100:101]
	s_cmp_lg_u32 s9, 0
	s_cbranch_scc1 .Lstag_out_1
	s_barrier

; DI void attn_unit(unsigned char* smem, const Params& P, int bh, int qb) {
;   const int tid = TID(), lane = tid & 63, w = tid >> 6, l31 = lane & 31, hh = lane >> 5;
;   bf16_t* sK = (bf16_t*)smem;
;   bf16_t* sV = sK + 64 * KLD;
;   const bf16_t* qbuf = (const bf16_t*)(P.ws + OFF_Q) + (size_t)bh * 8192 * 192;
;   bf16_t* obuf = (bf16_t*)(P.ws + OFF_MIX) + ((size_t)(bh >> 2) * 8192) * 1024 + (bh & 3) * 128;
;   const bf16_t* kbuf = (const bf16_t*)(P.ws + OFF_K) + (size_t)bh * 8192 * 192;
;   const bf16_t* vtb = (const bf16_t*)(P.ws + OFF_VT) + (size_t)bh * 128 * 8192;
;   const int q0 = qb * 128, qrow = q0 + 32 * w + l31;
;   bf16x8 qf[12];
; #pragma unroll
;   for (int ks = 0; ks < 12; ++ks) qf[ks] = *(const bf16x8*)(qbuf + (size_t)qrow * 192 + ks * 16 + hh * 8);
;   f32x16 O[4];
; #pragma unroll
;   for (int d = 0; d < 4; ++d)
; #pragma unroll
;     for (int i = 0; i < 16; ++i) O[d][i] = 0.f;
;   float mrun = -1e30f, lrun = 0.f;
;   const int ntiles = 2 * qb + 2;
;   bf16_t* sK1 = sV + 128 * LDK;
;   uint4 kr0, kr1, kr2, kr3, kr4, kr5, vr0, vr1, vr2, vr3;
;   const int kgo = (tid >> 2) * 192 + (tid & 3) * 8, klo = (tid >> 2) * KLD + (tid & 3) * 8;
;   __syncthreads();
;   kr0 = *(const uint4*)(kbuf + kgo + 0); kr1 = *(const uint4*)(kbuf + kgo + 32); kr2 = *(const uint4*)(kbuf + kgo + 64); kr3 = *(const uint4*)(kbuf + kgo + 96); kr4 = *(const uint4*)(kbuf + kgo + 128); kr5 = *(const uint4*)(kbuf + kgo + 160);
;   *(uint4*)(sK + klo + 0) = kr0; *(uint4*)(sK + klo + 32) = kr1; *(uint4*)(sK + klo + 64) = kr2; *(uint4*)(sK + klo + 96) = kr3; *(uint4*)(sK + klo + 128) = kr4; *(uint4*)(sK + klo + 160) = kr5;
;   __syncthreads();
;   for (int jt = 0; jt < ntiles; ++jt) {
;     const bf16_t* cK = (jt & 1) ? sK1 : sK;
;     bf16_t* nK = (jt & 1) ? sK : sK1;
;     const bool more = (jt + 1 < ntiles);
;     const bool active = (jt * 64 <= q0 + 32 * w + 31);
;     if (more) {
;       const bf16_t* kp = kbuf + (size_t)(jt + 1) * 64 * 192;
;       kr0 = *(const uint4*)(kp + kgo + 0); kr1 = *(const uint4*)(kp + kgo + 32); kr2 = *(const uint4*)(kp + kgo + 64); kr3 = *(const uint4*)(kp + kgo + 96); kr4 = *(const uint4*)(kp + kgo + 128); kr5 = *(const uint4*)(kp + kgo + 160);
;     }
;     __builtin_amdgcn_sched_barrier(0);
;     f32x16 S[2];
;     const float sref = (jt == 0) ? 0.f : mrun;
;     if (active) {
; #pragma unroll
;       for (int a = 0; a < 2; ++a)
.LBB0_1393:
	s_cmpk_gt_i32 s85, 0xff
	s_mov_b64 s[0:1], -1
	s_cbranch_scc0 .LBB0_1458
	s_cmpk_gt_u32 s85, 0x10f
	s_cbranch_scc0 .LBB0_1454
	s_cmp_eq_u32 s9, 0
	s_cbranch_scc1 .Lstag_in_2
	s_barrier
.Lstag_in_2:
	s_add_i32 s96, s85, 0xfffffef0
	s_and_b32 s8, s85, 15
	s_lshr_b32 s93, s96, 4
	v_mov_b32_e32 v4, v1
	s_sub_i32 s10, 63, s93
	s_mul_i32 s0, s8, 0x300000
	v_ashrrev_i32_e32 v2, 1, v4
	s_add_u32 s60, s29, s0
	v_and_b32_e32 v2, 0xffffffe0, v2
	v_and_b32_e32 v176, 31, v4
	s_addc_u32 s61, s64, 0
	v_lshl_add_u32 v175, s10, 7, v2
	v_bfe_u32 v174, v4, 5, 1
	v_or_b32_e32 v188, v175, v176
	v_mov_b64_e32 v[6:7], s[60:61]
	s_add_u32 s58, s65, s0
	v_mad_i64_i32 v[6:7], s[0:1], v188, s75, v[6:7]
	v_lshlrev_b32_e32 v2, 4, v174
	v_lshl_add_u64 v[6:7], v[6:7], 0, v[2:3]
	v_ashrrev_i32_e32 v5, 2, v4
	v_lshlrev_b32_e32 v70, 3, v4
	global_load_dwordx4 v[100:103], v[6:7], off
	global_load_dwordx4 v[104:107], v[6:7], off offset:32
	global_load_dwordx4 v[108:111], v[6:7], off offset:64
	global_load_dwordx4 v[112:115], v[6:7], off offset:96
	global_load_dwordx4 v[116:119], v[6:7], off offset:128
	global_load_dwordx4 v[120:123], v[6:7], off offset:160
	global_load_dwordx4 v[124:127], v[6:7], off offset:192
	global_load_dwordx4 v[128:131], v[6:7], off offset:224
	global_load_dwordx4 v[132:135], v[6:7], off offset:256
	global_load_dwordx4 v[136:139], v[6:7], off offset:288
	global_load_dwordx4 v[140:143], v[6:7], off offset:320
	global_load_dwordx4 v[144:147], v[6:7], off offset:352
	v_mul_lo_u32 v6, v5, s76
	v_and_b32_e32 v2, 24, v70
	v_or_b32_e32 v172, v6, v2
	s_addc_u32 s59, s66, 0
	v_ashrrev_i32_e32 v173, 31, v172
	v_lshl_add_u64 v[30:31], v[172:173], 1, s[58:59]
	s_waitcnt vmcnt(0)
	s_barrier
	global_load_dwordx4 v[6:9], v[30:31], off
	global_load_dwordx4 v[10:13], v[30:31], off offset:64
	global_load_dwordx4 v[14:17], v[30:31], off offset:128
	global_load_dwordx4 v[18:21], v[30:31], off offset:192
	global_load_dwordx4 v[22:25], v[30:31], off offset:256
	global_load_dwordx4 v[26:29], v[30:31], off offset:320
	s_movk_i32 s2, 0x6000
	v_mad_u64_u32 v[196:197], s[0:1], v5, s77, v[2:3]
	v_add_co_u32_e32 v30, vcc, s2, v30
	v_lshl_add_u32 v71, v196, 1, s9
	s_nop 0
	v_addc_co_u32_e32 v31, vcc, 0, v31, vcc
	v_lshlrev_b32_e32 v72, 3, v174
	v_cmp_lt_i32_e64 s[2:3], -1, v175
	v_mul_u32_u24_e32 v2, 0xc8, v176
	s_waitcnt vmcnt(5)
	ds_write_b128 v71, v[6:9]
	s_waitcnt vmcnt(4)
	ds_write_b128 v71, v[10:13] offset:64
	s_waitcnt vmcnt(3)
	ds_write_b128 v71, v[14:17] offset:128
	s_waitcnt vmcnt(2)
	ds_write_b128 v71, v[18:21] offset:192
	s_waitcnt vmcnt(1)
	ds_write_b128 v71, v[22:25] offset:256
	s_waitcnt vmcnt(0)
	ds_write_b128 v71, v[26:29] offset:320
	s_waitcnt lgkmcnt(0)
	s_barrier
	global_load_dwordx4 v[148:151], v[30:31], off
	global_load_dwordx4 v[152:155], v[30:31], off offset:64
	global_load_dwordx4 v[156:159], v[30:31], off offset:128
	global_load_dwordx4 v[160:163], v[30:31], off offset:192
	global_load_dwordx4 v[164:167], v[30:31], off offset:256
	global_load_dwordx4 v[168:171], v[30:31], off offset:320
	v_mov_b32_e32 v215, 0
	v_lshlrev_b32_e32 v197, 1, v2
	v_lshlrev_b32_e32 v201, 1, v72
	v_mov_b32_e32 v36, 0
	v_mov_b32_e32 v37, 0
	v_mov_b32_e32 v38, 0
	v_mov_b32_e32 v39, 0
	v_mov_b32_e32 v40, 0
	v_mov_b32_e32 v41, 0
	v_mov_b32_e32 v42, 0
	v_mov_b32_e32 v43, 0
	v_mov_b32_e32 v44, 0
	v_mov_b32_e32 v45, 0
	v_mov_b32_e32 v46, 0
	v_mov_b32_e32 v47, 0
	v_mov_b32_e32 v48, 0
	v_mov_b32_e32 v49, 0
	v_mov_b32_e32 v50, 0
	v_mov_b32_e32 v51, 0
	v_mov_b32_e32 v20, 0
	v_mov_b32_e32 v21, 0
	v_mov_b32_e32 v22, 0
	v_mov_b32_e32 v23, 0
	v_mov_b32_e32 v24, 0
	v_mov_b32_e32 v25, 0
	v_mov_b32_e32 v26, 0
	v_mov_b32_e32 v27, 0
	v_mov_b32_e32 v28, 0
	v_mov_b32_e32 v29, 0
	v_mov_b32_e32 v30, 0
	v_mov_b32_e32 v31, 0
	v_mov_b32_e32 v32, 0
	v_mov_b32_e32 v33, 0
	v_mov_b32_e32 v34, 0
	v_mov_b32_e32 v35, 0
	s_and_saveexec_b64 s[0:1], s[2:3]
	s_cbranch_execz .LBB0_1397
	s_setprio 1
	v_add3_u32 v2, s9, v197, v201
	ds_read_b128 v[6:9], v2
	s_mov_b32 s26, s12
	s_mov_b32 s27, s12
	s_mov_b32 s13, s12
	s_mov_b32 s14, s12
	s_mov_b32 s15, s12
	s_mov_b32 s16, s12
	s_mov_b32 s17, s12
	s_mov_b32 s18, s12
	s_mov_b32 s19, s12
	s_mov_b32 s20, s12
	s_mov_b32 s21, s12
	s_mov_b32 s22, s12
	s_mov_b32 s23, s12
	s_mov_b32 s24, s12
	s_mov_b32 s25, s12
	v_mov_b64_e32 v[34:35], s[26:27]
	v_mov_b64_e32 v[32:33], s[24:25]
	v_mov_b64_e32 v[30:31], s[22:23]
	v_mov_b64_e32 v[28:29], s[20:21]
	v_mov_b64_e32 v[26:27], s[18:19]
	v_mov_b64_e32 v[24:25], s[16:17]
	v_mov_b64_e32 v[22:23], s[14:15]
	v_mov_b64_e32 v[20:21], s[12:13]
	s_waitcnt lgkmcnt(0)
	s_nop 0
	v_mfma_f32_32x32x16_bf16 v[36:51], v[6:9], v[100:103], v[20:35]
	ds_read_b128 v[6:9], v2 offset:12800
	s_waitcnt lgkmcnt(0)
	v_mfma_f32_32x32x16_bf16 v[20:35], v[6:9], v[100:103], v[20:35]
	ds_read_b128 v[6:9], v2 offset:32
	s_waitcnt lgkmcnt(0)
	v_mfma_f32_32x32x16_bf16 v[36:51], v[6:9], v[104:107], v[36:51]
	ds_read_b128 v[6:9], v2 offset:12832
	s_waitcnt lgkmcnt(0)
	v_mfma_f32_32x32x16_bf16 v[20:35], v[6:9], v[104:107], v[20:35]
	ds_read_b128 v[6:9], v2 offset:64
	s_waitcnt lgkmcnt(0)
	v_mfma_f32_32x32x16_bf16 v[36:51], v[6:9], v[108:111], v[36:51]
	ds_read_b128 v[6:9], v2 offset:12864
	s_waitcnt lgkmcnt(0)
	v_mfma_f32_32x32x16_bf16 v[20:35], v[6:9], v[108:111], v[20:35]
	ds_read_b128 v[6:9], v2 offset:96
	s_waitcnt lgkmcnt(0)
	v_mfma_f32_32x32x16_bf16 v[36:51], v[6:9], v[112:115], v[36:51]
	ds_read_b128 v[6:9], v2 offset:12896
	s_waitcnt lgkmcnt(0)
	v_mfma_f32_32x32x16_bf16 v[20:35], v[6:9], v[112:115], v[20:35]
	ds_read_b128 v[6:9], v2 offset:128
	s_waitcnt lgkmcnt(0)
	v_mfma_f32_32x32x16_bf16 v[36:51], v[6:9], v[116:119], v[36:51]
	ds_read_b128 v[6:9], v2 offset:12928
	s_waitcnt lgkmcnt(0)
; DI float xmax32(float x) { auto r = __builtin_amdgcn_permlane32_swap(__float_as_uint(x), __float_as_uint(x), false, false); return fmaxf(__uint_as_float(r[0]), __uint_as_float(r[1])); }
; DI int crow(int i, int h) { return (i & 3) + 8 * (i >> 2) + 4 * h; }
; DI void attn_unit(unsigned char* smem, const Params& P, int bh, int qb) {
;     ...
;     if (active) {
; #pragma unroll
;       for (int a = 0; a < 2; ++a)
; #pragma unroll
;         for (int i = 0; i < 16; ++i) S[a][i] = -sref;
;       __builtin_amdgcn_s_setprio(1);
; #pragma unroll
;       for (int ks = 0; ks < 12; ++ks) {
;         const bf16x8 a0 = *(const bf16x8*)(cK + l31 * KLD + ks * 16 + hh * 8), a1 = *(const bf16x8*)(cK + (32 + l31) * KLD + ks * 16 + hh * 8);
;         S[0] = MFMA32(a0, qf[ks], S[0]); S[1] = MFMA32(a1, qf[ks], S[1]);
;       }
;       __builtin_amdgcn_s_setprio(0);
;     }
;     { const bf16_t* vp_ = vtb + (size_t)(tid >> 3) * 8192 + jt * 64 + (tid & 7) * 8; vr0 = *(const uint4*)(vp_ + (size_t)0 * 8192); vr1 = *(const uint4*)(vp_ + (size_t)32 * 8192); vr2 = *(const uint4*)(vp_ + (size_t)64 * 8192); vr3 = *(const uint4*)(vp_ + (size_t)96 * 8192); }
;     __builtin_amdgcn_sched_barrier(0);
;     if (active) {
;       if (jt >= ntiles - 2) {
; #pragma unroll
;         for (int kt = 0; kt < 2; ++kt)
; #pragma unroll
;           for (int i = 0; i < 16; ++i) { const int key = jt * 64 + kt * 32 + crow(i, hh); if (key > qrow) S[kt][i] = -1e30f; }
;       }
;       float mx = S[0][0];
; #pragma unroll
;       for (int i = 1; i < 16; ++i) mx = fmaxf(mx, S[0][i]);
; #pragma unroll
;       for (int i = 0; i < 16; ++i) mx = fmaxf(mx, S[1][i]);
;       mx = xmax32(mx);
;       if (!__all(mx - (mrun - sref) <= 8.0f)) {
;         const float mnew = fmaxf(mrun, mx + sref), alpha = __builtin_amdgcn_exp2f(mrun - mnew), shift = mnew - sref;
;         mrun = mnew; lrun *= alpha;
; #pragma unroll
;         for (int d = 0; d < 4; ++d)
; #pragma unroll
;           for (int i = 0; i < 16; ++i) O[d][i] *= alpha;
; #pragma unroll
;         for (int kt = 0; kt < 2; ++kt)
; #pragma unroll
;           for (int i = 0; i < 16; ++i) S[kt][i] -= shift;
;       }
;       float ls = 0.f;
; #pragma unroll
;       for (int kt = 0; kt < 2; ++kt)
; #pragma unroll
;         for (int i = 0; i < 16; ++i) { const float p = __builtin_amdgcn_exp2f(S[kt][i]); S[kt][i] = p; ls += p; }
;       lrun += ls;
	v_mfma_f32_32x32x16_bf16 v[20:35], v[6:9], v[116:119], v[20:35]
	ds_read_b128 v[6:9], v2 offset:160
	s_waitcnt lgkmcnt(0)
	v_mfma_f32_32x32x16_bf16 v[36:51], v[6:9], v[120:123], v[36:51]
	ds_read_b128 v[6:9], v2 offset:12960
	s_waitcnt lgkmcnt(0)
	v_mfma_f32_32x32x16_bf16 v[20:35], v[6:9], v[120:123], v[20:35]
	ds_read_b128 v[6:9], v2 offset:192
	s_waitcnt lgkmcnt(0)
	v_mfma_f32_32x32x16_bf16 v[36:51], v[6:9], v[124:127], v[36:51]
	ds_read_b128 v[6:9], v2 offset:12992
	s_waitcnt lgkmcnt(0)
	v_mfma_f32_32x32x16_bf16 v[20:35], v[6:9], v[124:127], v[20:35]
	ds_read_b128 v[6:9], v2 offset:224
	s_waitcnt lgkmcnt(0)
	v_mfma_f32_32x32x16_bf16 v[36:51], v[6:9], v[128:131], v[36:51]
	ds_read_b128 v[6:9], v2 offset:13024
	s_waitcnt lgkmcnt(0)
	v_mfma_f32_32x32x16_bf16 v[20:35], v[6:9], v[128:131], v[20:35]
	ds_read_b128 v[6:9], v2 offset:256
	s_waitcnt lgkmcnt(0)
	v_mfma_f32_32x32x16_bf16 v[36:51], v[6:9], v[132:135], v[36:51]
	ds_read_b128 v[6:9], v2 offset:13056
	s_waitcnt lgkmcnt(0)
	v_mfma_f32_32x32x16_bf16 v[20:35], v[6:9], v[132:135], v[20:35]
	ds_read_b128 v[6:9], v2 offset:288
	s_waitcnt lgkmcnt(0)
	v_mfma_f32_32x32x16_bf16 v[36:51], v[6:9], v[136:139], v[36:51]
	ds_read_b128 v[6:9], v2 offset:13088
	s_waitcnt lgkmcnt(0)
	v_mfma_f32_32x32x16_bf16 v[20:35], v[6:9], v[136:139], v[20:35]
	ds_read_b128 v[6:9], v2 offset:320
	s_waitcnt lgkmcnt(0)
	v_mfma_f32_32x32x16_bf16 v[36:51], v[6:9], v[140:143], v[36:51]
	ds_read_b128 v[6:9], v2 offset:13120
	s_waitcnt lgkmcnt(0)
	v_mfma_f32_32x32x16_bf16 v[20:35], v[6:9], v[140:143], v[20:35]
	ds_read_b128 v[6:9], v2 offset:352
	s_waitcnt lgkmcnt(0)
	v_mfma_f32_32x32x16_bf16 v[36:51], v[6:9], v[144:147], v[36:51]
	ds_read_b128 v[6:9], v2 offset:13152
	s_waitcnt lgkmcnt(0)
	v_mfma_f32_32x32x16_bf16 v[20:35], v[6:9], v[144:147], v[20:35]
	s_setprio 0
.LBB0_1397:
	s_or_b64 exec, exec, s[0:1]
	s_barrier
	s_lshl_b32 s0, s8, 21
	v_ashrrev_i32_e32 v68, 3, v4
	s_add_u32 s62, s67, s0
	v_ashrrev_i32_e32 v69, 31, v68
	s_addc_u32 s63, s68, 0
	v_lshlrev_b64 v[4:5], 14, v[68:69]
	v_and_b32_e32 v2, 56, v70
	v_lshl_add_u64 v[4:5], s[62:63], 0, v[4:5]
	v_lshlrev_b32_e32 v2, 1, v2
	v_lshl_add_u64 v[198:199], v[4:5], 0, v[2:3]
	v_add_co_u32_e32 v4, vcc, s78, v198
	s_nop 1
	v_addc_co_u32_e32 v5, vcc, 0, v199, vcc
	global_load_dwordx4 v[52:55], v[198:199], off
	global_load_dwordx4 v[56:59], v[4:5], off
	v_add_co_u32_e32 v4, vcc, s79, v198
	s_nop 1
	v_addc_co_u32_e32 v5, vcc, 0, v199, vcc
	v_add_co_u32_e32 v6, vcc, s80, v198
	s_nop 1
	v_addc_co_u32_e32 v7, vcc, 0, v199, vcc
	global_load_dwordx4 v[60:63], v[4:5], off
	global_load_dwordx4 v[64:67], v[6:7], off
	v_mov_b32_e32 v4, v3
	v_mov_b32_e32 v5, v3
	v_mov_b32_e32 v6, v3
	v_mov_b32_e32 v7, v3
	v_mov_b32_e32 v8, v3
	v_mov_b32_e32 v9, v3
	v_mov_b32_e32 v10, v3
	v_mov_b32_e32 v11, v3
	v_mov_b32_e32 v12, v3
	v_mov_b32_e32 v13, v3
	v_mov_b32_e32 v14, v3
	v_mov_b32_e32 v15, v3
	v_mov_b32_e32 v16, v3
	v_mov_b32_e32 v17, v3
	v_mov_b32_e32 v2, v3
	v_mov_b64_e32 v[18:19], v[16:17]
	v_mov_b32_e32 v200, 0xf149f2ca
	v_mov_b64_e32 v[16:17], v[14:15]
	v_mov_b64_e32 v[14:15], v[12:13]
	v_mov_b64_e32 v[12:13], v[10:11]
	v_mov_b64_e32 v[10:11], v[8:9]
	v_mov_b64_e32 v[8:9], v[6:7]
	v_mov_b64_e32 v[6:7], v[4:5]
	v_mov_b64_e32 v[4:5], v[2:3]
	s_and_saveexec_b64 s[0:1], s[2:3]
	s_cbranch_execz .LBB0_1402
	v_max_f32_e32 v2, v37, v37
	v_max_f32_e32 v4, v36, v36
	v_max_f32_e32 v2, v4, v2
	v_max3_f32 v2, v2, v38, v39
	v_max3_f32 v2, v2, v40, v41
	v_max3_f32 v2, v2, v42, v43
	v_max3_f32 v2, v2, v44, v45
	v_max3_f32 v2, v2, v46, v47
	v_max3_f32 v2, v2, v48, v49
	v_max3_f32 v2, v2, v50, v51
	v_max3_f32 v2, v2, v20, v21
	v_max3_f32 v2, v2, v22, v23
	v_max3_f32 v2, v2, v24, v25
	v_max3_f32 v2, v2, v26, v27
	v_max3_f32 v2, v2, v28, v29
	v_max3_f32 v2, v2, v30, v31
	v_max3_f32 v2, v2, v32, v33
	v_max3_f32 v2, v2, v34, v35
	v_mov_b32_e32 v4, v2
	s_nop 1
	v_permlane32_swap_b32_e32 v2, v4
	v_max_f32_e32 v4, v4, v4
	v_max_f32_e32 v2, v2, v2
	v_max_f32_e32 v2, v2, v4
	v_add_f32_e32 v4, 0x7149f2ca, v2
	v_cmp_ge_f32_e32 vcc, s81, v4
	s_cmp_eq_u64 vcc, exec
	s_cbranch_scc1 .LBB0_1400
	v_add_f32_e32 v2, 0, v2
	v_max_f32_e32 v200, 0xf149f2ca, v2
	v_sub_f32_e32 v2, 0xf149f2ca, v200
	v_exp_f32_e32 v2, v2
	v_pk_add_f32 v[36:37], v[36:37], v[200:201] op_sel_hi:[1,0] neg_lo:[0,1] neg_hi:[0,1]
	v_pk_add_f32 v[38:39], v[38:39], v[200:201] op_sel_hi:[1,0] neg_lo:[0,1] neg_hi:[0,1]
	v_pk_add_f32 v[40:41], v[40:41], v[200:201] op_sel_hi:[1,0] neg_lo:[0,1] neg_hi:[0,1]
	v_mul_f32_e32 v4, 0, v2
	v_mov_b32_e32 v5, v4
	v_mov_b32_e32 v6, v4
	v_mov_b32_e32 v7, v4
	v_mov_b32_e32 v8, v4
	v_mov_b32_e32 v9, v4
	v_mov_b32_e32 v10, v4
	v_mov_b32_e32 v11, v4
	v_mov_b32_e32 v12, v4
	v_mov_b32_e32 v13, v4
	v_mov_b32_e32 v14, v4
	v_mov_b32_e32 v15, v4
	v_mov_b32_e32 v16, v4
	v_mov_b32_e32 v17, v4
	v_mov_b32_e32 v18, v4
	v_mov_b32_e32 v19, v4
	v_pk_add_f32 v[42:43], v[42:43], v[200:201] op_sel_hi:[1,0] neg_lo:[0,1] neg_hi:[0,1]
	v_pk_add_f32 v[44:45], v[44:45], v[200:201] op_sel_hi:[1,0] neg_lo:[0,1] neg_hi:[0,1]
	v_pk_add_f32 v[46:47], v[46:47], v[200:201] op_sel_hi:[1,0] neg_lo:[0,1] neg_hi:[0,1]
	v_pk_add_f32 v[48:49], v[48:49], v[200:201] op_sel_hi:[1,0] neg_lo:[0,1] neg_hi:[0,1]
	v_pk_add_f32 v[50:51], v[50:51], v[200:201] op_sel_hi:[1,0] neg_lo:[0,1] neg_hi:[0,1]
	v_pk_add_f32 v[20:21], v[20:21], v[200:201] op_sel_hi:[1,0] neg_lo:[0,1] neg_hi:[0,1]
	v_pk_add_f32 v[22:23], v[22:23], v[200:201] op_sel_hi:[1,0] neg_lo:[0,1] neg_hi:[0,1]
	v_pk_add_f32 v[24:25], v[24:25], v[200:201] op_sel_hi:[1,0] neg_lo:[0,1] neg_hi:[0,1]
	v_pk_add_f32 v[26:27], v[26:27], v[200:201] op_sel_hi:[1,0] neg_lo:[0,1] neg_hi:[0,1]
	v_pk_add_f32 v[28:29], v[28:29], v[200:201] op_sel_hi:[1,0] neg_lo:[0,1] neg_hi:[0,1]
	v_pk_add_f32 v[30:31], v[30:31], v[200:201] op_sel_hi:[1,0] neg_lo:[0,1] neg_hi:[0,1]
	v_pk_add_f32 v[32:33], v[32:33], v[200:201] op_sel_hi:[1,0] neg_lo:[0,1] neg_hi:[0,1]
	v_pk_add_f32 v[34:35], v[34:35], v[200:201] op_sel_hi:[1,0] neg_lo:[0,1] neg_hi:[0,1]
	v_mov_b32_e32 v69, v4
	s_branch .LBB0_1401

; DI void attn_unit(unsigned char* smem, const Params& P, int bh, int qb) {
;     ...
;     { bf16_t* vq_ = sV + (tid >> 3) * LDK + ((tid & 7) >> 1) * 16 + (tid & 1) * 4;
;       *(uint2*)(vq_) = make_uint2(vr0.x, vr0.y); *(uint2*)(vq_ + 8) = make_uint2(vr0.z, vr0.w);
;       *(uint2*)(vq_ + 32 * LDK) = make_uint2(vr1.x, vr1.y); *(uint2*)(vq_ + 32 * LDK + 8) = make_uint2(vr1.z, vr1.w);
;       *(uint2*)(vq_ + 64 * LDK) = make_uint2(vr2.x, vr2.y); *(uint2*)(vq_ + 64 * LDK + 8) = make_uint2(vr2.z, vr2.w);
;       *(uint2*)(vq_ + 96 * LDK) = make_uint2(vr3.x, vr3.y); *(uint2*)(vq_ + 96 * LDK + 8) = make_uint2(vr3.z, vr3.w); }
;     if (more) {
;       *(uint4*)(nK + klo + 0) = kr0; *(uint4*)(nK + klo + 32) = kr1; *(uint4*)(nK + klo + 64) = kr2; *(uint4*)(nK + klo + 96) = kr3; *(uint4*)(nK + klo + 128) = kr4; *(uint4*)(nK + klo + 160) = kr5;
;     }
;     __syncthreads();
.LBB0_1402:
	s_or_b64 exec, exec, s[0:1]
	v_mul_lo_u32 v2, v68, s82
	v_and_b32_e32 v68, 48, v70
	v_add_u32_e32 v2, s9, v2
	v_lshlrev_b32_e32 v68, 1, v68
	v_and_b32_e32 v69, 8, v70
	v_ashrrev_i32_e32 v189, 31, v188
	v_add3_u32 v68, v2, v68, v69
	v_lshl_add_u32 v177, v72, 1, s9
	v_add_u32_e32 v2, 0x6000, v68
	v_add_u32_e32 v216, 0x7000, v68
	v_add_u32_e32 v217, 0x8800, v68
	v_add_u32_e32 v218, 0x9800, v68
	v_mul_u32_u24_e32 v178, 0x48, v176
	v_mad_u32_u24 v179, v176, s83, v210
	v_mad_u32_u24 v180, v176, s83, v211
	v_mad_u32_u24 v181, v176, s83, v212
	s_waitcnt vmcnt(3)
	ds_write2_b64 v2, v[52:53], v[54:55] offset0:128 offset1:130
	s_waitcnt vmcnt(2)
	ds_write2_b64 v216, v[56:57], v[58:59] offset0:192 offset1:194
	s_waitcnt vmcnt(1)
	ds_write2_b64 v217, v[60:61], v[62:63] offset1:2
	s_waitcnt vmcnt(0)
	ds_write2_b64 v218, v[64:65], v[66:67] offset0:64 offset1:66
	ds_write_b128 v71, v[148:151] offset:44032
	ds_write_b128 v71, v[152:155] offset:44096
	ds_write_b128 v71, v[156:159] offset:44160
	ds_write_b128 v71, v[160:163] offset:44224
	ds_write_b128 v71, v[164:167] offset:44288
	ds_write_b128 v71, v[168:171] offset:44352
	s_waitcnt lgkmcnt(0)
	s_barrier
	s_nop 8
	v_mov_b64_e32 v[66:67], v[18:19]
	v_mov_b64_e32 v[82:83], v[18:19]
	v_mov_b64_e32 v[98:99], v[18:19]
	v_mov_b64_e32 v[64:65], v[16:17]
	v_mov_b64_e32 v[62:63], v[14:15]
	v_mov_b64_e32 v[60:61], v[12:13]
	v_mov_b64_e32 v[58:59], v[10:11]
	v_mov_b64_e32 v[56:57], v[8:9]
	v_mov_b64_e32 v[54:55], v[6:7]
	v_mov_b64_e32 v[52:53], v[4:5]
	v_mov_b64_e32 v[80:81], v[16:17]
	v_mov_b64_e32 v[78:79], v[14:15]
	v_mov_b64_e32 v[76:77], v[12:13]
	v_mov_b64_e32 v[74:75], v[10:11]
	v_mov_b64_e32 v[72:73], v[8:9]
	v_mov_b64_e32 v[70:71], v[6:7]
	v_mov_b64_e32 v[68:69], v[4:5]
	v_mov_b64_e32 v[96:97], v[16:17]
	v_mov_b64_e32 v[94:95], v[14:15]
	v_mov_b64_e32 v[92:93], v[12:13]
	v_mov_b64_e32 v[90:91], v[10:11]
	v_mov_b64_e32 v[88:89], v[8:9]
	v_mov_b64_e32 v[86:87], v[6:7]
	v_mov_b64_e32 v[84:85], v[4:5]
	s_and_b32 s0, s7, 15
	s_mul_i32 s97, s0, 0x300000
	s_lshr_b32 s0, s73, 4
	s_lshl_b32 s13, s10, 1
	s_lshl_b32 s92, s0, 1
	s_add_i32 s18, s13, 2
	s_sub_i32 s19, 0, s92
	s_add_u32 s0, s71, s97
	s_addc_u32 s1, s72, 0
	v_or_b32_e32 v220, 31, v175
	v_lshlrev_b32_e32 v219, 2, v174
	s_mov_b32 s21, 0
	v_lshl_add_u32 v221, v178, 1, v177
	v_lshl_add_u32 v222, v179, 1, v177
	v_lshl_add_u32 v223, v180, 1, v177
	v_lshl_add_u32 v224, v181, 1, v177
	v_lshl_add_u64 v[202:203], v[172:173], 1, s[0:1]
	s_movk_i32 s20, 0xff81

; #define MFMA32(a, b, c) __builtin_amdgcn_mfma_f32_32x32x16_bf16((a), (b), (c), 0, 0, 0)
; DI void attn_unit(unsigned char* smem, const Params& P, int bh, int qb) {
;     ...
;   for (int jt = 0; jt < ntiles; ++jt) {
;     const bf16_t* cK = (jt & 1) ? sK1 : sK;
;     bf16_t* nK = (jt & 1) ? sK : sK1;
;     const bool more = (jt + 1 < ntiles);
;     const bool active = (jt * 64 <= q0 + 32 * w + 31);
;     if (more) {
;       const bf16_t* kp = kbuf + (size_t)(jt + 1) * 64 * 192;
;       kr0 = *(const uint4*)(kp + kgo + 0); kr1 = *(const uint4*)(kp + kgo + 32); kr2 = *(const uint4*)(kp + kgo + 64); kr3 = *(const uint4*)(kp + kgo + 96); kr4 = *(const uint4*)(kp + kgo + 128); kr5 = *(const uint4*)(kp + kgo + 160);
;     }
;     __builtin_amdgcn_sched_barrier(0);
;     f32x16 S[2];
;     const float sref = (jt == 0) ? 0.f : mrun;
;     if (active) {
; #pragma unroll
;       for (int a = 0; a < 2; ++a)
; #pragma unroll
;         for (int i = 0; i < 16; ++i) S[a][i] = -sref;
;       __builtin_amdgcn_s_setprio(1);
; #pragma unroll
;       for (int ks = 0; ks < 12; ++ks) {
;         const bf16x8 a0 = *(const bf16x8*)(cK + l31 * KLD + ks * 16 + hh * 8), a1 = *(const bf16x8*)(cK + (32 + l31) * KLD + ks * 16 + hh * 8);
;         S[0] = MFMA32(a0, qf[ks], S[0]); S[1] = MFMA32(a1, qf[ks], S[1]);
;       }
;       __builtin_amdgcn_s_setprio(0);
;     }
;     { const bf16_t* vp_ = vtb + (size_t)(tid >> 3) * 8192 + jt * 64 + (tid & 7) * 8; vr0 = *(const uint4*)(vp_ + (size_t)0 * 8192); vr1 = *(const uint4*)(vp_ + (size_t)32 * 8192); vr2 = *(const uint4*)(vp_ + (size_t)64 * 8192); vr3 = *(const uint4*)(vp_ + (size_t)96 * 8192); }
;     ...
;     if (active) {
;       __builtin_amdgcn_s_setprio(1);
; #pragma unroll
;       for (int kt = 0; kt < 2; ++kt)
; #pragma unroll
;         for (int s2 = 0; s2 < 2; ++s2) {
;           uint4 pp; pp.x = pk2(S[kt][8 * s2], S[kt][8 * s2 + 1]); pp.y = pk2(S[kt][8 * s2 + 2], S[kt][8 * s2 + 3]);
;           pp.z = pk2(S[kt][8 * s2 + 4], S[kt][8 * s2 + 5]); pp.w = pk2(S[kt][8 * s2 + 6], S[kt][8 * s2 + 7]);
;           const bf16x8 pb = __builtin_bit_cast(bf16x8, pp);
; #pragma unroll
;           for (int d = 0; d < 4; ++d) {
;             const bf16x8 vf = *(const bf16x8*)(sV + (d * 32 + l31) * LDK + kt * 32 + s2 * 16 + hh * 8);
;             O[d] = MFMA32(vf, pb, O[d]);
;           }
;         }
;       __builtin_amdgcn_s_setprio(0);
;     }
.LBB0_1409:
	s_add_i32 s22, s20, 0x80
	s_bitcmp0_b32 s22, 0
	s_cselect_b64 s[14:15], -1, 0
	s_add_i32 s10, s21, 64
	v_cmp_le_i32_e64 s[2:3], s10, v220
	v_cmp_le_i32_e64 s[98:99], s21, v220
	s_cmp_lg_u64 s[2:3], 0
	s_cbranch_scc0 .Lslow_2
	s_and_b64 s[24:25], s[14:15], exec
	s_cselect_b32 s23, s9, s28
	v_add3_u32 v243, s23, v197, v201
	s_setprio 1
	ds_read_b128 v[180:183], v221 offset:25600
	ds_read_b128 v[184:187], v222 offset:25600
	ds_read_b128 v[226:229], v223 offset:25600
	ds_read_b128 v[230:233], v224 offset:25600
	ds_read_b128 v[244:247], v221 offset:25632
	ds_read_b128 v[248:251], v222 offset:25632
	ds_read_b128 v[252:255], v223 offset:25632
	v_cvt_pk_bf16_f32 v176, v36, v37
	v_cvt_pk_bf16_f32 v177, v38, v39
	v_cvt_pk_bf16_f32 v178, v40, v41
	v_cvt_pk_bf16_f32 v179, v42, v43
	v_cvt_pk_bf16_f32 v172, v44, v45
	v_cvt_pk_bf16_f32 v173, v46, v47
	v_cvt_pk_bf16_f32 v174, v48, v49
	v_cvt_pk_bf16_f32 v175, v50, v51
	s_waitcnt lgkmcnt(6)
	v_mfma_f32_32x32x16_bf16 v[84:99], v[180:183], v[176:179], v[84:99]
	ds_read_b128 v[180:183], v224 offset:25632
	global_load_dwordx4 v[148:151], v[202:203], off
	s_waitcnt lgkmcnt(6)
	v_mfma_f32_32x32x16_bf16 v[68:83], v[184:187], v[176:179], v[68:83]
	ds_read_b128 v[184:187], v221 offset:25664
	global_load_dwordx4 v[152:155], v[202:203], off offset:64
	s_waitcnt lgkmcnt(6)
	v_mfma_f32_32x32x16_bf16 v[52:67], v[226:229], v[176:179], v[52:67]
	ds_read_b128 v[226:229], v222 offset:25664
	global_load_dwordx4 v[156:159], v[202:203], off offset:128
	s_waitcnt lgkmcnt(6)
	v_mfma_f32_32x32x16_bf16 v[4:19], v[230:233], v[176:179], v[4:19]
	ds_read_b128 v[230:233], v223 offset:25664
	global_load_dwordx4 v[160:163], v[202:203], off offset:192
	s_waitcnt lgkmcnt(6)
	v_mfma_f32_32x32x16_bf16 v[84:99], v[244:247], v[172:175], v[84:99]
	ds_read_b128 v[244:247], v224 offset:25664
	global_load_dwordx4 v[164:167], v[202:203], off offset:256
	v_cvt_pk_bf16_f32 v176, v20, v21
	v_cvt_pk_bf16_f32 v177, v22, v23
	v_cvt_pk_bf16_f32 v178, v24, v25
	v_cvt_pk_bf16_f32 v179, v26, v27
	s_waitcnt lgkmcnt(6)
	v_mfma_f32_32x32x16_bf16 v[68:83], v[248:251], v[172:175], v[68:83]
	ds_read_b128 v[248:251], v221 offset:25696
	global_load_dwordx4 v[168:171], v[202:203], off offset:320
	s_waitcnt lgkmcnt(6)
	v_mfma_f32_32x32x16_bf16 v[52:67], v[252:255], v[172:175], v[52:67]
	ds_read_b128 v[252:255], v222 offset:25696
	s_waitcnt lgkmcnt(6)
	v_mfma_f32_32x32x16_bf16 v[4:19], v[180:183], v[172:175], v[4:19]
	ds_read_b128 v[180:183], v223 offset:25696
	s_waitcnt lgkmcnt(6)
	v_mfma_f32_32x32x16_bf16 v[84:99], v[184:187], v[176:179], v[84:99]
	ds_read_b128 v[184:187], v224 offset:25696
	v_cvt_pk_bf16_f32 v172, v28, v29
	v_cvt_pk_bf16_f32 v173, v30, v31
	v_cvt_pk_bf16_f32 v174, v32, v33
	v_cvt_pk_bf16_f32 v175, v34, v35
	s_waitcnt lgkmcnt(6)
	v_mfma_f32_32x32x16_bf16 v[68:83], v[226:229], v[176:179], v[68:83]
	v_xor_b32_e32 v20, 0x80000000, v200
	v_mov_b32_e32 v21, v20
	v_mov_b32_e32 v22, v20
	v_mov_b32_e32 v23, v20
	ds_read_b128 v[226:229], v243 offset:12832
	s_waitcnt lgkmcnt(6)
	v_mfma_f32_32x32x16_bf16 v[52:67], v[230:233], v[176:179], v[52:67]
	v_mov_b32_e32 v24, v20
	v_mov_b32_e32 v25, v20
	v_mov_b32_e32 v26, v20
	v_mov_b32_e32 v27, v20
	ds_read_b128 v[230:233], v243 offset:64
	s_waitcnt lgkmcnt(6)
	v_mfma_f32_32x32x16_bf16 v[4:19], v[244:247], v[176:179], v[4:19]
	v_mov_b32_e32 v28, v20
	v_mov_b32_e32 v29, v20
	v_mov_b32_e32 v30, v20
	v_mov_b32_e32 v31, v20
	ds_read_b128 v[244:247], v243
	s_waitcnt lgkmcnt(6)
	v_mfma_f32_32x32x16_bf16 v[84:99], v[248:251], v[172:175], v[84:99]
	v_mov_b32_e32 v32, v20
	v_mov_b32_e32 v33, v20
	v_mov_b32_e32 v34, v20
	v_mov_b32_e32 v35, v20
	ds_read_b128 v[248:251], v243 offset:12800
	s_waitcnt lgkmcnt(6)
	v_mfma_f32_32x32x16_bf16 v[68:83], v[252:255], v[172:175], v[68:83]
	ds_read_b128 v[252:255], v243 offset:32
	s_waitcnt lgkmcnt(6)
; #define MFMA32(a, b, c) __builtin_amdgcn_mfma_f32_32x32x16_bf16((a), (b), (c), 0, 0, 0)
; DI void attn_unit(unsigned char* smem, const Params& P, int bh, int qb) {
;     ...
;     if (active) {
; #pragma unroll
;       for (int a = 0; a < 2; ++a)
; #pragma unroll
;         for (int i = 0; i < 16; ++i) S[a][i] = -sref;
;       __builtin_amdgcn_s_setprio(1);
; #pragma unroll
;       for (int ks = 0; ks < 12; ++ks) {
;         const bf16x8 a0 = *(const bf16x8*)(cK + l31 * KLD + ks * 16 + hh * 8), a1 = *(const bf16x8*)(cK + (32 + l31) * KLD + ks * 16 + hh * 8);
;         S[0] = MFMA32(a0, qf[ks], S[0]); S[1] = MFMA32(a1, qf[ks], S[1]);
;       }
;       __builtin_amdgcn_s_setprio(0);
;     }
;     { const bf16_t* vp_ = vtb + (size_t)(tid >> 3) * 8192 + jt * 64 + (tid & 7) * 8; vr0 = *(const uint4*)(vp_ + (size_t)0 * 8192); vr1 = *(const uint4*)(vp_ + (size_t)32 * 8192); vr2 = *(const uint4*)(vp_ + (size_t)64 * 8192); vr3 = *(const uint4*)(vp_ + (size_t)96 * 8192); }
	v_mfma_f32_32x32x16_bf16 v[52:67], v[180:183], v[172:175], v[52:67]
	s_waitcnt lgkmcnt(5)
	v_mfma_f32_32x32x16_bf16 v[4:19], v[184:187], v[172:175], v[4:19]
	s_waitcnt lgkmcnt(2)
	v_mfma_f32_32x32x16_bf16 v[36:51], v[244:247], v[100:103], v[20:35]
	ds_read_b128 v[244:247], v243 offset:12864
	v_lshl_add_u64 v[180:181], s[10:11], 1, v[198:199]
	v_add_co_u32_e32 v176, vcc, s78, v180
	s_nop 1
	v_addc_co_u32_e32 v177, vcc, 0, v181, vcc
	s_waitcnt lgkmcnt(2)
	v_mfma_f32_32x32x16_bf16 v[20:35], v[248:251], v[100:103], v[20:35]
	ds_read_b128 v[248:251], v243 offset:96
	v_add_co_u32_e32 v182, vcc, 0x100000, v180
	global_load_dwordx4 v[172:175], v[180:181], off
	s_nop 0
	global_load_dwordx4 v[176:179], v[176:177], off
	s_waitcnt lgkmcnt(2)
	v_mfma_f32_32x32x16_bf16 v[36:51], v[252:255], v[104:107], v[36:51]
	ds_read_b128 v[252:255], v243 offset:12896
	v_addc_co_u32_e32 v183, vcc, 0, v181, vcc
	v_add_co_u32_e32 v180, vcc, 0x180000, v180
	s_nop 1
	v_addc_co_u32_e32 v181, vcc, 0, v181, vcc
	s_waitcnt lgkmcnt(7)
	v_mfma_f32_32x32x16_bf16 v[20:35], v[226:229], v[104:107], v[20:35]
	ds_read_b128 v[226:229], v243 offset:128
	global_load_dwordx4 v[184:187], v[182:183], off
	s_nop 0
	global_load_dwordx4 v[180:183], v[180:181], off
	s_waitcnt lgkmcnt(7)
	v_mfma_f32_32x32x16_bf16 v[36:51], v[230:233], v[108:111], v[36:51]
	ds_read_b128 v[230:233], v243 offset:12928
	s_waitcnt lgkmcnt(4)
	v_mfma_f32_32x32x16_bf16 v[20:35], v[244:247], v[108:111], v[20:35]
	ds_read_b128 v[244:247], v243 offset:160
	s_waitcnt lgkmcnt(4)
	v_mfma_f32_32x32x16_bf16 v[36:51], v[248:251], v[112:115], v[36:51]
	ds_read_b128 v[248:251], v243 offset:12960
	s_waitcnt lgkmcnt(4)
	v_mfma_f32_32x32x16_bf16 v[20:35], v[252:255], v[112:115], v[20:35]
	ds_read_b128 v[252:255], v243 offset:192
	s_waitcnt lgkmcnt(4)
	v_mfma_f32_32x32x16_bf16 v[36:51], v[226:229], v[116:119], v[36:51]
	ds_read_b128 v[226:229], v243 offset:12992
	s_waitcnt lgkmcnt(4)
	v_mfma_f32_32x32x16_bf16 v[20:35], v[230:233], v[116:119], v[20:35]
	ds_read_b128 v[230:233], v243 offset:224
	s_waitcnt lgkmcnt(4)
	v_mfma_f32_32x32x16_bf16 v[36:51], v[244:247], v[120:123], v[36:51]
	ds_read_b128 v[244:247], v243 offset:13024
	s_waitcnt lgkmcnt(4)
	v_mfma_f32_32x32x16_bf16 v[20:35], v[248:251], v[120:123], v[20:35]
	ds_read_b128 v[248:251], v243 offset:256
	s_waitcnt lgkmcnt(4)
	v_mfma_f32_32x32x16_bf16 v[36:51], v[252:255], v[124:127], v[36:51]
	ds_read_b128 v[252:255], v243 offset:13056
	s_waitcnt lgkmcnt(4)
	v_mfma_f32_32x32x16_bf16 v[20:35], v[226:229], v[124:127], v[20:35]
	ds_read_b128 v[226:229], v243 offset:288
	s_waitcnt lgkmcnt(4)
	v_mfma_f32_32x32x16_bf16 v[36:51], v[230:233], v[128:131], v[36:51]
	ds_read_b128 v[230:233], v243 offset:13088
	s_waitcnt lgkmcnt(4)
	v_mfma_f32_32x32x16_bf16 v[20:35], v[244:247], v[128:131], v[20:35]
	ds_read_b128 v[244:247], v243 offset:320
	s_waitcnt lgkmcnt(4)
	v_mfma_f32_32x32x16_bf16 v[36:51], v[248:251], v[132:135], v[36:51]
	ds_read_b128 v[248:251], v243 offset:13120
	s_waitcnt lgkmcnt(4)
	v_mfma_f32_32x32x16_bf16 v[20:35], v[252:255], v[132:135], v[20:35]
	ds_read_b128 v[252:255], v243 offset:352
	s_waitcnt lgkmcnt(4)
	v_mfma_f32_32x32x16_bf16 v[36:51], v[226:229], v[136:139], v[36:51]
	ds_read_b128 v[226:229], v243 offset:13152
	s_waitcnt lgkmcnt(4)
	v_mfma_f32_32x32x16_bf16 v[20:35], v[230:233], v[136:139], v[20:35]
	s_waitcnt lgkmcnt(3)
	v_mfma_f32_32x32x16_bf16 v[36:51], v[244:247], v[140:143], v[36:51]
	s_waitcnt lgkmcnt(2)
	v_mfma_f32_32x32x16_bf16 v[20:35], v[248:251], v[140:143], v[20:35]
	s_waitcnt lgkmcnt(1)
	v_mfma_f32_32x32x16_bf16 v[36:51], v[252:255], v[144:147], v[36:51]
	s_waitcnt lgkmcnt(0)
	v_mfma_f32_32x32x16_bf16 v[20:35], v[226:229], v[144:147], v[20:35]
	s_nop 11
	s_setprio 0
	s_branch .LBB0_1411

; #define MFMA32(a, b, c) __builtin_amdgcn_mfma_f32_32x32x16_bf16((a), (b), (c), 0, 0, 0)
; DI void attn_unit(unsigned char* smem, const Params& P, int bh, int qb) {
;     ...
;     if (active) {
; #pragma unroll
;       for (int a = 0; a < 2; ++a)
; #pragma unroll
;         for (int i = 0; i < 16; ++i) S[a][i] = -sref;
;       __builtin_amdgcn_s_setprio(1);
; #pragma unroll
;       for (int ks = 0; ks < 12; ++ks) {
;         const bf16x8 a0 = *(const bf16x8*)(cK + l31 * KLD + ks * 16 + hh * 8), a1 = *(const bf16x8*)(cK + (32 + l31) * KLD + ks * 16 + hh * 8);
;         S[0] = MFMA32(a0, qf[ks], S[0]); S[1] = MFMA32(a1, qf[ks], S[1]);
;       }
;       __builtin_amdgcn_s_setprio(0);
;     }
;     { const bf16_t* vp_ = vtb + (size_t)(tid >> 3) * 8192 + jt * 64 + (tid & 7) * 8; vr0 = *(const uint4*)(vp_ + (size_t)0 * 8192); vr1 = *(const uint4*)(vp_ + (size_t)32 * 8192); vr2 = *(const uint4*)(vp_ + (size_t)64 * 8192); vr3 = *(const uint4*)(vp_ + (size_t)96 * 8192); }
.Lpvtop_skip_2:
	s_or_b64 exec, exec, s[100:101]
	v_lshl_add_u64 v[180:181], s[10:11], 1, v[198:199]
	v_add_co_u32_e32 v176, vcc, s78, v180
	s_nop 1
	v_addc_co_u32_e32 v177, vcc, 0, v181, vcc
	v_add_co_u32_e32 v182, vcc, 0x100000, v180
	global_load_dwordx4 v[172:175], v[180:181], off
	s_nop 0
	global_load_dwordx4 v[176:179], v[176:177], off
	v_addc_co_u32_e32 v183, vcc, 0, v181, vcc
	v_add_co_u32_e32 v180, vcc, 0x180000, v180
	s_nop 1
	v_addc_co_u32_e32 v181, vcc, 0, v181, vcc
	global_load_dwordx4 v[184:187], v[182:183], off
	s_nop 0
	global_load_dwordx4 v[180:183], v[180:181], off
	s_and_saveexec_b64 s[16:17], s[2:3]
	s_cbranch_execz .LBB0_1411
	s_and_b64 s[24:25], s[14:15], exec
	v_xor_b32_e32 v20, 0x80000000, v200
	s_cselect_b32 s23, s9, s28
	s_setprio 1
	v_add3_u32 v243, s23, v197, v201
	ds_read_b128 v[244:247], v243
	ds_read_b128 v[248:251], v243 offset:12800
	ds_read_b128 v[252:255], v243 offset:32
	ds_read_b128 v[226:229], v243 offset:12832
	ds_read_b128 v[230:233], v243 offset:64
	v_mov_b32_e32 v21, v20
	v_mov_b32_e32 v22, v20
	v_mov_b32_e32 v23, v20
	v_mov_b32_e32 v24, v20
	v_mov_b32_e32 v25, v20
	v_mov_b32_e32 v26, v20
	v_mov_b32_e32 v27, v20
	v_mov_b32_e32 v28, v20
	v_mov_b32_e32 v29, v20
	v_mov_b32_e32 v30, v20
	v_mov_b32_e32 v31, v20
	v_mov_b32_e32 v32, v20
	v_mov_b32_e32 v33, v20
	v_mov_b32_e32 v34, v20
	v_mov_b32_e32 v35, v20
	s_waitcnt lgkmcnt(4)
	s_nop 0
	v_mfma_f32_32x32x16_bf16 v[36:51], v[244:247], v[100:103], v[20:35]
	ds_read_b128 v[244:247], v243 offset:12864
	s_waitcnt lgkmcnt(4)
	v_mfma_f32_32x32x16_bf16 v[20:35], v[248:251], v[100:103], v[20:35]
	ds_read_b128 v[248:251], v243 offset:96
	s_waitcnt lgkmcnt(4)
	v_mfma_f32_32x32x16_bf16 v[36:51], v[252:255], v[104:107], v[36:51]
	ds_read_b128 v[252:255], v243 offset:12896
	s_waitcnt lgkmcnt(4)
	v_mfma_f32_32x32x16_bf16 v[20:35], v[226:229], v[104:107], v[20:35]
	ds_read_b128 v[226:229], v243 offset:128
	s_waitcnt lgkmcnt(4)
	v_mfma_f32_32x32x16_bf16 v[36:51], v[230:233], v[108:111], v[36:51]
	ds_read_b128 v[230:233], v243 offset:12928
	s_waitcnt lgkmcnt(4)
	v_mfma_f32_32x32x16_bf16 v[20:35], v[244:247], v[108:111], v[20:35]
	ds_read_b128 v[244:247], v243 offset:160
	s_waitcnt lgkmcnt(4)
	v_mfma_f32_32x32x16_bf16 v[36:51], v[248:251], v[112:115], v[36:51]
	ds_read_b128 v[248:251], v243 offset:12960
	s_waitcnt lgkmcnt(4)
	v_mfma_f32_32x32x16_bf16 v[20:35], v[252:255], v[112:115], v[20:35]
	ds_read_b128 v[252:255], v243 offset:192
	s_waitcnt lgkmcnt(4)
	v_mfma_f32_32x32x16_bf16 v[36:51], v[226:229], v[116:119], v[36:51]
	ds_read_b128 v[226:229], v243 offset:12992
	s_waitcnt lgkmcnt(4)
	v_mfma_f32_32x32x16_bf16 v[20:35], v[230:233], v[116:119], v[20:35]
	ds_read_b128 v[230:233], v243 offset:224
	s_waitcnt lgkmcnt(4)
	v_mfma_f32_32x32x16_bf16 v[36:51], v[244:247], v[120:123], v[36:51]
	ds_read_b128 v[244:247], v243 offset:13024
	s_waitcnt lgkmcnt(4)
	v_mfma_f32_32x32x16_bf16 v[20:35], v[248:251], v[120:123], v[20:35]
	ds_read_b128 v[248:251], v243 offset:256
	s_waitcnt lgkmcnt(4)
	v_mfma_f32_32x32x16_bf16 v[36:51], v[252:255], v[124:127], v[36:51]
	ds_read_b128 v[252:255], v243 offset:13056
	s_waitcnt lgkmcnt(4)
	v_mfma_f32_32x32x16_bf16 v[20:35], v[226:229], v[124:127], v[20:35]
	ds_read_b128 v[226:229], v243 offset:288
	s_waitcnt lgkmcnt(4)
	v_mfma_f32_32x32x16_bf16 v[36:51], v[230:233], v[128:131], v[36:51]
	ds_read_b128 v[230:233], v243 offset:13088
	s_waitcnt lgkmcnt(4)
	v_mfma_f32_32x32x16_bf16 v[20:35], v[244:247], v[128:131], v[20:35]
	ds_read_b128 v[244:247], v243 offset:320
	s_waitcnt lgkmcnt(4)
	v_mfma_f32_32x32x16_bf16 v[36:51], v[248:251], v[132:135], v[36:51]
	ds_read_b128 v[248:251], v243 offset:13120
	s_waitcnt lgkmcnt(4)
	v_mfma_f32_32x32x16_bf16 v[20:35], v[252:255], v[132:135], v[20:35]
	ds_read_b128 v[252:255], v243 offset:352
	s_waitcnt lgkmcnt(4)
	v_mfma_f32_32x32x16_bf16 v[36:51], v[226:229], v[136:139], v[36:51]
	ds_read_b128 v[226:229], v243 offset:13152
	s_waitcnt lgkmcnt(4)
	v_mfma_f32_32x32x16_bf16 v[20:35], v[230:233], v[136:139], v[20:35]
	s_waitcnt lgkmcnt(3)
	v_mfma_f32_32x32x16_bf16 v[36:51], v[244:247], v[140:143], v[36:51]
	s_waitcnt lgkmcnt(2)
	v_mfma_f32_32x32x16_bf16 v[20:35], v[248:251], v[140:143], v[20:35]
	s_waitcnt lgkmcnt(1)
	v_mfma_f32_32x32x16_bf16 v[36:51], v[252:255], v[144:147], v[36:51]
	s_waitcnt lgkmcnt(0)
	v_mfma_f32_32x32x16_bf16 v[20:35], v[226:229], v[144:147], v[20:35]
	s_nop 11
	s_setprio 0
; DI int crow(int i, int h) { return (i & 3) + 8 * (i >> 2) + 4 * h; }
; DI void attn_unit(unsigned char* smem, const Params& P, int bh, int qb) {
;     ...
;     { const bf16_t* vp_ = vtb + (size_t)(tid >> 3) * 8192 + jt * 64 + (tid & 7) * 8; vr0 = *(const uint4*)(vp_ + (size_t)0 * 8192); vr1 = *(const uint4*)(vp_ + (size_t)32 * 8192); vr2 = *(const uint4*)(vp_ + (size_t)64 * 8192); vr3 = *(const uint4*)(vp_ + (size_t)96 * 8192); }
;     __builtin_amdgcn_sched_barrier(0);
;     if (active) {
;       if (jt >= ntiles - 2) {
; #pragma unroll
;         for (int kt = 0; kt < 2; ++kt)
; #pragma unroll
;           for (int i = 0; i < 16; ++i) { const int key = jt * 64 + kt * 32 + crow(i, hh); if (key > qrow) S[kt][i] = -1e30f; }
;       }
.LBB0_1411:
	s_or_b64 exec, exec, s[16:17]
	s_barrier
	s_and_saveexec_b64 s[16:17], s[2:3]
	s_cbranch_execz .LBB0_1417
	s_cmp_lt_u32 s22, s13
	s_cbranch_scc1 .LBB0_1414
	v_add_u32_e32 v225, s21, v219
	v_add_u32_e32 v226, 64, v225
	v_cmp_le_i32_e32 vcc, v226, v188
	s_nop 1
	v_cndmask_b32_e32 v36, v213, v36, vcc
	v_cmp_lt_i32_e32 vcc, v226, v188
	v_add_u32_e32 v226, 0x42, v225
	s_nop 0
	v_cndmask_b32_e32 v37, v213, v37, vcc
	v_cmp_le_i32_e32 vcc, v226, v188
	v_add_u32_e32 v226, 0x43, v225
	s_nop 0
	v_cndmask_b32_e32 v38, v213, v38, vcc
	v_cmp_le_i32_e32 vcc, v226, v188
	v_add_u32_e32 v226, 0x48, v225
	s_nop 0
	v_cndmask_b32_e32 v39, v213, v39, vcc
	v_cmp_le_i32_e32 vcc, v226, v188
	v_add_u32_e32 v226, 0x49, v225
	s_nop 0
	v_cndmask_b32_e32 v40, v213, v40, vcc
	v_cmp_le_i32_e32 vcc, v226, v188
	v_add_u32_e32 v226, 0x4a, v225
	s_nop 0
	v_cndmask_b32_e32 v41, v213, v41, vcc
	v_cmp_le_i32_e32 vcc, v226, v188
	v_add_u32_e32 v226, 0x4b, v225
	s_nop 0
	v_cndmask_b32_e32 v42, v213, v42, vcc
	v_cmp_le_i32_e32 vcc, v226, v188
	v_add_u32_e32 v226, 0x50, v225
	s_nop 0
	v_cndmask_b32_e32 v43, v213, v43, vcc
	v_cmp_le_i32_e32 vcc, v226, v188
	v_add_u32_e32 v226, 0x51, v225
	s_nop 0
	v_cndmask_b32_e32 v44, v213, v44, vcc
	v_cmp_le_i32_e32 vcc, v226, v188
	v_add_u32_e32 v226, 0x52, v225
	s_nop 0
	v_cndmask_b32_e32 v45, v213, v45, vcc
	v_cmp_le_i32_e32 vcc, v226, v188
	v_add_u32_e32 v226, 0x53, v225
	s_nop 0
	v_cndmask_b32_e32 v46, v213, v46, vcc
	v_cmp_le_i32_e32 vcc, v226, v188
	v_add_u32_e32 v226, 0x58, v225
	s_nop 0
	v_cndmask_b32_e32 v47, v213, v47, vcc
	v_cmp_le_i32_e32 vcc, v226, v188
	v_add_u32_e32 v226, 0x59, v225
	s_nop 0
	v_cndmask_b32_e32 v48, v213, v48, vcc
	v_cmp_le_i32_e32 vcc, v226, v188
	v_add_u32_e32 v226, 0x5a, v225
	s_nop 0
	v_cndmask_b32_e32 v49, v213, v49, vcc
	v_cmp_le_i32_e32 vcc, v226, v188
	v_add_u32_e32 v226, 0x5b, v225
	s_nop 0
	v_cndmask_b32_e32 v50, v213, v50, vcc
	v_cmp_le_i32_e32 vcc, v226, v188
	v_add_u32_e32 v226, 0x60, v225
	s_nop 0
	v_cndmask_b32_e32 v51, v213, v51, vcc
	v_cmp_le_i32_e32 vcc, v226, v188
	v_add_u32_e32 v226, 0x61, v225
	s_nop 0
	v_cndmask_b32_e32 v20, v213, v20, vcc
	v_cmp_le_i32_e32 vcc, v226, v188
	v_add_u32_e32 v226, 0x62, v225
	s_nop 0
	v_cndmask_b32_e32 v21, v213, v21, vcc
	v_cmp_le_i32_e32 vcc, v226, v188
	v_add_u32_e32 v226, 0x63, v225
	s_nop 0
	v_cndmask_b32_e32 v22, v213, v22, vcc
	v_cmp_le_i32_e32 vcc, v226, v188
	v_add_u32_e32 v226, 0x68, v225
	s_nop 0
	v_cndmask_b32_e32 v23, v213, v23, vcc
	v_cmp_le_i32_e32 vcc, v226, v188
	v_add_u32_e32 v226, 0x69, v225
	s_nop 0
	v_cndmask_b32_e32 v24, v213, v24, vcc
	v_cmp_le_i32_e32 vcc, v226, v188
	v_add_u32_e32 v226, 0x6a, v225
	s_nop 0
	v_cndmask_b32_e32 v25, v213, v25, vcc
	v_cmp_le_i32_e32 vcc, v226, v188
	v_add_u32_e32 v226, 0x6b, v225
	s_nop 0
	v_cndmask_b32_e32 v26, v213, v26, vcc
	v_cmp_le_i32_e32 vcc, v226, v188
	v_add_u32_e32 v226, 0x70, v225
	s_nop 0
	v_cndmask_b32_e32 v27, v213, v27, vcc
	v_cmp_le_i32_e32 vcc, v226, v188
	v_add_u32_e32 v226, 0x71, v225
	s_nop 0
	v_cndmask_b32_e32 v28, v213, v28, vcc
	v_cmp_le_i32_e32 vcc, v226, v188
	v_add_u32_e32 v226, 0x72, v225
	s_nop 0
	v_cndmask_b32_e32 v29, v213, v29, vcc
	v_cmp_le_i32_e32 vcc, v226, v188
	v_add_u32_e32 v226, 0x73, v225
	s_nop 0
	v_cndmask_b32_e32 v30, v213, v30, vcc
	v_cmp_le_i32_e32 vcc, v226, v188
	v_add_u32_e32 v226, 0x78, v225
	s_nop 0
	v_cndmask_b32_e32 v31, v213, v31, vcc
	v_cmp_le_i32_e32 vcc, v226, v188
	v_add_u32_e32 v226, 0x79, v225
	s_nop 0
	v_cndmask_b32_e32 v32, v213, v32, vcc
	v_cmp_le_i32_e32 vcc, v226, v188
	v_add_u32_e32 v226, 0x7a, v225
	v_add_u32_e32 v225, 0x7b, v225
	v_cndmask_b32_e32 v33, v213, v33, vcc
	v_cmp_le_i32_e32 vcc, v226, v188
	s_nop 1
	v_cndmask_b32_e32 v34, v213, v34, vcc
	v_cmp_le_i32_e32 vcc, v225, v188
	s_nop 1
	v_cndmask_b32_e32 v35, v213, v35, vcc

; #define MFMA32(a, b, c) __builtin_amdgcn_mfma_f32_32x32x16_bf16((a), (b), (c), 0, 0, 0)
; DI void attn_unit(unsigned char* smem, const Params& P, int bh, int qb) {
;     ...
;     __syncthreads();
;     if (active) {
;       __builtin_amdgcn_s_setprio(1);
; #pragma unroll
;       for (int kt = 0; kt < 2; ++kt)
; #pragma unroll
;         for (int s2 = 0; s2 < 2; ++s2) {
;           uint4 pp; pp.x = pk2(S[kt][8 * s2], S[kt][8 * s2 + 1]); pp.y = pk2(S[kt][8 * s2 + 2], S[kt][8 * s2 + 3]);
;           pp.z = pk2(S[kt][8 * s2 + 4], S[kt][8 * s2 + 5]); pp.w = pk2(S[kt][8 * s2 + 6], S[kt][8 * s2 + 7]);
;           const bf16x8 pb = __builtin_bit_cast(bf16x8, pp);
; #pragma unroll
;           for (int d = 0; d < 4; ++d) {
;             const bf16x8 vf = *(const bf16x8*)(sV + (d * 32 + l31) * LDK + kt * 32 + s2 * 16 + hh * 8);
;             O[d] = MFMA32(vf, pb, O[d]);
;           }
;         }
;       __builtin_amdgcn_s_setprio(0);
;     }
;     __syncthreads();
;   }
.LBB0_1419:
	s_waitcnt lgkmcnt(0)
	s_barrier
	s_add_i32 s20, s20, 1
	s_cmp_lg_u32 s19, s20
	v_lshl_add_u64 v[202:203], v[202:203], 0, s[40:41]
	s_cbranch_scc0 .LBB0_1423
	s_mov_b32 s21, s10
	s_branch .LBB0_1407

; DI void attn_unit(unsigned char* smem, const Params& P, int bh, int qb) {
;     ...
;   const int q0 = qb * 128, qrow = q0 + 32 * w + l31;
;   bf16x8 qf[12];
; #pragma unroll
;   for (int ks = 0; ks < 12; ++ks) qf[ks] = *(const bf16x8*)(qbuf + (size_t)qrow * 192 + ks * 16 + hh * 8);
;   f32x16 O[4];
; #pragma unroll
;   for (int d = 0; d < 4; ++d)
; #pragma unroll
;     for (int i = 0; i < 16; ++i) O[d][i] = 0.f;
;   float mrun = -1e30f, lrun = 0.f;
;   const int ntiles = 2 * qb + 2;
;   bf16_t* sK1 = sV + 128 * LDK;
;   uint4 kr0, kr1, kr2, kr3, kr4, kr5, vr0, vr1, vr2, vr3;
;   const int kgo = (tid >> 2) * 192 + (tid & 3) * 8, klo = (tid >> 2) * KLD + (tid & 3) * 8;
;   __syncthreads();
;     ...
;   const float ltot = lrun + __shfl_xor(lrun, 32), inv = 1.0f / ltot;
; #pragma unroll
;   for (int d = 0; d < 4; ++d)
; #pragma unroll
;     for (int g4 = 0; g4 < 4; ++g4) {
;       const int dv = d * 32 + 8 * g4 + 4 * hh;
;       uint2 pk; pk.x = pk2(O[d][4 * g4] * inv, O[d][4 * g4 + 1] * inv); pk.y = pk2(O[d][4 * g4 + 2] * inv, O[d][4 * g4 + 3] * inv);
;       *(uint2*)(obuf + (size_t)qrow * 1024 + dv) = pk;
;     }
.Lpvexit_skip_2:
	s_or_b64 exec, exec, s[100:101]
	v_and_b32_e32 v20, 64, v214
	v_xor_b32_e32 v2, 32, v214
	v_add_u32_e32 v20, 64, v20
	v_cmp_lt_i32_e32 vcc, v2, v20
	s_lshl_b32 s0, s8, 22
	s_and_b32 s0, s0, 0x3000000
	v_cndmask_b32_e32 v2, v214, v2, vcc
	v_lshlrev_b32_e32 v203, 2, v2
	ds_bpermute_b32 v2, v203, v215
	s_add_u32 s2, s69, s0
	s_addc_u32 s3, s70, 0
	s_lshl_b32 s8, s8, 8
	s_waitcnt lgkmcnt(0)
	v_add_f32_e32 v2, v215, v2
	v_div_scale_f32 v20, s[0:1], v2, v2, 1.0
	v_rcp_f32_e32 v21, v20
	s_and_b32 s0, s8, 0x300
	s_add_u32 s0, s2, s0
	s_addc_u32 s1, s3, 0
	v_fma_f32 v22, -v20, v21, 1.0
	v_fmac_f32_e32 v21, v22, v21
	v_div_scale_f32 v22, vcc, 1.0, v2, 1.0
	v_mul_f32_e32 v23, v22, v21
	v_fma_f32 v24, -v20, v23, v22
	v_fmac_f32_e32 v23, v24, v21
	v_fma_f32 v20, -v20, v23, v22
	v_div_fmas_f32 v20, v20, v21, v23
	v_div_fixup_f32 v24, v20, v2, 1.0
	v_lshlrev_b64 v[20:21], 11, v[188:189]
	v_lshl_add_u64 v[20:21], s[0:1], 0, v[20:21]
	v_mul_f32_e32 v22, v84, v24
	v_mul_f32_e32 v25, v85, v24
	v_mul_f32_e32 v23, v86, v24
	v_mul_f32_e32 v26, v87, v24
	v_lshlrev_b32_e32 v2, 1, v219
	v_lshl_add_u64 v[20:21], v[20:21], 0, v[2:3]
	v_cvt_pk_bf16_f32 v23, v23, v26
	v_cvt_pk_bf16_f32 v22, v22, v25
	global_store_dwordx2 v[20:21], v[22:23], off
	v_mul_f32_e32 v2, v88, v24
	v_mul_f32_e32 v22, v89, v24
	v_mul_f32_e32 v23, v90, v24
	v_mul_f32_e32 v25, v91, v24
	v_cvt_pk_bf16_f32 v23, v23, v25
	v_cvt_pk_bf16_f32 v22, v2, v22
	global_store_dwordx2 v[20:21], v[22:23], off offset:16
	v_mul_f32_e32 v2, v92, v24
	v_mul_f32_e32 v22, v93, v24
	v_mul_f32_e32 v23, v94, v24
	v_mul_f32_e32 v25, v95, v24
	v_cvt_pk_bf16_f32 v23, v23, v25
	v_cvt_pk_bf16_f32 v22, v2, v22
	global_store_dwordx2 v[20:21], v[22:23], off offset:32
	v_mul_f32_e32 v2, v96, v24
	v_mul_f32_e32 v22, v97, v24
	v_mul_f32_e32 v23, v98, v24
	v_mul_f32_e32 v25, v99, v24
	v_cvt_pk_bf16_f32 v23, v23, v25
	v_cvt_pk_bf16_f32 v22, v2, v22
	global_store_dwordx2 v[20:21], v[22:23], off offset:48
	v_mul_f32_e32 v2, v68, v24
	v_mul_f32_e32 v22, v69, v24
	v_mul_f32_e32 v23, v70, v24
	v_mul_f32_e32 v25, v71, v24
	v_cvt_pk_bf16_f32 v23, v23, v25
	v_cvt_pk_bf16_f32 v22, v2, v22
	global_store_dwordx2 v[20:21], v[22:23], off offset:64
	v_mul_f32_e32 v2, v72, v24
	v_mul_f32_e32 v22, v73, v24
	v_mul_f32_e32 v23, v74, v24
	v_mul_f32_e32 v25, v75, v24
	v_cvt_pk_bf16_f32 v23, v23, v25
	v_cvt_pk_bf16_f32 v22, v2, v22
	global_store_dwordx2 v[20:21], v[22:23], off offset:80
	v_mul_f32_e32 v2, v76, v24
	v_mul_f32_e32 v22, v77, v24
	v_mul_f32_e32 v23, v78, v24
	v_mul_f32_e32 v25, v79, v24
	v_cvt_pk_bf16_f32 v23, v23, v25
	v_cvt_pk_bf16_f32 v22, v2, v22
	global_store_dwordx2 v[20:21], v[22:23], off offset:96
	v_mul_f32_e32 v2, v80, v24
	v_mul_f32_e32 v22, v81, v24
	v_mul_f32_e32 v23, v82, v24
	v_mul_f32_e32 v25, v83, v24
	v_cvt_pk_bf16_f32 v23, v23, v25
	v_cvt_pk_bf16_f32 v22, v2, v22
	global_store_dwordx2 v[20:21], v[22:23], off offset:112
	v_mul_f32_e32 v2, v52, v24
	v_mul_f32_e32 v22, v53, v24
	v_mul_f32_e32 v23, v54, v24
	v_mul_f32_e32 v25, v55, v24
	v_cvt_pk_bf16_f32 v23, v23, v25
	v_cvt_pk_bf16_f32 v22, v2, v22
	global_store_dwordx2 v[20:21], v[22:23], off offset:128
	v_mul_f32_e32 v2, v56, v24
	v_mul_f32_e32 v22, v57, v24
	v_mul_f32_e32 v23, v58, v24
	v_mul_f32_e32 v25, v59, v24
	v_cvt_pk_bf16_f32 v23, v23, v25
	v_cvt_pk_bf16_f32 v22, v2, v22
	global_store_dwordx2 v[20:21], v[22:23], off offset:144
	v_mul_f32_e32 v2, v60, v24
	v_mul_f32_e32 v22, v61, v24
	v_mul_f32_e32 v23, v62, v24
	v_mul_f32_e32 v25, v63, v24
	v_cvt_pk_bf16_f32 v23, v23, v25
	v_cvt_pk_bf16_f32 v22, v2, v22
	global_store_dwordx2 v[20:21], v[22:23], off offset:160
	v_mul_f32_e32 v2, v64, v24
	v_mul_f32_e32 v22, v65, v24
	v_cvt_pk_bf16_f32 v22, v2, v22
	v_mul_f32_e32 v2, v4, v24
	v_mul_f32_e32 v4, v5, v24
	v_mul_f32_e32 v5, v6, v24
	v_mul_f32_e32 v6, v7, v24
	v_cvt_pk_bf16_f32 v5, v5, v6
	v_cvt_pk_bf16_f32 v4, v2, v4
	global_store_dwordx2 v[20:21], v[4:5], off offset:192
	v_mul_f32_e32 v2, v8, v24
	v_mul_f32_e32 v4, v9, v24
	v_mul_f32_e32 v5, v10, v24
	v_mul_f32_e32 v6, v11, v24
	v_cvt_pk_bf16_f32 v5, v5, v6
	v_cvt_pk_bf16_f32 v4, v2, v4
	global_store_dwordx2 v[20:21], v[4:5], off offset:208
	v_mul_f32_e32 v2, v12, v24
	v_mul_f32_e32 v4, v13, v24
	v_mul_f32_e32 v5, v14, v24
	v_mul_f32_e32 v6, v15, v24
	v_cvt_pk_bf16_f32 v5, v5, v6
	v_cvt_pk_bf16_f32 v4, v2, v4
	global_store_dwordx2 v[20:21], v[4:5], off offset:224
	v_mul_f32_e32 v2, v16, v24
	v_mul_f32_e32 v4, v17, v24
	v_mul_f32_e32 v5, v18, v24
	v_mul_f32_e32 v6, v19, v24
	v_mul_f32_e32 v23, v66, v24
	v_mul_f32_e32 v25, v67, v24
	v_cvt_pk_bf16_f32 v5, v5, v6
	v_cvt_pk_bf16_f32 v4, v2, v4
	v_cvt_pk_bf16_f32 v23, v23, v25
	global_store_dwordx2 v[20:21], v[4:5], off offset:240
	v_mov_b32_e32 v5, v1
	global_store_dwordx2 v[20:21], v[22:23], off offset:176
	v_mov_b64_e32 v[6:7], s[60:61]
	v_ashrrev_i32_e32 v2, 1, v5
	v_and_b32_e32 v2, 0xffffffe0, v2
	v_and_b32_e32 v189, 31, v5
	v_lshl_add_u32 v188, s93, 7, v2
	v_bfe_u32 v4, v5, 5, 1
	v_or_b32_e32 v196, v188, v189
	v_mad_i64_i32 v[6:7], s[2:3], v196, s75, v[6:7]
	v_lshlrev_b32_e32 v2, 4, v4
	v_lshl_add_u64 v[6:7], v[6:7], 0, v[2:3]
	v_ashrrev_i32_e32 v32, 2, v5
	v_lshlrev_b32_e32 v84, 3, v5
	global_load_dwordx4 v[114:117], v[6:7], off
	global_load_dwordx4 v[118:121], v[6:7], off offset:32
	global_load_dwordx4 v[122:125], v[6:7], off offset:64
	global_load_dwordx4 v[126:129], v[6:7], off offset:96
	global_load_dwordx4 v[130:133], v[6:7], off offset:128
	global_load_dwordx4 v[134:137], v[6:7], off offset:160
	global_load_dwordx4 v[138:141], v[6:7], off offset:192
	global_load_dwordx4 v[142:145], v[6:7], off offset:224
	global_load_dwordx4 v[146:149], v[6:7], off offset:256
	global_load_dwordx4 v[150:153], v[6:7], off offset:288
	global_load_dwordx4 v[154:157], v[6:7], off offset:320
	global_load_dwordx4 v[158:161], v[6:7], off offset:352
	v_mul_lo_u32 v6, v32, s76
	v_and_b32_e32 v2, 24, v84
	v_or_b32_e32 v186, v6, v2
	v_ashrrev_i32_e32 v187, 31, v186
	v_lshl_add_u64 v[30:31], v[186:187], 1, s[58:59]
	s_barrier
; #define MFMA32(a, b, c) __builtin_amdgcn_mfma_f32_32x32x16_bf16((a), (b), (c), 0, 0, 0)
; DI void attn_unit(unsigned char* smem, const Params& P, int bh, int qb) {
;     ...
;   kr0 = *(const uint4*)(kbuf + kgo + 0); kr1 = *(const uint4*)(kbuf + kgo + 32); kr2 = *(const uint4*)(kbuf + kgo + 64); kr3 = *(const uint4*)(kbuf + kgo + 96); kr4 = *(const uint4*)(kbuf + kgo + 128); kr5 = *(const uint4*)(kbuf + kgo + 160);
;   *(uint4*)(sK + klo + 0) = kr0; *(uint4*)(sK + klo + 32) = kr1; *(uint4*)(sK + klo + 64) = kr2; *(uint4*)(sK + klo + 96) = kr3; *(uint4*)(sK + klo + 128) = kr4; *(uint4*)(sK + klo + 160) = kr5;
;   __syncthreads();
;   for (int jt = 0; jt < ntiles; ++jt) {
;     const bf16_t* cK = (jt & 1) ? sK1 : sK;
;     bf16_t* nK = (jt & 1) ? sK : sK1;
;     const bool more = (jt + 1 < ntiles);
;     const bool active = (jt * 64 <= q0 + 32 * w + 31);
;     if (more) {
;       const bf16_t* kp = kbuf + (size_t)(jt + 1) * 64 * 192;
;       kr0 = *(const uint4*)(kp + kgo + 0); kr1 = *(const uint4*)(kp + kgo + 32); kr2 = *(const uint4*)(kp + kgo + 64); kr3 = *(const uint4*)(kp + kgo + 96); kr4 = *(const uint4*)(kp + kgo + 128); kr5 = *(const uint4*)(kp + kgo + 160);
;     }
;     __builtin_amdgcn_sched_barrier(0);
;     f32x16 S[2];
;     const float sref = (jt == 0) ? 0.f : mrun;
;     if (active) {
; #pragma unroll
;       for (int a = 0; a < 2; ++a)
; #pragma unroll
;         for (int i = 0; i < 16; ++i) S[a][i] = -sref;
;       __builtin_amdgcn_s_setprio(1);
; #pragma unroll
;       for (int ks = 0; ks < 12; ++ks) {
;         const bf16x8 a0 = *(const bf16x8*)(cK + l31 * KLD + ks * 16 + hh * 8), a1 = *(const bf16x8*)(cK + (32 + l31) * KLD + ks * 16 + hh * 8);
;         S[0] = MFMA32(a0, qf[ks], S[0]); S[1] = MFMA32(a1, qf[ks], S[1]);
;       }
	global_load_dwordx4 v[6:9], v[30:31], off
	global_load_dwordx4 v[10:13], v[30:31], off offset:64
	global_load_dwordx4 v[14:17], v[30:31], off offset:128
	global_load_dwordx4 v[18:21], v[30:31], off offset:192
	global_load_dwordx4 v[22:25], v[30:31], off offset:256
	global_load_dwordx4 v[26:29], v[30:31], off offset:320
	v_mad_u64_u32 v[198:199], s[2:3], v32, s77, v[2:3]
	v_lshl_add_u32 v85, v198, 1, s9
	s_waitcnt vmcnt(5)
	ds_write_b128 v85, v[6:9]
	s_waitcnt vmcnt(4)
	ds_write_b128 v85, v[10:13] offset:64
	s_waitcnt vmcnt(3)
	ds_write_b128 v85, v[14:17] offset:128
	s_waitcnt vmcnt(2)
	ds_write_b128 v85, v[18:21] offset:192
	s_waitcnt vmcnt(1)
	ds_write_b128 v85, v[22:25] offset:256
	s_waitcnt vmcnt(0)
	ds_write_b128 v85, v[26:29] offset:320
	v_add_co_u32_e32 v6, vcc, 0x6000, v30
	s_waitcnt lgkmcnt(0)
	s_nop 0
	v_addc_co_u32_e32 v7, vcc, 0, v31, vcc
	s_barrier
	global_load_dwordx4 v[162:165], v[6:7], off
	global_load_dwordx4 v[166:169], v[6:7], off offset:64
	global_load_dwordx4 v[170:173], v[6:7], off offset:128
	global_load_dwordx4 v[174:177], v[6:7], off offset:192
	global_load_dwordx4 v[178:181], v[6:7], off offset:256
	global_load_dwordx4 v[182:185], v[6:7], off offset:320
	v_lshlrev_b32_e32 v86, 3, v4
	v_cmp_lt_i32_e64 s[2:3], -1, v188
	v_mul_u32_u24_e32 v2, 0xc8, v189
	v_mov_b32_e32 v217, 0
	v_lshlrev_b32_e32 v199, 1, v2
	v_lshlrev_b32_e32 v215, 1, v86
	v_mov_b32_e32 v34, 0
	v_mov_b32_e32 v35, 0
	v_mov_b32_e32 v36, 0
	v_mov_b32_e32 v37, 0
	v_mov_b32_e32 v38, 0
	v_mov_b32_e32 v39, 0
	v_mov_b32_e32 v40, 0
	v_mov_b32_e32 v41, 0
	v_mov_b32_e32 v42, 0
	v_mov_b32_e32 v43, 0
	v_mov_b32_e32 v44, 0
	v_mov_b32_e32 v45, 0
	v_mov_b32_e32 v46, 0
	v_mov_b32_e32 v47, 0
	v_mov_b32_e32 v48, 0
	v_mov_b32_e32 v49, 0
	v_mov_b32_e32 v18, 0
	v_mov_b32_e32 v19, 0
	v_mov_b32_e32 v20, 0
	v_mov_b32_e32 v21, 0
	v_mov_b32_e32 v22, 0
	v_mov_b32_e32 v23, 0
	v_mov_b32_e32 v24, 0
	v_mov_b32_e32 v25, 0
	v_mov_b32_e32 v26, 0
	v_mov_b32_e32 v27, 0
	v_mov_b32_e32 v28, 0
	v_mov_b32_e32 v29, 0
	v_mov_b32_e32 v30, 0
	v_mov_b32_e32 v31, 0
	v_mov_b32_e32 v32, 0
	v_mov_b32_e32 v33, 0
	s_and_saveexec_b64 s[58:59], s[2:3]
	s_cbranch_execz .LBB0_1425
	s_setprio 1
	v_add3_u32 v2, s9, v199, v215
	ds_read_b128 v[6:9], v2
	s_mov_b32 s26, s12
	s_mov_b32 s27, s12
	s_mov_b32 s13, s12
	s_mov_b32 s14, s12
	s_mov_b32 s15, s12
	s_mov_b32 s16, s12
	s_mov_b32 s17, s12
	s_mov_b32 s18, s12
	s_mov_b32 s19, s12
	s_mov_b32 s20, s12
	s_mov_b32 s21, s12
	s_mov_b32 s22, s12
	s_mov_b32 s23, s12
	s_mov_b32 s24, s12
	s_mov_b32 s25, s12
	v_mov_b64_e32 v[32:33], s[26:27]
	v_mov_b64_e32 v[30:31], s[24:25]
	v_mov_b64_e32 v[28:29], s[22:23]
	v_mov_b64_e32 v[26:27], s[20:21]
	v_mov_b64_e32 v[24:25], s[18:19]
	v_mov_b64_e32 v[22:23], s[16:17]
	v_mov_b64_e32 v[20:21], s[14:15]
	v_mov_b64_e32 v[18:19], s[12:13]
	s_waitcnt lgkmcnt(0)
	s_nop 0
	v_mfma_f32_32x32x16_bf16 v[34:49], v[6:9], v[114:117], v[18:33]
	ds_read_b128 v[6:9], v2 offset:12800
	s_waitcnt lgkmcnt(0)
	v_mfma_f32_32x32x16_bf16 v[18:33], v[6:9], v[114:117], v[18:33]
	ds_read_b128 v[6:9], v2 offset:32
	s_waitcnt lgkmcnt(0)
	v_mfma_f32_32x32x16_bf16 v[34:49], v[6:9], v[118:121], v[34:49]
	ds_read_b128 v[6:9], v2 offset:12832
	s_waitcnt lgkmcnt(0)
	v_mfma_f32_32x32x16_bf16 v[18:33], v[6:9], v[118:121], v[18:33]
	ds_read_b128 v[6:9], v2 offset:64
	s_waitcnt lgkmcnt(0)
	v_mfma_f32_32x32x16_bf16 v[34:49], v[6:9], v[122:125], v[34:49]
	ds_read_b128 v[6:9], v2 offset:12864
	s_waitcnt lgkmcnt(0)
	v_mfma_f32_32x32x16_bf16 v[18:33], v[6:9], v[122:125], v[18:33]
	ds_read_b128 v[6:9], v2 offset:96
	s_waitcnt lgkmcnt(0)
	v_mfma_f32_32x32x16_bf16 v[34:49], v[6:9], v[126:129], v[34:49]
	ds_read_b128 v[6:9], v2 offset:12896
	s_waitcnt lgkmcnt(0)
	v_mfma_f32_32x32x16_bf16 v[18:33], v[6:9], v[126:129], v[18:33]
	ds_read_b128 v[6:9], v2 offset:128
	s_waitcnt lgkmcnt(0)
	v_mfma_f32_32x32x16_bf16 v[34:49], v[6:9], v[130:133], v[34:49]
	ds_read_b128 v[6:9], v2 offset:12928
	s_waitcnt lgkmcnt(0)
	v_mfma_f32_32x32x16_bf16 v[18:33], v[6:9], v[130:133], v[18:33]
	ds_read_b128 v[6:9], v2 offset:160
	s_waitcnt lgkmcnt(0)
	v_mfma_f32_32x32x16_bf16 v[34:49], v[6:9], v[134:137], v[34:49]
	ds_read_b128 v[6:9], v2 offset:12960
	s_waitcnt lgkmcnt(0)
	v_mfma_f32_32x32x16_bf16 v[18:33], v[6:9], v[134:137], v[18:33]
	ds_read_b128 v[6:9], v2 offset:192
	s_waitcnt lgkmcnt(0)
	v_mfma_f32_32x32x16_bf16 v[34:49], v[6:9], v[138:141], v[34:49]
	ds_read_b128 v[6:9], v2 offset:12992
	s_waitcnt lgkmcnt(0)
	v_mfma_f32_32x32x16_bf16 v[18:33], v[6:9], v[138:141], v[18:33]
	ds_read_b128 v[6:9], v2 offset:224
	s_waitcnt lgkmcnt(0)
	v_mfma_f32_32x32x16_bf16 v[34:49], v[6:9], v[142:145], v[34:49]
	ds_read_b128 v[6:9], v2 offset:13024
	s_waitcnt lgkmcnt(0)
	v_mfma_f32_32x32x16_bf16 v[18:33], v[6:9], v[142:145], v[18:33]
	ds_read_b128 v[6:9], v2 offset:256
	s_waitcnt lgkmcnt(0)
	v_mfma_f32_32x32x16_bf16 v[34:49], v[6:9], v[146:149], v[34:49]
	ds_read_b128 v[6:9], v2 offset:13056
	s_waitcnt lgkmcnt(0)
	v_mfma_f32_32x32x16_bf16 v[18:33], v[6:9], v[146:149], v[18:33]
	ds_read_b128 v[6:9], v2 offset:288
	s_waitcnt lgkmcnt(0)
	v_mfma_f32_32x32x16_bf16 v[34:49], v[6:9], v[150:153], v[34:49]
	ds_read_b128 v[6:9], v2 offset:13088
	s_waitcnt lgkmcnt(0)
	v_mfma_f32_32x32x16_bf16 v[18:33], v[6:9], v[150:153], v[18:33]
	ds_read_b128 v[6:9], v2 offset:320
	s_waitcnt lgkmcnt(0)
	v_mfma_f32_32x32x16_bf16 v[34:49], v[6:9], v[154:157], v[34:49]
	ds_read_b128 v[6:9], v2 offset:13120
	s_waitcnt lgkmcnt(0)
	v_mfma_f32_32x32x16_bf16 v[18:33], v[6:9], v[154:157], v[18:33]
	ds_read_b128 v[6:9], v2 offset:352
	s_waitcnt lgkmcnt(0)
	v_mfma_f32_32x32x16_bf16 v[34:49], v[6:9], v[158:161], v[34:49]
	ds_read_b128 v[6:9], v2 offset:13152
	s_waitcnt lgkmcnt(0)
	v_mfma_f32_32x32x16_bf16 v[18:33], v[6:9], v[158:161], v[18:33]
	s_setprio 0
; DI int crow(int i, int h) { return (i & 3) + 8 * (i >> 2) + 4 * h; }
; DI void attn_unit(unsigned char* smem, const Params& P, int bh, int qb) {
;     ...
;   f32x16 O[4];
; #pragma unroll
;   for (int d = 0; d < 4; ++d)
; #pragma unroll
;     for (int i = 0; i < 16; ++i) O[d][i] = 0.f;
;   float mrun = -1e30f, lrun = 0.f;
;     ...
;     { const bf16_t* vp_ = vtb + (size_t)(tid >> 3) * 8192 + jt * 64 + (tid & 7) * 8; vr0 = *(const uint4*)(vp_ + (size_t)0 * 8192); vr1 = *(const uint4*)(vp_ + (size_t)32 * 8192); vr2 = *(const uint4*)(vp_ + (size_t)64 * 8192); vr3 = *(const uint4*)(vp_ + (size_t)96 * 8192); }
;     __builtin_amdgcn_sched_barrier(0);
;     if (active) {
;       if (jt >= ntiles - 2) {
; #pragma unroll
;         for (int kt = 0; kt < 2; ++kt)
; #pragma unroll
;           for (int i = 0; i < 16; ++i) { const int key = jt * 64 + kt * 32 + crow(i, hh); if (key > qrow) S[kt][i] = -1e30f; }
;       }
.LBB0_1425:
	s_or_b64 exec, exec, s[58:59]
	s_barrier
	v_ashrrev_i32_e32 v82, 3, v5
	v_ashrrev_i32_e32 v83, 31, v82
	v_lshlrev_b64 v[6:7], 14, v[82:83]
	v_and_b32_e32 v2, 56, v84
	v_lshl_add_u64 v[6:7], s[62:63], 0, v[6:7]
	v_lshlrev_b32_e32 v2, 1, v2
	v_lshl_add_u64 v[200:201], v[6:7], 0, v[2:3]
	v_add_co_u32_e32 v6, vcc, s78, v200
	v_ashrrev_i32_e32 v197, 31, v196
	s_nop 0
	v_addc_co_u32_e32 v7, vcc, 0, v201, vcc
	global_load_dwordx4 v[66:69], v[200:201], off
	global_load_dwordx4 v[70:73], v[6:7], off
	v_add_co_u32_e32 v6, vcc, s79, v200
	v_lshlrev_b32_e32 v216, 2, v4
	s_nop 0
	v_addc_co_u32_e32 v7, vcc, 0, v201, vcc
	v_add_co_u32_e32 v8, vcc, s80, v200
	s_nop 1
	v_addc_co_u32_e32 v9, vcc, 0, v201, vcc
	global_load_dwordx4 v[74:77], v[6:7], off
	global_load_dwordx4 v[78:81], v[8:9], off
	v_mov_b32_e32 v16, v3
	v_mov_b32_e32 v17, v3
	v_mov_b32_e32 v2, v3
	v_mov_b32_e32 v4, v3
	v_mov_b32_e32 v5, v3
	v_mov_b32_e32 v6, v3
	v_mov_b32_e32 v7, v3
	v_mov_b32_e32 v8, v3
	v_mov_b32_e32 v9, v3
	v_mov_b32_e32 v10, v3
	v_mov_b32_e32 v11, v3
	v_mov_b32_e32 v12, v3
	v_mov_b32_e32 v13, v3
	v_mov_b32_e32 v14, v3
	v_mov_b32_e32 v15, v3
	v_mov_b64_e32 v[64:65], v[16:17]
	v_mov_b32_e32 v202, 0xf149f2ca
	v_mov_b64_e32 v[62:63], v[14:15]
	v_mov_b64_e32 v[60:61], v[12:13]
	v_mov_b64_e32 v[58:59], v[10:11]
	v_mov_b64_e32 v[56:57], v[8:9]
	v_mov_b64_e32 v[54:55], v[6:7]
	v_mov_b64_e32 v[52:53], v[4:5]
	v_mov_b64_e32 v[50:51], v[2:3]
	s_and_saveexec_b64 s[14:15], s[2:3]
	s_cbranch_execz .LBB0_1432
	s_cmp_gt_u32 s96, 15
	s_cbranch_scc1 .LBB0_1428
	v_cmp_le_i32_e32 vcc, v216, v196
	v_or_b32_e32 v2, 2, v216
	s_nop 0
	v_cndmask_b32_e32 v34, v213, v34, vcc
	v_cmp_lt_i32_e32 vcc, v216, v196
	s_nop 1
	v_cndmask_b32_e32 v35, v213, v35, vcc
	v_cmp_le_i32_e32 vcc, v2, v196
	v_or_b32_e32 v2, 3, v216
	s_nop 0
	v_cndmask_b32_e32 v36, v213, v36, vcc
	v_cmp_le_i32_e32 vcc, v2, v196
	v_or_b32_e32 v2, 8, v216
	s_nop 0
	v_cndmask_b32_e32 v37, v213, v37, vcc
	v_cmp_le_i32_e32 vcc, v2, v196
	v_or_b32_e32 v2, 9, v216
	s_nop 0
	v_cndmask_b32_e32 v38, v213, v38, vcc
	v_cmp_le_i32_e32 vcc, v2, v196
	v_or_b32_e32 v2, 10, v216
	s_nop 0
	v_cndmask_b32_e32 v39, v213, v39, vcc
	v_cmp_le_i32_e32 vcc, v2, v196
	v_or_b32_e32 v2, 11, v216
	s_nop 0
	v_cndmask_b32_e32 v40, v213, v40, vcc
	v_cmp_le_i32_e32 vcc, v2, v196
	v_or_b32_e32 v2, 16, v216
	s_nop 0
	v_cndmask_b32_e32 v41, v213, v41, vcc
	v_cmp_le_i32_e32 vcc, v2, v196
	v_or_b32_e32 v2, 17, v216
	s_nop 0
	v_cndmask_b32_e32 v42, v213, v42, vcc
	v_cmp_le_i32_e32 vcc, v2, v196
	v_or_b32_e32 v2, 18, v216
	s_nop 0
	v_cndmask_b32_e32 v43, v213, v43, vcc
	v_cmp_le_i32_e32 vcc, v2, v196
	v_or_b32_e32 v2, 19, v216
	s_nop 0
	v_cndmask_b32_e32 v44, v213, v44, vcc
	v_cmp_le_i32_e32 vcc, v2, v196
	v_or_b32_e32 v2, 24, v216
	s_nop 0
	v_cndmask_b32_e32 v45, v213, v45, vcc
	v_cmp_le_i32_e32 vcc, v2, v196
	v_or_b32_e32 v2, 25, v216
	s_nop 0
	v_cndmask_b32_e32 v46, v213, v46, vcc
	v_cmp_le_i32_e32 vcc, v2, v196
	v_or_b32_e32 v2, 26, v216
	s_nop 0
	v_cndmask_b32_e32 v47, v213, v47, vcc
	v_cmp_le_i32_e32 vcc, v2, v196
	v_or_b32_e32 v2, 27, v216
	s_nop 0
	v_cndmask_b32_e32 v48, v213, v48, vcc
	v_cmp_le_i32_e32 vcc, v2, v196
	v_or_b32_e32 v2, 32, v216
	s_nop 0
	v_cndmask_b32_e32 v49, v213, v49, vcc
	v_cmp_le_i32_e32 vcc, v2, v196
	v_or_b32_e32 v2, 33, v216
	s_nop 0
	v_cndmask_b32_e32 v18, v213, v18, vcc
	v_cmp_le_i32_e32 vcc, v2, v196
	v_or_b32_e32 v2, 34, v216
	s_nop 0
	v_cndmask_b32_e32 v19, v213, v19, vcc
	v_cmp_le_i32_e32 vcc, v2, v196
	v_or_b32_e32 v2, 35, v216
	s_nop 0
	v_cndmask_b32_e32 v20, v213, v20, vcc
	v_cmp_le_i32_e32 vcc, v2, v196
	v_or_b32_e32 v2, 40, v216
	s_nop 0
	v_cndmask_b32_e32 v21, v213, v21, vcc
	v_cmp_le_i32_e32 vcc, v2, v196
	v_or_b32_e32 v2, 41, v216
	s_nop 0
	v_cndmask_b32_e32 v22, v213, v22, vcc
	v_cmp_le_i32_e32 vcc, v2, v196
	v_or_b32_e32 v2, 42, v216
	s_nop 0
	v_cndmask_b32_e32 v23, v213, v23, vcc
	v_cmp_le_i32_e32 vcc, v2, v196
	v_or_b32_e32 v2, 43, v216
	s_nop 0
	v_cndmask_b32_e32 v24, v213, v24, vcc
	v_cmp_le_i32_e32 vcc, v2, v196
	v_or_b32_e32 v2, 48, v216
	s_nop 0
	v_cndmask_b32_e32 v25, v213, v25, vcc
	v_cmp_le_i32_e32 vcc, v2, v196
	v_or_b32_e32 v2, 49, v216
	s_nop 0
	v_cndmask_b32_e32 v26, v213, v26, vcc
	v_cmp_le_i32_e32 vcc, v2, v196
	v_or_b32_e32 v2, 50, v216
	s_nop 0
	v_cndmask_b32_e32 v27, v213, v27, vcc
	v_cmp_le_i32_e32 vcc, v2, v196
	v_or_b32_e32 v2, 51, v216
	s_nop 0
	v_cndmask_b32_e32 v28, v213, v28, vcc
	v_cmp_le_i32_e32 vcc, v2, v196
	v_or_b32_e32 v2, 56, v216
	s_nop 0
	v_cndmask_b32_e32 v29, v213, v29, vcc
	v_cmp_le_i32_e32 vcc, v2, v196
	v_or_b32_e32 v2, 57, v216
	s_nop 0
	v_cndmask_b32_e32 v30, v213, v30, vcc
	v_cmp_le_i32_e32 vcc, v2, v196
	v_or_b32_e32 v2, 58, v216
	s_nop 0
	v_cndmask_b32_e32 v31, v213, v31, vcc
	v_cmp_le_i32_e32 vcc, v2, v196
	v_or_b32_e32 v2, 59, v216
	s_nop 0
	v_cndmask_b32_e32 v32, v213, v32, vcc
	v_cmp_le_i32_e32 vcc, v2, v196
	s_nop 1
	v_cndmask_b32_e32 v33, v213, v33, vcc

; DI void attn_unit(unsigned char* smem, const Params& P, int bh, int qb) {
;     ...
;     { bf16_t* vq_ = sV + (tid >> 3) * LDK + ((tid & 7) >> 1) * 16 + (tid & 1) * 4;
;       *(uint2*)(vq_) = make_uint2(vr0.x, vr0.y); *(uint2*)(vq_ + 8) = make_uint2(vr0.z, vr0.w);
;       *(uint2*)(vq_ + 32 * LDK) = make_uint2(vr1.x, vr1.y); *(uint2*)(vq_ + 32 * LDK + 8) = make_uint2(vr1.z, vr1.w);
;       *(uint2*)(vq_ + 64 * LDK) = make_uint2(vr2.x, vr2.y); *(uint2*)(vq_ + 64 * LDK + 8) = make_uint2(vr2.z, vr2.w);
;       *(uint2*)(vq_ + 96 * LDK) = make_uint2(vr3.x, vr3.y); *(uint2*)(vq_ + 96 * LDK + 8) = make_uint2(vr3.z, vr3.w); }
;     if (more) {
;       *(uint4*)(nK + klo + 0) = kr0; *(uint4*)(nK + klo + 32) = kr1; *(uint4*)(nK + klo + 64) = kr2; *(uint4*)(nK + klo + 96) = kr3; *(uint4*)(nK + klo + 128) = kr4; *(uint4*)(nK + klo + 160) = kr5;
;     }
;     __syncthreads();
.LBB0_1432:
	s_or_b64 exec, exec, s[14:15]
	v_mul_lo_u32 v2, v82, s82
	v_and_b32_e32 v4, 48, v84
	v_add_u32_e32 v2, s9, v2
	v_lshlrev_b32_e32 v4, 1, v4
	v_and_b32_e32 v5, 8, v84
	v_add3_u32 v5, v2, v4, v5
	v_lshl_add_u32 v4, v86, 1, s9
	v_add_u32_e32 v2, 0x6000, v5
	v_add_u32_e32 v218, 0x7000, v5
	v_add_u32_e32 v219, 0x8800, v5
	v_add_u32_e32 v220, 0x9800, v5
	v_mul_u32_u24_e32 v5, 0x48, v189
	v_mad_u32_u24 v6, v189, s83, v210
	v_mad_u32_u24 v7, v189, s83, v211
	v_mad_u32_u24 v8, v189, s83, v212
	s_waitcnt vmcnt(3)
	ds_write2_b64 v2, v[66:67], v[68:69] offset0:128 offset1:130
	s_waitcnt vmcnt(2)
	ds_write2_b64 v218, v[70:71], v[72:73] offset0:192 offset1:194
	s_waitcnt vmcnt(1)
	ds_write2_b64 v219, v[74:75], v[76:77] offset1:2
	s_waitcnt vmcnt(0)
	ds_write2_b64 v220, v[78:79], v[80:81] offset0:64 offset1:66
	ds_write_b128 v85, v[162:165] offset:44032
	ds_write_b128 v85, v[166:169] offset:44096
	ds_write_b128 v85, v[170:173] offset:44160
	ds_write_b128 v85, v[174:177] offset:44224
	ds_write_b128 v85, v[178:181] offset:44288
	ds_write_b128 v85, v[182:185] offset:44352
	s_waitcnt lgkmcnt(0)
	s_barrier
	s_nop 8
	v_mov_b64_e32 v[80:81], v[64:65]
	v_mov_b64_e32 v[96:97], v[64:65]
	v_mov_b64_e32 v[112:113], v[64:65]
	v_mov_b64_e32 v[78:79], v[62:63]
	v_mov_b64_e32 v[76:77], v[60:61]
	v_mov_b64_e32 v[74:75], v[58:59]
	v_mov_b64_e32 v[72:73], v[56:57]
	v_mov_b64_e32 v[70:71], v[54:55]
	v_mov_b64_e32 v[68:69], v[52:53]
	v_mov_b64_e32 v[66:67], v[50:51]
	v_mov_b64_e32 v[94:95], v[62:63]
	v_mov_b64_e32 v[92:93], v[60:61]
	v_mov_b64_e32 v[90:91], v[58:59]
	v_mov_b64_e32 v[88:89], v[56:57]
	v_mov_b64_e32 v[86:87], v[54:55]
	v_mov_b64_e32 v[84:85], v[52:53]
	v_mov_b64_e32 v[82:83], v[50:51]
	v_mov_b64_e32 v[110:111], v[62:63]
	v_mov_b64_e32 v[108:109], v[60:61]
	v_mov_b64_e32 v[106:107], v[58:59]
	v_mov_b64_e32 v[104:105], v[56:57]
	v_mov_b64_e32 v[102:103], v[54:55]
	v_mov_b64_e32 v[100:101], v[52:53]
	v_mov_b64_e32 v[98:99], v[50:51]
	s_lshl_b32 s8, s93, 1
	s_add_i32 s13, s8, 2
	s_add_u32 s2, s71, s97
	s_addc_u32 s3, s72, 0
	v_or_b32_e32 v221, 31, v188
	v_lshl_add_u32 v222, v5, 1, v4
	v_lshl_add_u32 v223, v6, 1, v4
	v_lshl_add_u32 v224, v7, 1, v4
	v_lshl_add_u32 v225, v8, 1, v4
	v_lshl_add_u64 v[16:17], v[186:187], 1, s[2:3]
	s_mov_b32 s20, -1
	s_mov_b32 s21, 0

; DI void attn_unit(unsigned char* smem, const Params& P, int bh, int qb) {
;     ...
;   for (int jt = 0; jt < ntiles; ++jt) {
;     const bf16_t* cK = (jt & 1) ? sK1 : sK;
;     bf16_t* nK = (jt & 1) ? sK : sK1;
;     const bool more = (jt + 1 < ntiles);
;     const bool active = (jt * 64 <= q0 + 32 * w + 31);
;     if (more) {
;       const bf16_t* kp = kbuf + (size_t)(jt + 1) * 64 * 192;
;       kr0 = *(const uint4*)(kp + kgo + 0); kr1 = *(const uint4*)(kp + kgo + 32); kr2 = *(const uint4*)(kp + kgo + 64); kr3 = *(const uint4*)(kp + kgo + 96); kr4 = *(const uint4*)(kp + kgo + 128); kr5 = *(const uint4*)(kp + kgo + 160);
;     }
.LBB0_1449:
	s_waitcnt lgkmcnt(0)
	s_barrier
	s_add_i32 s20, s20, 1
	s_cmp_lg_u32 s92, s20
	v_lshl_add_u64 v[16:17], v[16:17], 0, s[40:41]
	s_cbranch_scc0 .LBB0_1453
	s_mov_b32 s21, s10
	s_branch .LBB0_1437

; __global__ void __launch_bounds__(512) mega_fwd(Params P, int ph_lo, int ph_hi) {
	.amdhsa_kernel _Z8mega_fwd6Paramsii
		.amdhsa_group_segment_fixed_size 0
		.amdhsa_private_segment_fixed_size 0
		.amdhsa_kernarg_size 496
		.amdhsa_user_sgpr_count 2
		.amdhsa_user_sgpr_dispatch_ptr 0
		.amdhsa_user_sgpr_queue_ptr 0
		.amdhsa_user_sgpr_kernarg_segment_ptr 1
		.amdhsa_user_sgpr_dispatch_id 0
		.amdhsa_user_sgpr_kernarg_preload_length 0
		.amdhsa_user_sgpr_kernarg_preload_offset 0
		.amdhsa_user_sgpr_private_segment_size 0
		.amdhsa_uses_dynamic_stack 0
		.amdhsa_enable_private_segment 0
		.amdhsa_system_sgpr_workgroup_id_x 1
		.amdhsa_system_sgpr_workgroup_id_y 0
		.amdhsa_system_sgpr_workgroup_id_z 0
		.amdhsa_system_sgpr_workgroup_info 0
		.amdhsa_system_vgpr_workitem_id 2
		.amdhsa_next_free_vgpr 256
		.amdhsa_next_free_sgpr 102
		.amdhsa_accum_offset 256
		.amdhsa_reserve_vcc 1
		.amdhsa_float_round_mode_32 0
		.amdhsa_float_round_mode_16_64 0
		.amdhsa_float_denorm_mode_32 3
		.amdhsa_float_denorm_mode_16_64 3
		.amdhsa_dx10_clamp 1
		.amdhsa_ieee_mode 1
		.amdhsa_fp16_overflow 0
		.amdhsa_tg_split 0
		.amdhsa_exception_fp_ieee_invalid_op 0
		.amdhsa_exception_fp_denorm_src 0
		.amdhsa_exception_fp_ieee_div_zero 0
		.amdhsa_exception_fp_ieee_overflow 0
		.amdhsa_exception_fp_ieee_underflow 0
		.amdhsa_exception_fp_ieee_inexact 0
		.amdhsa_exception_int_div_zero 0
	.end_amdhsa_kernel

; __global__ void __launch_bounds__(512) mega_fwd(Params P, int ph_lo, int ph_hi) {
amdhsa.kernels:
  - .agpr_count:     0
    .args:
      - .offset:         0
        .size:           232
        .value_kind:     by_value
      - .offset:         232
        .size:           4
        .value_kind:     by_value
      - .offset:         236
        .size:           4
        .value_kind:     by_value
      - .offset:         240
        .size:           4
        .value_kind:     hidden_block_count_x
      - .offset:         244
        .size:           4
        .value_kind:     hidden_block_count_y
      - .offset:         248
        .size:           4
        .value_kind:     hidden_block_count_z
      - .offset:         252
        .size:           2
        .value_kind:     hidden_group_size_x
      - .offset:         254
        .size:           2
        .value_kind:     hidden_group_size_y
      - .offset:         256
        .size:           2
        .value_kind:     hidden_group_size_z
      - .offset:         258
        .size:           2
        .value_kind:     hidden_remainder_x
      - .offset:         260
        .size:           2
        .value_kind:     hidden_remainder_y
      - .offset:         262
        .size:           2
        .value_kind:     hidden_remainder_z
      - .offset:         280
        .size:           8
        .value_kind:     hidden_global_offset_x
      - .offset:         288
        .size:           8
        .value_kind:     hidden_global_offset_y
      - .offset:         296
        .size:           8
        .value_kind:     hidden_global_offset_z
      - .offset:         304
        .size:           2
        .value_kind:     hidden_grid_dims
      - .offset:         328
        .size:           8
        .value_kind:     hidden_multigrid_sync_arg
      - .offset:         360
        .size:           4
        .value_kind:     hidden_dynamic_lds_size
    .group_segment_fixed_size: 0
    .kernarg_segment_align: 8
    .kernarg_segment_size: 496
    .language:       OpenCL C
    .language_version:
      - 2
      - 0
    .max_flat_workgroup_size: 512
    .name:           _Z8mega_fwd6Paramsii
    .private_segment_fixed_size: 0
    .sgpr_count:     108
    .sgpr_spill_count: 41
    .symbol:         _Z8mega_fwd6Paramsii.kd
    .uniform_work_group_size: 1
    .uses_dynamic_stack: false
    .vgpr_count:     256
    .vgpr_spill_count: 0
    .wavefront_size: 64
